# GEMM K loop: As[0][0] STAGE issued in super-phase 3 instead of 2 (DMA pieces 2/4/4/6 per phase), P2 wait vmcnt(6)
# speedup vs baseline: 1.0127x; 1.0009x over previous
; #define STAGE(bufoff, gbase, voff) do { _Pragma("unroll") for (int _i = 0; _i < 2; ++_i) \
;     __builtin_amdgcn_global_load_lds((const unsigned*)((const char*)(gbase) + (voff)[_i]), (LAS unsigned*)(lds + (bufoff) + ldsw + _i * 8192), 16, 0, 0); } while (0)
; #define LDA(dst, b, h) do { _Pragma("unroll") for (int m = 0; m < 4; ++m) _Pragma("unroll") for (int k = 0; k < 2; ++k) dst[m][k] = *(const LAS half8*)(lds + SA(b, h) + aoff + m * 2048 + k * 1024); } while (0)
; #define LDB(dst, b, h) do { _Pragma("unroll") for (int n = 0; n < 2; ++n) _Pragma("unroll") for (int k = 0; k < 2; ++k) dst[n][k] = *(const LAS half8*)(lds + SB(b, h) + boff + n * 2048 + k * 1024); } while (0)
; #define MMA(ai, bj, At_, Bt_) do { __builtin_amdgcn_s_setprio(1); \
;     _Pragma("unroll") for (int m = 0; m < 4; ++m) _Pragma("unroll") for (int n = 0; n < 2; ++n) _Pragma("unroll") for (int k = 0; k < 2; ++k) \
;       acc[ai][bj][m][n] = MFMA16(Bt_[n][k], At_[m][k], acc[ai][bj][m][n]); \
;     __builtin_amdgcn_s_setprio(0); } while (0)
; #define WAIT_V(n) asm volatile("s_waitcnt vmcnt(" #n ")" ::: "memory")
; #define WAIT_L(n) asm volatile("s_waitcnt lgkmcnt(" #n ")" ::: "memory")
; #define BAR __builtin_amdgcn_s_barrier()
; template <int EPI>
; DI void gemm_phase(const int wid_s, const h16* __restrict__ A, const h16* __restrict__ Bt, const int N, const int K, const EpiArgs ea) {
;     ...
;     const int Ln = L + (int)gridDim.x;
;     const bool has_next = Ln < nwg;
;     int nbrow = brow, nbcol = bcol;
;     if (has_next) TILE_RC(Ln, nbrow, nbcol);
;     const char* nA = (const char*)A + (size_t)nbrow * K * 2;
;     const char* nB = (const char*)Bt + (size_t)nbcol * K * 2;
;     for (int t = 0; t < nt; t += 2) {
;       const bool last = (t == nt - 2);
;       const char* a1 = cA + (size_t)(t + 1) * kstep;
;       const char* a2 = last ? nA : cA + (size_t)(t + 2) * kstep; const char* b2 = last ? nB : cB + (size_t)(t + 2) * kstep;
;       const char* a3 = a2 + kstep; const char* b3 = b2 + kstep;
;       LDB(B0, 0, 0); LDB(B1, 0, 1); SCHED; LDA(At, 0, 0); STAGE(SA(1, 1), a1 + hstep, voffA);
;       WAIT_V(8); WAIT_L(0); BAR; MMA(0, 0, At, B0); MMA(0, 1, At, B1); BAR; SCHED;
;       LDA(At, 0, 1); STAGE(SB(0, 0), b2, voffB); STAGE(SB(0, 1), b2 + hstep, voffB); STAGE(SA(0, 0), a2, voffA);
;       WAIT_V(8); WAIT_L(0); BAR; MMA(1, 0, At, B0); MMA(1, 1, At, B1); BAR; SCHED;
.LBB0_121:
	s_mul_i32 s8, s31, 0x1600
	s_mul_hi_i32 s9, s31, 0x1600
	s_add_u32 s8, s28, s8
	s_addc_u32 s9, s29, s9
	s_mul_i32 s10, s38, 0x1600
	v_readlane_b32 s16, v250, 58
	s_mul_hi_i32 s11, s38, 0x1600
	s_add_u32 s41, s16, s10
	v_readlane_b32 s16, v250, 61
	s_addc_u32 s42, s16, s11
	v_readlane_b32 s16, v249, 21
	s_add_u32 s43, s16, s14
	v_readlane_b32 s14, v249, 22
	v_mov_b32_e32 v6, 0
	s_addc_u32 s44, s14, s15
	s_mov_b32 s45, -2
	s_add_u32 s14, s12, 0x100
	s_addc_u32 s15, s13, 0
	s_add_i32 s46, 0, 0x10000
	s_cmp_eq_u32 s45, 40
	s_cselect_b32 s19, s9, s15
	s_cselect_b32 s18, s8, s14
	v_add_u32_e32 v177, s46, v148
	s_cselect_b32 s17, s42, s44
	s_cselect_b32 s16, s41, s43
	s_add_i32 s47, 0, 0x14000
	ds_read_b128 v[144:147], v177
	ds_read_b128 v[152:155], v177 offset:1024
	ds_read_b128 v[178:181], v177 offset:2048
	ds_read_b128 v[182:185], v177 offset:3072
	v_add_u32_e32 v177, s47, v148
	ds_read_b128 v[186:189], v177
	ds_read_b128 v[190:193], v177 offset:1024
	ds_read_b128 v[194:197], v177 offset:2048
	ds_read_b128 v[198:201], v177 offset:3072
	v_lshl_add_u64 v[234:235], s[12:13], 0, v[142:143]
	s_add_i32 m0, s22, 0xc000
	ds_read_b128 v[202:205], v151
	ds_read_b128 v[206:209], v151 offset:1024
	ds_read_b128 v[210:213], v151 offset:2048
	ds_read_b128 v[214:217], v151 offset:3072
	ds_read_b128 v[218:221], v151 offset:4096
	ds_read_b128 v[222:225], v151 offset:5120
	ds_read_b128 v[226:229], v151 offset:6144
	ds_read_b128 v[230:233], v151 offset:7168
	global_load_lds_dwordx4 v[234:235], off
	v_lshl_add_u64 v[234:235], s[12:13], 0, v[140:141]
	s_add_i32 m0, s22, 0xe000
	s_nop 0
	global_load_lds_dwordx4 v[234:235], off
	s_waitcnt vmcnt(8)
	s_waitcnt lgkmcnt(0)
	s_barrier
	s_waitcnt lgkmcnt(0)
	v_mfma_f32_16x16x32_f16 v[130:133], v[144:147], v[202:205], 0
	v_mfma_f32_16x16x32_f16 v[126:129], v[178:181], v[202:205], 0
	v_mfma_f32_16x16x32_f16 v[114:117], v[144:147], v[210:213], 0
	v_mfma_f32_16x16x32_f16 v[110:113], v[178:181], v[210:213], 0
	v_mfma_f32_16x16x32_f16 v[98:101], v[144:147], v[218:221], 0
	v_mfma_f32_16x16x32_f16 v[94:97], v[178:181], v[218:221], 0
	v_mfma_f32_16x16x32_f16 v[82:85], v[144:147], v[226:229], 0
	v_mfma_f32_16x16x32_f16 v[78:81], v[178:181], v[226:229], 0
	v_mfma_f32_16x16x32_f16 v[130:133], v[152:155], v[206:209], v[130:133]
	v_mfma_f32_16x16x32_f16 v[126:129], v[182:185], v[206:209], v[126:129]
	v_mfma_f32_16x16x32_f16 v[114:117], v[152:155], v[214:217], v[114:117]
	v_mfma_f32_16x16x32_f16 v[110:113], v[182:185], v[214:217], v[110:113]
	v_mfma_f32_16x16x32_f16 v[98:101], v[152:155], v[222:225], v[98:101]
	v_mfma_f32_16x16x32_f16 v[94:97], v[182:185], v[222:225], v[94:97]
	v_mfma_f32_16x16x32_f16 v[82:85], v[152:155], v[230:233], v[82:85]
	v_mfma_f32_16x16x32_f16 v[78:81], v[182:185], v[230:233], v[78:81]
	v_mfma_f32_16x16x32_f16 v[122:125], v[186:189], v[202:205], 0
	v_mfma_f32_16x16x32_f16 v[118:121], v[194:197], v[202:205], 0
	v_mfma_f32_16x16x32_f16 v[106:109], v[186:189], v[210:213], 0
	v_mfma_f32_16x16x32_f16 v[102:105], v[194:197], v[210:213], 0
	v_mfma_f32_16x16x32_f16 v[90:93], v[186:189], v[218:221], 0
	v_mfma_f32_16x16x32_f16 v[86:89], v[194:197], v[218:221], 0
	v_mfma_f32_16x16x32_f16 v[74:77], v[186:189], v[226:229], 0
	v_mfma_f32_16x16x32_f16 v[70:73], v[194:197], v[226:229], 0
	v_mfma_f32_16x16x32_f16 v[122:125], v[190:193], v[206:209], v[122:125]
	v_mfma_f32_16x16x32_f16 v[118:121], v[198:201], v[206:209], v[118:121]
	v_mfma_f32_16x16x32_f16 v[106:109], v[190:193], v[214:217], v[106:109]
	v_mfma_f32_16x16x32_f16 v[102:105], v[198:201], v[214:217], v[102:105]
	v_mfma_f32_16x16x32_f16 v[90:93], v[190:193], v[222:225], v[90:93]
	v_mfma_f32_16x16x32_f16 v[86:89], v[198:201], v[222:225], v[86:89]
	v_mfma_f32_16x16x32_f16 v[74:77], v[190:193], v[230:233], v[74:77]
	v_mfma_f32_16x16x32_f16 v[70:73], v[198:201], v[230:233], v[70:73]
	s_barrier
	s_add_i32 s12, s46, s21
	v_lshl_add_u64 v[234:235], s[16:17], 0, v[0:1]
	s_mov_b32 m0, s12
	ds_read_b128 v[202:205], v151 offset:16384
	ds_read_b128 v[206:209], v151 offset:17408
	ds_read_b128 v[210:213], v151 offset:18432
	ds_read_b128 v[214:217], v151 offset:19456
	ds_read_b128 v[218:221], v151 offset:20480
	ds_read_b128 v[222:225], v151 offset:21504
	ds_read_b128 v[226:229], v151 offset:22528
	ds_read_b128 v[230:233], v151 offset:23552
	global_load_lds_dwordx4 v[234:235], off
	s_add_i32 m0, s12, 0x2000
	s_add_u32 s12, s16, 0xb0000
	v_lshl_add_u64 v[236:237], s[16:17], 0, v[138:139]
	s_addc_u32 s13, s17, 0
	s_add_i32 s46, s47, s21
	global_load_lds_dwordx4 v[236:237], off
	v_lshl_add_u64 v[238:239], s[12:13], 0, v[0:1]
	s_mov_b32 m0, s46
	v_lshl_add_u64 v[240:241], s[18:19], 0, v[134:135]
	global_load_lds_dwordx4 v[238:239], off
	v_lshl_add_u64 v[238:239], s[12:13], 0, v[138:139]
	s_add_i32 m0, s46, 0x2000
	s_nop 0
	global_load_lds_dwordx4 v[238:239], off
	v_lshl_add_u64 v[238:239], s[18:19], 0, v[2:3]
	s_waitcnt vmcnt(6)
	s_waitcnt lgkmcnt(0)
	s_barrier
; #define STAGE(bufoff, gbase, voff) do { _Pragma("unroll") for (int _i = 0; _i < 2; ++_i) \
;     __builtin_amdgcn_global_load_lds((const unsigned*)((const char*)(gbase) + (voff)[_i]), (LAS unsigned*)(lds + (bufoff) + ldsw + _i * 8192), 16, 0, 0); } while (0)
; #define LDA(dst, b, h) do { _Pragma("unroll") for (int m = 0; m < 4; ++m) _Pragma("unroll") for (int k = 0; k < 2; ++k) dst[m][k] = *(const LAS half8*)(lds + SA(b, h) + aoff + m * 2048 + k * 1024); } while (0)
; #define LDB(dst, b, h) do { _Pragma("unroll") for (int n = 0; n < 2; ++n) _Pragma("unroll") for (int k = 0; k < 2; ++k) dst[n][k] = *(const LAS half8*)(lds + SB(b, h) + boff + n * 2048 + k * 1024); } while (0)
; #define MMA(ai, bj, At_, Bt_) do { __builtin_amdgcn_s_setprio(1); \
;     _Pragma("unroll") for (int m = 0; m < 4; ++m) _Pragma("unroll") for (int n = 0; n < 2; ++n) _Pragma("unroll") for (int k = 0; k < 2; ++k) \
;       acc[ai][bj][m][n] = MFMA16(Bt_[n][k], At_[m][k], acc[ai][bj][m][n]); \
;     __builtin_amdgcn_s_setprio(0); } while (0)
; #define WAIT_V(n) asm volatile("s_waitcnt vmcnt(" #n ")" ::: "memory")
; #define WAIT_L(n) asm volatile("s_waitcnt lgkmcnt(" #n ")" ::: "memory")
; #define BAR __builtin_amdgcn_s_barrier()
; #define SCHED __builtin_amdgcn_sched_barrier(0)
; template <int EPI>
; DI void gemm_phase(const int wid_s, const h16* __restrict__ A, const h16* __restrict__ Bt, const int N, const int K, const EpiArgs ea) {
;     ...
;       WAIT_V(8); WAIT_L(0); BAR; MMA(1, 0, At, B0); MMA(1, 1, At, B1); BAR; SCHED;
;       LDB(B0, 1, 0); LDB(B1, 1, 1); SCHED; LDA(At, 1, 0); STAGE(SA(0, 1), a2 + hstep, voffA);
;       WAIT_V(8); WAIT_L(0); BAR; MMA(0, 0, At, B0); MMA(0, 1, At, B1); BAR; SCHED;
	s_waitcnt lgkmcnt(0)
	v_mfma_f32_16x16x32_f16 v[66:69], v[144:147], v[202:205], 0
	v_mfma_f32_16x16x32_f16 v[62:65], v[178:181], v[202:205], 0
	v_mfma_f32_16x16x32_f16 v[50:53], v[144:147], v[210:213], 0
	v_mfma_f32_16x16x32_f16 v[46:49], v[178:181], v[210:213], 0
	v_mfma_f32_16x16x32_f16 v[34:37], v[144:147], v[218:221], 0
	v_mfma_f32_16x16x32_f16 v[30:33], v[178:181], v[218:221], 0
	v_mfma_f32_16x16x32_f16 v[18:21], v[144:147], v[226:229], 0
	v_mfma_f32_16x16x32_f16 v[14:17], v[178:181], v[226:229], 0
	v_mfma_f32_16x16x32_f16 v[66:69], v[152:155], v[206:209], v[66:69]
	v_mfma_f32_16x16x32_f16 v[62:65], v[182:185], v[206:209], v[62:65]
	v_mfma_f32_16x16x32_f16 v[50:53], v[152:155], v[214:217], v[50:53]
	v_mfma_f32_16x16x32_f16 v[46:49], v[182:185], v[214:217], v[46:49]
	v_mfma_f32_16x16x32_f16 v[34:37], v[152:155], v[222:225], v[34:37]
	v_mfma_f32_16x16x32_f16 v[30:33], v[182:185], v[222:225], v[30:33]
	v_mfma_f32_16x16x32_f16 v[18:21], v[152:155], v[230:233], v[18:21]
	v_mfma_f32_16x16x32_f16 v[14:17], v[182:185], v[230:233], v[14:17]
	v_mfma_f32_16x16x32_f16 v[58:61], v[186:189], v[202:205], 0
	v_mfma_f32_16x16x32_f16 v[54:57], v[194:197], v[202:205], 0
	v_mfma_f32_16x16x32_f16 v[42:45], v[186:189], v[210:213], 0
	v_mfma_f32_16x16x32_f16 v[38:41], v[194:197], v[210:213], 0
	v_mfma_f32_16x16x32_f16 v[26:29], v[186:189], v[218:221], 0
	v_mfma_f32_16x16x32_f16 v[22:25], v[194:197], v[218:221], 0
	v_mfma_f32_16x16x32_f16 v[10:13], v[186:189], v[226:229], 0
	v_mfma_f32_16x16x32_f16 v[6:9], v[194:197], v[226:229], 0
	v_mfma_f32_16x16x32_f16 v[58:61], v[190:193], v[206:209], v[58:61]
	v_mfma_f32_16x16x32_f16 v[54:57], v[198:201], v[206:209], v[54:57]
	v_mfma_f32_16x16x32_f16 v[42:45], v[190:193], v[214:217], v[42:45]
	v_mfma_f32_16x16x32_f16 v[38:41], v[198:201], v[214:217], v[38:41]
	v_mfma_f32_16x16x32_f16 v[26:29], v[190:193], v[222:225], v[26:29]
	v_mfma_f32_16x16x32_f16 v[22:25], v[198:201], v[222:225], v[22:25]
	v_mfma_f32_16x16x32_f16 v[10:13], v[190:193], v[230:233], v[10:13]
	v_mfma_f32_16x16x32_f16 v[6:9], v[198:201], v[230:233], v[6:9]
	s_barrier
	s_add_i32 s46, 0, 0x18000
	v_add_u32_e32 v177, s46, v148
	s_add_i32 s47, 0, 0x1c000
	ds_read_b128 v[144:147], v177
	ds_read_b128 v[152:155], v177 offset:1024
	ds_read_b128 v[178:181], v177 offset:2048
	ds_read_b128 v[182:185], v177 offset:3072
	v_add_u32_e32 v177, s47, v148
	ds_read_b128 v[186:189], v177
	ds_read_b128 v[190:193], v177 offset:1024
	ds_read_b128 v[194:197], v177 offset:2048
	ds_read_b128 v[198:201], v177 offset:3072
	s_add_u32 s12, s18, 0xb0000
	s_addc_u32 s13, s19, 0
	v_lshl_add_u64 v[242:243], s[12:13], 0, v[2:3]
	ds_read_b128 v[202:205], v151 offset:32768
	ds_read_b128 v[206:209], v151 offset:33792
	ds_read_b128 v[210:213], v151 offset:34816
	ds_read_b128 v[214:217], v151 offset:35840
	ds_read_b128 v[218:221], v151 offset:36864
	ds_read_b128 v[222:225], v151 offset:37888
	ds_read_b128 v[226:229], v151 offset:38912
	ds_read_b128 v[230:233], v151 offset:39936
	s_mov_b32 m0, s22
	s_nop 0
	global_load_lds_dwordx4 v[238:239], off
	s_mov_b32 m0, s23
	s_nop 0
	global_load_lds_dwordx4 v[240:241], off
	s_mov_b32 m0, s24
	s_nop 0
	global_load_lds_dwordx4 v[242:243], off
	v_lshl_add_u64 v[242:243], s[12:13], 0, v[134:135]
	s_mov_b32 m0, s26
	s_nop 0
	global_load_lds_dwordx4 v[242:243], off
	s_waitcnt vmcnt(8)
	s_waitcnt lgkmcnt(0)
	s_barrier
	s_waitcnt lgkmcnt(0)
	v_mfma_f32_16x16x32_f16 v[130:133], v[144:147], v[202:205], v[130:133]
	v_mfma_f32_16x16x32_f16 v[126:129], v[178:181], v[202:205], v[126:129]
	v_mfma_f32_16x16x32_f16 v[114:117], v[144:147], v[210:213], v[114:117]
	v_mfma_f32_16x16x32_f16 v[110:113], v[178:181], v[210:213], v[110:113]
	v_mfma_f32_16x16x32_f16 v[98:101], v[144:147], v[218:221], v[98:101]
	v_mfma_f32_16x16x32_f16 v[94:97], v[178:181], v[218:221], v[94:97]
	v_mfma_f32_16x16x32_f16 v[82:85], v[144:147], v[226:229], v[82:85]
	v_mfma_f32_16x16x32_f16 v[78:81], v[178:181], v[226:229], v[78:81]
	v_mfma_f32_16x16x32_f16 v[130:133], v[152:155], v[206:209], v[130:133]
	v_mfma_f32_16x16x32_f16 v[126:129], v[182:185], v[206:209], v[126:129]
	v_mfma_f32_16x16x32_f16 v[114:117], v[152:155], v[214:217], v[114:117]
	v_mfma_f32_16x16x32_f16 v[110:113], v[182:185], v[214:217], v[110:113]
	v_mfma_f32_16x16x32_f16 v[98:101], v[152:155], v[222:225], v[98:101]
	v_mfma_f32_16x16x32_f16 v[94:97], v[182:185], v[222:225], v[94:97]
	v_mfma_f32_16x16x32_f16 v[82:85], v[152:155], v[230:233], v[82:85]
	v_mfma_f32_16x16x32_f16 v[78:81], v[182:185], v[230:233], v[78:81]
	v_mfma_f32_16x16x32_f16 v[122:125], v[186:189], v[202:205], v[122:125]
	v_mfma_f32_16x16x32_f16 v[118:121], v[194:197], v[202:205], v[118:121]
	v_mfma_f32_16x16x32_f16 v[106:109], v[186:189], v[210:213], v[106:109]
	v_mfma_f32_16x16x32_f16 v[102:105], v[194:197], v[210:213], v[102:105]
	v_mfma_f32_16x16x32_f16 v[90:93], v[186:189], v[218:221], v[90:93]
	v_mfma_f32_16x16x32_f16 v[86:89], v[194:197], v[218:221], v[86:89]
	v_mfma_f32_16x16x32_f16 v[74:77], v[186:189], v[226:229], v[74:77]
	v_mfma_f32_16x16x32_f16 v[70:73], v[194:197], v[226:229], v[70:73]
	v_mfma_f32_16x16x32_f16 v[122:125], v[190:193], v[206:209], v[122:125]
	v_mfma_f32_16x16x32_f16 v[118:121], v[198:201], v[206:209], v[118:121]
	v_mfma_f32_16x16x32_f16 v[106:109], v[190:193], v[214:217], v[106:109]
	v_mfma_f32_16x16x32_f16 v[102:105], v[198:201], v[214:217], v[102:105]
	v_mfma_f32_16x16x32_f16 v[90:93], v[190:193], v[222:225], v[90:93]
	v_mfma_f32_16x16x32_f16 v[86:89], v[198:201], v[222:225], v[86:89]
	v_mfma_f32_16x16x32_f16 v[74:77], v[190:193], v[230:233], v[74:77]
	v_mfma_f32_16x16x32_f16 v[70:73], v[198:201], v[230:233], v[70:73]
	s_barrier
; #define STAGE(bufoff, gbase, voff) do { _Pragma("unroll") for (int _i = 0; _i < 2; ++_i) \
;     __builtin_amdgcn_global_load_lds((const unsigned*)((const char*)(gbase) + (voff)[_i]), (LAS unsigned*)(lds + (bufoff) + ldsw + _i * 8192), 16, 0, 0); } while (0)
; #define LDA(dst, b, h) do { _Pragma("unroll") for (int m = 0; m < 4; ++m) _Pragma("unroll") for (int k = 0; k < 2; ++k) dst[m][k] = *(const LAS half8*)(lds + SA(b, h) + aoff + m * 2048 + k * 1024); } while (0)
; #define LDB(dst, b, h) do { _Pragma("unroll") for (int n = 0; n < 2; ++n) _Pragma("unroll") for (int k = 0; k < 2; ++k) dst[n][k] = *(const LAS half8*)(lds + SB(b, h) + boff + n * 2048 + k * 1024); } while (0)
; #define MMA(ai, bj, At_, Bt_) do { __builtin_amdgcn_s_setprio(1); \
;     _Pragma("unroll") for (int m = 0; m < 4; ++m) _Pragma("unroll") for (int n = 0; n < 2; ++n) _Pragma("unroll") for (int k = 0; k < 2; ++k) \
;       acc[ai][bj][m][n] = MFMA16(Bt_[n][k], At_[m][k], acc[ai][bj][m][n]); \
;     __builtin_amdgcn_s_setprio(0); } while (0)
; #define WAIT_V(n) asm volatile("s_waitcnt vmcnt(" #n ")" ::: "memory")
; #define BAR __builtin_amdgcn_s_barrier()
; template <int EPI>
; DI void gemm_phase(const int wid_s, const h16* __restrict__ A, const h16* __restrict__ Bt, const int N, const int K, const EpiArgs ea) {
;     ...
;     for (int t = 0; t < nt; t += 2) {
;       const bool last = (t == nt - 2);
;       const char* a1 = cA + (size_t)(t + 1) * kstep;
;       const char* a2 = last ? nA : cA + (size_t)(t + 2) * kstep; const char* b2 = last ? nB : cB + (size_t)(t + 2) * kstep;
;       const char* a3 = a2 + kstep; const char* b3 = b2 + kstep;
;       LDB(B0, 0, 0); LDB(B1, 0, 1); SCHED; LDA(At, 0, 0); STAGE(SA(1, 1), a1 + hstep, voffA);
;       WAIT_V(8); WAIT_L(0); BAR; MMA(0, 0, At, B0); MMA(0, 1, At, B1); BAR; SCHED;
;       LDA(At, 0, 1); STAGE(SB(0, 0), b2, voffB); STAGE(SB(0, 1), b2 + hstep, voffB); STAGE(SA(0, 0), a2, voffA);
;       WAIT_V(8); WAIT_L(0); BAR; MMA(1, 0, At, B0); MMA(1, 1, At, B1); BAR; SCHED;
;       LDB(B0, 1, 0); LDB(B1, 1, 1); SCHED; LDA(At, 1, 0); STAGE(SA(0, 1), a2 + hstep, voffA);
;       WAIT_V(8); WAIT_L(0); BAR; MMA(0, 0, At, B0); MMA(0, 1, At, B1); BAR; SCHED;
;       LDA(At, 1, 1); STAGE(SB(1, 0), b3, voffB); STAGE(SB(1, 1), b3 + hstep, voffB); STAGE(SA(1, 0), a3, voffA);
;       WAIT_V(8); WAIT_L(0); BAR; MMA(1, 0, At, B0); MMA(1, 1, At, B1); BAR; SCHED;
	s_add_i32 s12, s46, s21
	v_lshl_add_u64 v[234:235], v[234:235], 0, s[36:37]
	s_mov_b32 m0, s12
	ds_read_b128 v[202:205], v151 offset:49152
	ds_read_b128 v[206:209], v151 offset:50176
	ds_read_b128 v[210:213], v151 offset:51200
	ds_read_b128 v[214:217], v151 offset:52224
	ds_read_b128 v[218:221], v151 offset:53248
	ds_read_b128 v[222:225], v151 offset:54272
	ds_read_b128 v[226:229], v151 offset:55296
	ds_read_b128 v[230:233], v151 offset:56320
	global_load_lds_dwordx4 v[234:235], off
	s_add_i32 m0, s12, 0x2000
	s_add_u32 s12, s16, 0xb0080
	v_lshl_add_u64 v[234:235], v[236:237], 0, s[36:37]
	s_addc_u32 s13, s17, 0
	s_add_i32 s16, s47, s21
	global_load_lds_dwordx4 v[234:235], off
	v_lshl_add_u64 v[234:235], s[12:13], 0, v[0:1]
	s_mov_b32 m0, s16
	s_nop 0
	global_load_lds_dwordx4 v[234:235], off
	v_lshl_add_u64 v[234:235], s[12:13], 0, v[138:139]
	s_add_i32 m0, s16, 0x2000
	s_nop 0
	global_load_lds_dwordx4 v[234:235], off
	v_lshl_add_u64 v[234:235], v[238:239], 0, s[36:37]
	s_mov_b32 m0, s27
	s_nop 0
	global_load_lds_dwordx4 v[234:235], off
	v_lshl_add_u64 v[234:235], v[240:241], 0, s[36:37]
	s_mov_b32 m0, s30
	s_nop 0
	global_load_lds_dwordx4 v[234:235], off
	s_waitcnt vmcnt(8)
	s_waitcnt lgkmcnt(0)
	s_barrier
	s_waitcnt lgkmcnt(0)
	v_mfma_f32_16x16x32_f16 v[66:69], v[144:147], v[202:205], v[66:69]
	v_mfma_f32_16x16x32_f16 v[62:65], v[178:181], v[202:205], v[62:65]
	v_mfma_f32_16x16x32_f16 v[50:53], v[144:147], v[210:213], v[50:53]
	v_mfma_f32_16x16x32_f16 v[46:49], v[178:181], v[210:213], v[46:49]
	v_mfma_f32_16x16x32_f16 v[34:37], v[144:147], v[218:221], v[34:37]
	v_mfma_f32_16x16x32_f16 v[30:33], v[178:181], v[218:221], v[30:33]
	v_mfma_f32_16x16x32_f16 v[18:21], v[144:147], v[226:229], v[18:21]
	v_mfma_f32_16x16x32_f16 v[14:17], v[178:181], v[226:229], v[14:17]
	v_mfma_f32_16x16x32_f16 v[66:69], v[152:155], v[206:209], v[66:69]
	v_mfma_f32_16x16x32_f16 v[62:65], v[182:185], v[206:209], v[62:65]
	v_mfma_f32_16x16x32_f16 v[50:53], v[152:155], v[214:217], v[50:53]
	v_mfma_f32_16x16x32_f16 v[46:49], v[182:185], v[214:217], v[46:49]
	v_mfma_f32_16x16x32_f16 v[34:37], v[152:155], v[222:225], v[34:37]
	v_mfma_f32_16x16x32_f16 v[30:33], v[182:185], v[222:225], v[30:33]
	v_mfma_f32_16x16x32_f16 v[18:21], v[152:155], v[230:233], v[18:21]
	v_mfma_f32_16x16x32_f16 v[14:17], v[182:185], v[230:233], v[14:17]
	v_mfma_f32_16x16x32_f16 v[58:61], v[186:189], v[202:205], v[58:61]
	v_mfma_f32_16x16x32_f16 v[54:57], v[194:197], v[202:205], v[54:57]
	v_mfma_f32_16x16x32_f16 v[42:45], v[186:189], v[210:213], v[42:45]
	v_mfma_f32_16x16x32_f16 v[38:41], v[194:197], v[210:213], v[38:41]
	v_mfma_f32_16x16x32_f16 v[26:29], v[186:189], v[218:221], v[26:29]
	v_mfma_f32_16x16x32_f16 v[22:25], v[194:197], v[218:221], v[22:25]
	v_mfma_f32_16x16x32_f16 v[10:13], v[186:189], v[226:229], v[10:13]
	v_mfma_f32_16x16x32_f16 v[6:9], v[194:197], v[226:229], v[6:9]
	v_mfma_f32_16x16x32_f16 v[58:61], v[190:193], v[206:209], v[58:61]
	v_mfma_f32_16x16x32_f16 v[54:57], v[198:201], v[206:209], v[54:57]
	v_mfma_f32_16x16x32_f16 v[42:45], v[190:193], v[214:217], v[42:45]
	v_mfma_f32_16x16x32_f16 v[38:41], v[198:201], v[214:217], v[38:41]
	v_mfma_f32_16x16x32_f16 v[26:29], v[190:193], v[222:225], v[26:29]
	v_mfma_f32_16x16x32_f16 v[22:25], v[198:201], v[222:225], v[22:25]
	v_mfma_f32_16x16x32_f16 v[10:13], v[190:193], v[230:233], v[10:13]
	v_mfma_f32_16x16x32_f16 v[6:9], v[198:201], v[230:233], v[6:9]
	s_barrier
	s_add_i32 s45, s45, 2
	s_add_u32 s43, s43, 0x100
	s_addc_u32 s44, s44, 0
	s_cmp_gt_u32 s45, 41
	s_mov_b64 s[12:13], s[14:15]
.LBB0_122:
	s_add_u32 s14, s12, 0x100
	s_addc_u32 s15, s13, 0
	s_add_i32 s46, 0, 0x10000
	s_cmp_eq_u32 s45, 40
	s_cselect_b32 s19, s9, s15
	s_cselect_b32 s18, s8, s14
	v_add_u32_e32 v177, s46, v148
	s_cselect_b32 s17, s42, s44
	s_cselect_b32 s16, s41, s43
	s_add_i32 s47, 0, 0x14000
	ds_read_b128 v[144:147], v177
	ds_read_b128 v[152:155], v177 offset:1024
	ds_read_b128 v[178:181], v177 offset:2048
	ds_read_b128 v[182:185], v177 offset:3072
	v_add_u32_e32 v177, s47, v148
	ds_read_b128 v[186:189], v177
	ds_read_b128 v[190:193], v177 offset:1024
	ds_read_b128 v[194:197], v177 offset:2048
	ds_read_b128 v[198:201], v177 offset:3072
	v_lshl_add_u64 v[234:235], s[12:13], 0, v[142:143]
	s_add_i32 m0, s22, 0xc000
	ds_read_b128 v[202:205], v151
	ds_read_b128 v[206:209], v151 offset:1024
	ds_read_b128 v[210:213], v151 offset:2048
	ds_read_b128 v[214:217], v151 offset:3072
	ds_read_b128 v[218:221], v151 offset:4096
	ds_read_b128 v[222:225], v151 offset:5120
	ds_read_b128 v[226:229], v151 offset:6144
	ds_read_b128 v[230:233], v151 offset:7168
	global_load_lds_dwordx4 v[234:235], off
	v_lshl_add_u64 v[234:235], s[12:13], 0, v[140:141]
	s_add_i32 m0, s22, 0xe000
	s_nop 0
	global_load_lds_dwordx4 v[234:235], off
	s_waitcnt vmcnt(8)
	s_waitcnt lgkmcnt(0)
	s_barrier
; #define STAGE(bufoff, gbase, voff) do { _Pragma("unroll") for (int _i = 0; _i < 2; ++_i) \
;     __builtin_amdgcn_global_load_lds((const unsigned*)((const char*)(gbase) + (voff)[_i]), (LAS unsigned*)(lds + (bufoff) + ldsw + _i * 8192), 16, 0, 0); } while (0)
; #define LDA(dst, b, h) do { _Pragma("unroll") for (int m = 0; m < 4; ++m) _Pragma("unroll") for (int k = 0; k < 2; ++k) dst[m][k] = *(const LAS half8*)(lds + SA(b, h) + aoff + m * 2048 + k * 1024); } while (0)
; #define MMA(ai, bj, At_, Bt_) do { __builtin_amdgcn_s_setprio(1); \
;     _Pragma("unroll") for (int m = 0; m < 4; ++m) _Pragma("unroll") for (int n = 0; n < 2; ++n) _Pragma("unroll") for (int k = 0; k < 2; ++k) \
;       acc[ai][bj][m][n] = MFMA16(Bt_[n][k], At_[m][k], acc[ai][bj][m][n]); \
;     __builtin_amdgcn_s_setprio(0); } while (0)
; #define WAIT_V(n) asm volatile("s_waitcnt vmcnt(" #n ")" ::: "memory")
; #define WAIT_L(n) asm volatile("s_waitcnt lgkmcnt(" #n ")" ::: "memory")
; #define BAR __builtin_amdgcn_s_barrier()
; #define SCHED __builtin_amdgcn_sched_barrier(0)
; template <int EPI>
; DI void gemm_phase(const int wid_s, const h16* __restrict__ A, const h16* __restrict__ Bt, const int N, const int K, const EpiArgs ea) {
;     ...
;       WAIT_V(8); WAIT_L(0); BAR; MMA(0, 0, At, B0); MMA(0, 1, At, B1); BAR; SCHED;
;       LDA(At, 0, 1); STAGE(SB(0, 0), b2, voffB); STAGE(SB(0, 1), b2 + hstep, voffB); STAGE(SA(0, 0), a2, voffA);
;       WAIT_V(8); WAIT_L(0); BAR; MMA(1, 0, At, B0); MMA(1, 1, At, B1); BAR; SCHED;
	s_waitcnt lgkmcnt(0)
	v_mfma_f32_16x16x32_f16 v[130:133], v[144:147], v[202:205], v[130:133]
	v_mfma_f32_16x16x32_f16 v[126:129], v[178:181], v[202:205], v[126:129]
	v_mfma_f32_16x16x32_f16 v[114:117], v[144:147], v[210:213], v[114:117]
	v_mfma_f32_16x16x32_f16 v[110:113], v[178:181], v[210:213], v[110:113]
	v_mfma_f32_16x16x32_f16 v[98:101], v[144:147], v[218:221], v[98:101]
	v_mfma_f32_16x16x32_f16 v[94:97], v[178:181], v[218:221], v[94:97]
	v_mfma_f32_16x16x32_f16 v[82:85], v[144:147], v[226:229], v[82:85]
	v_mfma_f32_16x16x32_f16 v[78:81], v[178:181], v[226:229], v[78:81]
	v_mfma_f32_16x16x32_f16 v[130:133], v[152:155], v[206:209], v[130:133]
	v_mfma_f32_16x16x32_f16 v[126:129], v[182:185], v[206:209], v[126:129]
	v_mfma_f32_16x16x32_f16 v[114:117], v[152:155], v[214:217], v[114:117]
	v_mfma_f32_16x16x32_f16 v[110:113], v[182:185], v[214:217], v[110:113]
	v_mfma_f32_16x16x32_f16 v[98:101], v[152:155], v[222:225], v[98:101]
	v_mfma_f32_16x16x32_f16 v[94:97], v[182:185], v[222:225], v[94:97]
	v_mfma_f32_16x16x32_f16 v[82:85], v[152:155], v[230:233], v[82:85]
	v_mfma_f32_16x16x32_f16 v[78:81], v[182:185], v[230:233], v[78:81]
	v_mfma_f32_16x16x32_f16 v[122:125], v[186:189], v[202:205], v[122:125]
	v_mfma_f32_16x16x32_f16 v[118:121], v[194:197], v[202:205], v[118:121]
	v_mfma_f32_16x16x32_f16 v[106:109], v[186:189], v[210:213], v[106:109]
	v_mfma_f32_16x16x32_f16 v[102:105], v[194:197], v[210:213], v[102:105]
	v_mfma_f32_16x16x32_f16 v[90:93], v[186:189], v[218:221], v[90:93]
	v_mfma_f32_16x16x32_f16 v[86:89], v[194:197], v[218:221], v[86:89]
	v_mfma_f32_16x16x32_f16 v[74:77], v[186:189], v[226:229], v[74:77]
	v_mfma_f32_16x16x32_f16 v[70:73], v[194:197], v[226:229], v[70:73]
	v_mfma_f32_16x16x32_f16 v[122:125], v[190:193], v[206:209], v[122:125]
	v_mfma_f32_16x16x32_f16 v[118:121], v[198:201], v[206:209], v[118:121]
	v_mfma_f32_16x16x32_f16 v[106:109], v[190:193], v[214:217], v[106:109]
	v_mfma_f32_16x16x32_f16 v[102:105], v[198:201], v[214:217], v[102:105]
	v_mfma_f32_16x16x32_f16 v[90:93], v[190:193], v[222:225], v[90:93]
	v_mfma_f32_16x16x32_f16 v[86:89], v[198:201], v[222:225], v[86:89]
	v_mfma_f32_16x16x32_f16 v[74:77], v[190:193], v[230:233], v[74:77]
	v_mfma_f32_16x16x32_f16 v[70:73], v[198:201], v[230:233], v[70:73]
	s_barrier
	s_add_i32 s12, s46, s21
	v_lshl_add_u64 v[234:235], s[16:17], 0, v[0:1]
	s_mov_b32 m0, s12
	ds_read_b128 v[202:205], v151 offset:16384
	ds_read_b128 v[206:209], v151 offset:17408
	ds_read_b128 v[210:213], v151 offset:18432
	ds_read_b128 v[214:217], v151 offset:19456
	ds_read_b128 v[218:221], v151 offset:20480
	ds_read_b128 v[222:225], v151 offset:21504
	ds_read_b128 v[226:229], v151 offset:22528
	ds_read_b128 v[230:233], v151 offset:23552
	global_load_lds_dwordx4 v[234:235], off
	s_add_i32 m0, s12, 0x2000
	s_add_u32 s12, s16, 0xb0000
	v_lshl_add_u64 v[236:237], s[16:17], 0, v[138:139]
	s_addc_u32 s13, s17, 0
	s_add_i32 s46, s47, s21
	global_load_lds_dwordx4 v[236:237], off
	v_lshl_add_u64 v[238:239], s[12:13], 0, v[0:1]
	s_mov_b32 m0, s46
	v_lshl_add_u64 v[240:241], s[18:19], 0, v[134:135]
	global_load_lds_dwordx4 v[238:239], off
	v_lshl_add_u64 v[238:239], s[12:13], 0, v[138:139]
	s_add_i32 m0, s46, 0x2000
	s_nop 0
	global_load_lds_dwordx4 v[238:239], off
	v_lshl_add_u64 v[238:239], s[18:19], 0, v[2:3]
	s_waitcnt vmcnt(6)
	s_waitcnt lgkmcnt(0)
	s_barrier
	s_waitcnt lgkmcnt(0)
	v_mfma_f32_16x16x32_f16 v[66:69], v[144:147], v[202:205], v[66:69]
	v_mfma_f32_16x16x32_f16 v[62:65], v[178:181], v[202:205], v[62:65]
	v_mfma_f32_16x16x32_f16 v[50:53], v[144:147], v[210:213], v[50:53]
	v_mfma_f32_16x16x32_f16 v[46:49], v[178:181], v[210:213], v[46:49]
	v_mfma_f32_16x16x32_f16 v[34:37], v[144:147], v[218:221], v[34:37]
	v_mfma_f32_16x16x32_f16 v[30:33], v[178:181], v[218:221], v[30:33]
	v_mfma_f32_16x16x32_f16 v[18:21], v[144:147], v[226:229], v[18:21]
	v_mfma_f32_16x16x32_f16 v[14:17], v[178:181], v[226:229], v[14:17]
	v_mfma_f32_16x16x32_f16 v[66:69], v[152:155], v[206:209], v[66:69]
	v_mfma_f32_16x16x32_f16 v[62:65], v[182:185], v[206:209], v[62:65]
	v_mfma_f32_16x16x32_f16 v[50:53], v[152:155], v[214:217], v[50:53]
	v_mfma_f32_16x16x32_f16 v[46:49], v[182:185], v[214:217], v[46:49]
	v_mfma_f32_16x16x32_f16 v[34:37], v[152:155], v[222:225], v[34:37]
	v_mfma_f32_16x16x32_f16 v[30:33], v[182:185], v[222:225], v[30:33]
	v_mfma_f32_16x16x32_f16 v[18:21], v[152:155], v[230:233], v[18:21]
	v_mfma_f32_16x16x32_f16 v[14:17], v[182:185], v[230:233], v[14:17]
	v_mfma_f32_16x16x32_f16 v[58:61], v[186:189], v[202:205], v[58:61]
	v_mfma_f32_16x16x32_f16 v[54:57], v[194:197], v[202:205], v[54:57]
	v_mfma_f32_16x16x32_f16 v[42:45], v[186:189], v[210:213], v[42:45]
	v_mfma_f32_16x16x32_f16 v[38:41], v[194:197], v[210:213], v[38:41]
	v_mfma_f32_16x16x32_f16 v[26:29], v[186:189], v[218:221], v[26:29]
	v_mfma_f32_16x16x32_f16 v[22:25], v[194:197], v[218:221], v[22:25]
	v_mfma_f32_16x16x32_f16 v[10:13], v[186:189], v[226:229], v[10:13]
	v_mfma_f32_16x16x32_f16 v[6:9], v[194:197], v[226:229], v[6:9]
	v_mfma_f32_16x16x32_f16 v[58:61], v[190:193], v[206:209], v[58:61]
	v_mfma_f32_16x16x32_f16 v[54:57], v[198:201], v[206:209], v[54:57]
	v_mfma_f32_16x16x32_f16 v[42:45], v[190:193], v[214:217], v[42:45]
	v_mfma_f32_16x16x32_f16 v[38:41], v[198:201], v[214:217], v[38:41]
	v_mfma_f32_16x16x32_f16 v[26:29], v[190:193], v[222:225], v[26:29]
	v_mfma_f32_16x16x32_f16 v[22:25], v[198:201], v[222:225], v[22:25]
	v_mfma_f32_16x16x32_f16 v[10:13], v[190:193], v[230:233], v[10:13]
	v_mfma_f32_16x16x32_f16 v[6:9], v[198:201], v[230:233], v[6:9]
	s_barrier
; #define STAGE(bufoff, gbase, voff) do { _Pragma("unroll") for (int _i = 0; _i < 2; ++_i) \
;     __builtin_amdgcn_global_load_lds((const unsigned*)((const char*)(gbase) + (voff)[_i]), (LAS unsigned*)(lds + (bufoff) + ldsw + _i * 8192), 16, 0, 0); } while (0)
; #define LDA(dst, b, h) do { _Pragma("unroll") for (int m = 0; m < 4; ++m) _Pragma("unroll") for (int k = 0; k < 2; ++k) dst[m][k] = *(const LAS half8*)(lds + SA(b, h) + aoff + m * 2048 + k * 1024); } while (0)
; #define LDB(dst, b, h) do { _Pragma("unroll") for (int n = 0; n < 2; ++n) _Pragma("unroll") for (int k = 0; k < 2; ++k) dst[n][k] = *(const LAS half8*)(lds + SB(b, h) + boff + n * 2048 + k * 1024); } while (0)
; #define MMA(ai, bj, At_, Bt_) do { __builtin_amdgcn_s_setprio(1); \
;     _Pragma("unroll") for (int m = 0; m < 4; ++m) _Pragma("unroll") for (int n = 0; n < 2; ++n) _Pragma("unroll") for (int k = 0; k < 2; ++k) \
;       acc[ai][bj][m][n] = MFMA16(Bt_[n][k], At_[m][k], acc[ai][bj][m][n]); \
;     __builtin_amdgcn_s_setprio(0); } while (0)
; #define WAIT_V(n) asm volatile("s_waitcnt vmcnt(" #n ")" ::: "memory")
; #define WAIT_L(n) asm volatile("s_waitcnt lgkmcnt(" #n ")" ::: "memory")
; #define BAR __builtin_amdgcn_s_barrier()
; #define SCHED __builtin_amdgcn_sched_barrier(0)
; template <int EPI>
; DI void gemm_phase(const int wid_s, const h16* __restrict__ A, const h16* __restrict__ Bt, const int N, const int K, const EpiArgs ea) {
;     ...
;       LDB(B0, 1, 0); LDB(B1, 1, 1); SCHED; LDA(At, 1, 0); STAGE(SA(0, 1), a2 + hstep, voffA);
;       WAIT_V(8); WAIT_L(0); BAR; MMA(0, 0, At, B0); MMA(0, 1, At, B1); BAR; SCHED;
	s_add_i32 s46, 0, 0x18000
	v_add_u32_e32 v177, s46, v148
	s_add_i32 s47, 0, 0x1c000
	ds_read_b128 v[144:147], v177
	ds_read_b128 v[152:155], v177 offset:1024
	ds_read_b128 v[178:181], v177 offset:2048
	ds_read_b128 v[182:185], v177 offset:3072
	v_add_u32_e32 v177, s47, v148
	ds_read_b128 v[186:189], v177
	ds_read_b128 v[190:193], v177 offset:1024
	ds_read_b128 v[194:197], v177 offset:2048
	ds_read_b128 v[198:201], v177 offset:3072
	s_add_u32 s12, s18, 0xb0000
	s_addc_u32 s13, s19, 0
	v_lshl_add_u64 v[242:243], s[12:13], 0, v[2:3]
	ds_read_b128 v[202:205], v151 offset:32768
	ds_read_b128 v[206:209], v151 offset:33792
	ds_read_b128 v[210:213], v151 offset:34816
	ds_read_b128 v[214:217], v151 offset:35840
	ds_read_b128 v[218:221], v151 offset:36864
	ds_read_b128 v[222:225], v151 offset:37888
	ds_read_b128 v[226:229], v151 offset:38912
	ds_read_b128 v[230:233], v151 offset:39936
	s_mov_b32 m0, s22
	s_nop 0
	global_load_lds_dwordx4 v[238:239], off
	s_mov_b32 m0, s23
	s_nop 0
	global_load_lds_dwordx4 v[240:241], off
	s_mov_b32 m0, s24
	s_nop 0
	global_load_lds_dwordx4 v[242:243], off
	v_lshl_add_u64 v[242:243], s[12:13], 0, v[134:135]
	s_mov_b32 m0, s26
	s_nop 0
	global_load_lds_dwordx4 v[242:243], off
	s_waitcnt vmcnt(8)
	s_waitcnt lgkmcnt(0)
	s_barrier
	s_waitcnt lgkmcnt(0)
	v_mfma_f32_16x16x32_f16 v[130:133], v[144:147], v[202:205], v[130:133]
	v_mfma_f32_16x16x32_f16 v[126:129], v[178:181], v[202:205], v[126:129]
	v_mfma_f32_16x16x32_f16 v[114:117], v[144:147], v[210:213], v[114:117]
	v_mfma_f32_16x16x32_f16 v[110:113], v[178:181], v[210:213], v[110:113]
	v_mfma_f32_16x16x32_f16 v[98:101], v[144:147], v[218:221], v[98:101]
	v_mfma_f32_16x16x32_f16 v[94:97], v[178:181], v[218:221], v[94:97]
	v_mfma_f32_16x16x32_f16 v[82:85], v[144:147], v[226:229], v[82:85]
	v_mfma_f32_16x16x32_f16 v[78:81], v[178:181], v[226:229], v[78:81]
	v_mfma_f32_16x16x32_f16 v[130:133], v[152:155], v[206:209], v[130:133]
	v_mfma_f32_16x16x32_f16 v[126:129], v[182:185], v[206:209], v[126:129]
	v_mfma_f32_16x16x32_f16 v[114:117], v[152:155], v[214:217], v[114:117]
	v_mfma_f32_16x16x32_f16 v[110:113], v[182:185], v[214:217], v[110:113]
	v_mfma_f32_16x16x32_f16 v[98:101], v[152:155], v[222:225], v[98:101]
	v_mfma_f32_16x16x32_f16 v[94:97], v[182:185], v[222:225], v[94:97]
	v_mfma_f32_16x16x32_f16 v[82:85], v[152:155], v[230:233], v[82:85]
	v_mfma_f32_16x16x32_f16 v[78:81], v[182:185], v[230:233], v[78:81]
	v_mfma_f32_16x16x32_f16 v[122:125], v[186:189], v[202:205], v[122:125]
	v_mfma_f32_16x16x32_f16 v[118:121], v[194:197], v[202:205], v[118:121]
	v_mfma_f32_16x16x32_f16 v[106:109], v[186:189], v[210:213], v[106:109]
	v_mfma_f32_16x16x32_f16 v[102:105], v[194:197], v[210:213], v[102:105]
	v_mfma_f32_16x16x32_f16 v[90:93], v[186:189], v[218:221], v[90:93]
	v_mfma_f32_16x16x32_f16 v[86:89], v[194:197], v[218:221], v[86:89]
	v_mfma_f32_16x16x32_f16 v[74:77], v[186:189], v[226:229], v[74:77]
	v_mfma_f32_16x16x32_f16 v[70:73], v[194:197], v[226:229], v[70:73]
	v_mfma_f32_16x16x32_f16 v[122:125], v[190:193], v[206:209], v[122:125]
	v_mfma_f32_16x16x32_f16 v[118:121], v[198:201], v[206:209], v[118:121]
	v_mfma_f32_16x16x32_f16 v[106:109], v[190:193], v[214:217], v[106:109]
	v_mfma_f32_16x16x32_f16 v[102:105], v[198:201], v[214:217], v[102:105]
	v_mfma_f32_16x16x32_f16 v[90:93], v[190:193], v[222:225], v[90:93]
	v_mfma_f32_16x16x32_f16 v[86:89], v[198:201], v[222:225], v[86:89]
	v_mfma_f32_16x16x32_f16 v[74:77], v[190:193], v[230:233], v[74:77]
	v_mfma_f32_16x16x32_f16 v[70:73], v[198:201], v[230:233], v[70:73]
	s_barrier
; #define STAGE(bufoff, gbase, voff) do { _Pragma("unroll") for (int _i = 0; _i < 2; ++_i) \
;     __builtin_amdgcn_global_load_lds((const unsigned*)((const char*)(gbase) + (voff)[_i]), (LAS unsigned*)(lds + (bufoff) + ldsw + _i * 8192), 16, 0, 0); } while (0)
; #define LDA(dst, b, h) do { _Pragma("unroll") for (int m = 0; m < 4; ++m) _Pragma("unroll") for (int k = 0; k < 2; ++k) dst[m][k] = *(const LAS half8*)(lds + SA(b, h) + aoff + m * 2048 + k * 1024); } while (0)
; #define MMA(ai, bj, At_, Bt_) do { __builtin_amdgcn_s_setprio(1); \
;     _Pragma("unroll") for (int m = 0; m < 4; ++m) _Pragma("unroll") for (int n = 0; n < 2; ++n) _Pragma("unroll") for (int k = 0; k < 2; ++k) \
;       acc[ai][bj][m][n] = MFMA16(Bt_[n][k], At_[m][k], acc[ai][bj][m][n]); \
;     __builtin_amdgcn_s_setprio(0); } while (0)
; #define WAIT_V(n) asm volatile("s_waitcnt vmcnt(" #n ")" ::: "memory")
; #define WAIT_L(n) asm volatile("s_waitcnt lgkmcnt(" #n ")" ::: "memory")
; #define BAR __builtin_amdgcn_s_barrier()
; #define SCHED __builtin_amdgcn_sched_barrier(0)
; template <int EPI>
; DI void gemm_phase(const int wid_s, const h16* __restrict__ A, const h16* __restrict__ Bt, const int N, const int K, const EpiArgs ea) {
;     ...
;       LDA(At, 1, 1); STAGE(SB(1, 0), b3, voffB); STAGE(SB(1, 1), b3 + hstep, voffB); STAGE(SA(1, 0), a3, voffA);
;       WAIT_V(8); WAIT_L(0); BAR; MMA(1, 0, At, B0); MMA(1, 1, At, B1); BAR; SCHED;
;     }
	s_add_i32 s12, s46, s21
	v_lshl_add_u64 v[234:235], v[234:235], 0, s[36:37]
	s_mov_b32 m0, s12
	ds_read_b128 v[202:205], v151 offset:49152
	ds_read_b128 v[206:209], v151 offset:50176
	ds_read_b128 v[210:213], v151 offset:51200
	ds_read_b128 v[214:217], v151 offset:52224
	ds_read_b128 v[218:221], v151 offset:53248
	ds_read_b128 v[222:225], v151 offset:54272
	ds_read_b128 v[226:229], v151 offset:55296
	ds_read_b128 v[230:233], v151 offset:56320
	global_load_lds_dwordx4 v[234:235], off
	s_add_i32 m0, s12, 0x2000
	s_add_u32 s12, s16, 0xb0080
	v_lshl_add_u64 v[234:235], v[236:237], 0, s[36:37]
	s_addc_u32 s13, s17, 0
	s_add_i32 s16, s47, s21
	global_load_lds_dwordx4 v[234:235], off
	v_lshl_add_u64 v[234:235], s[12:13], 0, v[0:1]
	s_mov_b32 m0, s16
	s_nop 0
	global_load_lds_dwordx4 v[234:235], off
	v_lshl_add_u64 v[234:235], s[12:13], 0, v[138:139]
	s_add_i32 m0, s16, 0x2000
	s_nop 0
	global_load_lds_dwordx4 v[234:235], off
	v_lshl_add_u64 v[234:235], v[238:239], 0, s[36:37]
	s_mov_b32 m0, s27
	s_nop 0
	global_load_lds_dwordx4 v[234:235], off
	v_lshl_add_u64 v[234:235], v[240:241], 0, s[36:37]
	s_mov_b32 m0, s30
	s_nop 0
	global_load_lds_dwordx4 v[234:235], off
	s_waitcnt vmcnt(8)
	s_waitcnt lgkmcnt(0)
	s_barrier
	s_waitcnt lgkmcnt(0)
	v_mfma_f32_16x16x32_f16 v[66:69], v[144:147], v[202:205], v[66:69]
	v_mfma_f32_16x16x32_f16 v[62:65], v[178:181], v[202:205], v[62:65]
	v_mfma_f32_16x16x32_f16 v[50:53], v[144:147], v[210:213], v[50:53]
	v_mfma_f32_16x16x32_f16 v[46:49], v[178:181], v[210:213], v[46:49]
	v_mfma_f32_16x16x32_f16 v[34:37], v[144:147], v[218:221], v[34:37]
	v_mfma_f32_16x16x32_f16 v[30:33], v[178:181], v[218:221], v[30:33]
	v_mfma_f32_16x16x32_f16 v[18:21], v[144:147], v[226:229], v[18:21]
	v_mfma_f32_16x16x32_f16 v[14:17], v[178:181], v[226:229], v[14:17]
	v_mfma_f32_16x16x32_f16 v[66:69], v[152:155], v[206:209], v[66:69]
	v_mfma_f32_16x16x32_f16 v[62:65], v[182:185], v[206:209], v[62:65]
	v_mfma_f32_16x16x32_f16 v[50:53], v[152:155], v[214:217], v[50:53]
	v_mfma_f32_16x16x32_f16 v[46:49], v[182:185], v[214:217], v[46:49]
	v_mfma_f32_16x16x32_f16 v[34:37], v[152:155], v[222:225], v[34:37]
	v_mfma_f32_16x16x32_f16 v[30:33], v[182:185], v[222:225], v[30:33]
	v_mfma_f32_16x16x32_f16 v[18:21], v[152:155], v[230:233], v[18:21]
	v_mfma_f32_16x16x32_f16 v[14:17], v[182:185], v[230:233], v[14:17]
	v_mfma_f32_16x16x32_f16 v[58:61], v[186:189], v[202:205], v[58:61]
	v_mfma_f32_16x16x32_f16 v[54:57], v[194:197], v[202:205], v[54:57]
	v_mfma_f32_16x16x32_f16 v[42:45], v[186:189], v[210:213], v[42:45]
	v_mfma_f32_16x16x32_f16 v[38:41], v[194:197], v[210:213], v[38:41]
	v_mfma_f32_16x16x32_f16 v[26:29], v[186:189], v[218:221], v[26:29]
	v_mfma_f32_16x16x32_f16 v[22:25], v[194:197], v[218:221], v[22:25]
	v_mfma_f32_16x16x32_f16 v[10:13], v[186:189], v[226:229], v[10:13]
	v_mfma_f32_16x16x32_f16 v[6:9], v[194:197], v[226:229], v[6:9]
	v_mfma_f32_16x16x32_f16 v[58:61], v[190:193], v[206:209], v[58:61]
	v_mfma_f32_16x16x32_f16 v[54:57], v[198:201], v[206:209], v[54:57]
	v_mfma_f32_16x16x32_f16 v[42:45], v[190:193], v[214:217], v[42:45]
	v_mfma_f32_16x16x32_f16 v[38:41], v[198:201], v[214:217], v[38:41]
	v_mfma_f32_16x16x32_f16 v[26:29], v[190:193], v[222:225], v[26:29]
	v_mfma_f32_16x16x32_f16 v[22:25], v[198:201], v[222:225], v[22:25]
	v_mfma_f32_16x16x32_f16 v[10:13], v[190:193], v[230:233], v[10:13]
	v_mfma_f32_16x16x32_f16 v[6:9], v[198:201], v[230:233], v[6:9]
	s_barrier
	s_add_i32 s45, s45, 2
	s_add_u32 s43, s43, 0x100
	s_addc_u32 s44, s44, 0
	s_cmp_gt_u32 s45, 41
	s_mov_b64 s[12:13], s[14:15]
	s_cbranch_scc0 .LBB0_122
	s_and_b64 vcc, exec, s[4:5]
	s_cbranch_vccz .LBB0_125
	s_barrier

; #define STAGE(bufoff, gbase, voff) do { _Pragma("unroll") for (int _i = 0; _i < 2; ++_i) \
;     __builtin_amdgcn_global_load_lds((const unsigned*)((const char*)(gbase) + (voff)[_i]), (LAS unsigned*)(lds + (bufoff) + ldsw + _i * 8192), 16, 0, 0); } while (0)
; #define LDA(dst, b, h) do { _Pragma("unroll") for (int m = 0; m < 4; ++m) _Pragma("unroll") for (int k = 0; k < 2; ++k) dst[m][k] = *(const LAS half8*)(lds + SA(b, h) + aoff + m * 2048 + k * 1024); } while (0)
; #define LDB(dst, b, h) do { _Pragma("unroll") for (int n = 0; n < 2; ++n) _Pragma("unroll") for (int k = 0; k < 2; ++k) dst[n][k] = *(const LAS half8*)(lds + SB(b, h) + boff + n * 2048 + k * 1024); } while (0)
; #define MMA(ai, bj, At_, Bt_) do { __builtin_amdgcn_s_setprio(1); \
;     _Pragma("unroll") for (int m = 0; m < 4; ++m) _Pragma("unroll") for (int n = 0; n < 2; ++n) _Pragma("unroll") for (int k = 0; k < 2; ++k) \
;       acc[ai][bj][m][n] = MFMA16(Bt_[n][k], At_[m][k], acc[ai][bj][m][n]); \
;     __builtin_amdgcn_s_setprio(0); } while (0)
; #define WAIT_V(n) asm volatile("s_waitcnt vmcnt(" #n ")" ::: "memory")
; #define WAIT_L(n) asm volatile("s_waitcnt lgkmcnt(" #n ")" ::: "memory")
; #define BAR __builtin_amdgcn_s_barrier()
; template <int EPI>
; DI void gemm_phase(const int wid_s, const h16* __restrict__ A, const h16* __restrict__ Bt, const int N, const int K, const EpiArgs ea) {
;     ...
;     const int Ln = L + (int)gridDim.x;
;     const bool has_next = Ln < nwg;
;     int nbrow = brow, nbcol = bcol;
;     if (has_next) TILE_RC(Ln, nbrow, nbcol);
;     const char* nA = (const char*)A + (size_t)nbrow * K * 2;
;     const char* nB = (const char*)Bt + (size_t)nbcol * K * 2;
;     for (int t = 0; t < nt; t += 2) {
;       const bool last = (t == nt - 2);
;       const char* a1 = cA + (size_t)(t + 1) * kstep;
;       const char* a2 = last ? nA : cA + (size_t)(t + 2) * kstep; const char* b2 = last ? nB : cB + (size_t)(t + 2) * kstep;
;       const char* a3 = a2 + kstep; const char* b3 = b2 + kstep;
;       LDB(B0, 0, 0); LDB(B1, 0, 1); SCHED; LDA(At, 0, 0); STAGE(SA(1, 1), a1 + hstep, voffA);
;       WAIT_V(8); WAIT_L(0); BAR; MMA(0, 0, At, B0); MMA(0, 1, At, B1); BAR; SCHED;
;       LDA(At, 0, 1); STAGE(SB(0, 0), b2, voffB); STAGE(SB(0, 1), b2 + hstep, voffB); STAGE(SA(0, 0), a2, voffA);
;       WAIT_V(8); WAIT_L(0); BAR; MMA(1, 0, At, B0); MMA(1, 1, At, B1); BAR; SCHED;
.LBB0_140:
	s_ashr_i32 s9, s8, 31
	s_lshl_b64 s[12:13], s[8:9], 11
	s_add_u32 s9, s92, s12
	s_addc_u32 s42, s93, s13
	s_ashr_i32 s11, s10, 31
	s_lshl_b64 s[14:15], s[10:11], 11
	v_readlane_b32 s11, v250, 62
	s_add_u32 s11, s11, s14
	v_readlane_b32 s26, v249, 1
	s_addc_u32 s43, s26, s15
	v_readlane_b32 s26, v249, 23
	s_add_u32 s44, s26, s22
	v_readlane_b32 s22, v249, 24
	s_addc_u32 s45, s22, s23
	s_add_u32 s46, s86, s20
	v_mov_b32_e32 v6, 0
	v_lshl_add_u64 v[144:145], v[140:141], 0, s[20:21]
	v_lshl_add_u64 v[146:147], v[142:143], 0, s[20:21]
	s_addc_u32 s47, s87, s21
	s_mov_b32 s48, -2
	s_mov_b64 s[20:21], 0
	s_add_u32 s22, s46, s20
	s_addc_u32 s23, s47, s21
	s_add_u32 s22, s22, 0x520e100
	s_addc_u32 s23, s23, 0
	s_add_u32 s49, s44, s20
	s_addc_u32 s50, s45, s21
	s_add_i32 s51, 0, 0x10000
	s_cmpk_eq_i32 s20, 0x700
	s_cselect_b32 s27, s42, s23
	s_cselect_b32 s26, s9, s22
	v_add_u32_e32 v177, s51, v148
	s_cselect_b32 s23, s43, s50
	s_cselect_b32 s22, s11, s49
	s_add_i32 s49, 0, 0x14000
	ds_read_b128 v[152:155], v177
	ds_read_b128 v[178:181], v177 offset:1024
	ds_read_b128 v[182:185], v177 offset:2048
	ds_read_b128 v[186:189], v177 offset:3072
	v_add_u32_e32 v177, s49, v148
	ds_read_b128 v[190:193], v177
	ds_read_b128 v[194:197], v177 offset:1024
	ds_read_b128 v[198:201], v177 offset:2048
	ds_read_b128 v[202:205], v177 offset:3072
	v_lshl_add_u64 v[238:239], v[146:147], 0, s[20:21]
	s_add_i32 m0, s17, 0xc000
	ds_read_b128 v[206:209], v151
	ds_read_b128 v[210:213], v151 offset:1024
	ds_read_b128 v[214:217], v151 offset:2048
	ds_read_b128 v[218:221], v151 offset:3072
	ds_read_b128 v[222:225], v151 offset:4096
	ds_read_b128 v[226:229], v151 offset:5120
	ds_read_b128 v[230:233], v151 offset:6144
	ds_read_b128 v[234:237], v151 offset:7168
	global_load_lds_dwordx4 v[238:239], off
	v_lshl_add_u64 v[238:239], v[144:145], 0, s[20:21]
	s_add_i32 m0, s17, 0xe000
	s_nop 0
	global_load_lds_dwordx4 v[238:239], off
	s_waitcnt vmcnt(8)
	s_waitcnt lgkmcnt(0)
	s_barrier
	s_waitcnt lgkmcnt(0)
	v_mfma_f32_16x16x32_f16 v[130:133], v[152:155], v[206:209], 0
	v_mfma_f32_16x16x32_f16 v[126:129], v[182:185], v[206:209], 0
	v_mfma_f32_16x16x32_f16 v[114:117], v[152:155], v[214:217], 0
	v_mfma_f32_16x16x32_f16 v[110:113], v[182:185], v[214:217], 0
	v_mfma_f32_16x16x32_f16 v[98:101], v[152:155], v[222:225], 0
	v_mfma_f32_16x16x32_f16 v[94:97], v[182:185], v[222:225], 0
	v_mfma_f32_16x16x32_f16 v[82:85], v[152:155], v[230:233], 0
	v_mfma_f32_16x16x32_f16 v[78:81], v[182:185], v[230:233], 0
	v_mfma_f32_16x16x32_f16 v[130:133], v[178:181], v[210:213], v[130:133]
	v_mfma_f32_16x16x32_f16 v[126:129], v[186:189], v[210:213], v[126:129]
	v_mfma_f32_16x16x32_f16 v[114:117], v[178:181], v[218:221], v[114:117]
	v_mfma_f32_16x16x32_f16 v[110:113], v[186:189], v[218:221], v[110:113]
	v_mfma_f32_16x16x32_f16 v[98:101], v[178:181], v[226:229], v[98:101]
	v_mfma_f32_16x16x32_f16 v[94:97], v[186:189], v[226:229], v[94:97]
	v_mfma_f32_16x16x32_f16 v[82:85], v[178:181], v[234:237], v[82:85]
	v_mfma_f32_16x16x32_f16 v[78:81], v[186:189], v[234:237], v[78:81]
	v_mfma_f32_16x16x32_f16 v[122:125], v[190:193], v[206:209], 0
	v_mfma_f32_16x16x32_f16 v[118:121], v[198:201], v[206:209], 0
	v_mfma_f32_16x16x32_f16 v[106:109], v[190:193], v[214:217], 0
	v_mfma_f32_16x16x32_f16 v[102:105], v[198:201], v[214:217], 0
	v_mfma_f32_16x16x32_f16 v[90:93], v[190:193], v[222:225], 0
	v_mfma_f32_16x16x32_f16 v[86:89], v[198:201], v[222:225], 0
	v_mfma_f32_16x16x32_f16 v[74:77], v[190:193], v[230:233], 0
	v_mfma_f32_16x16x32_f16 v[70:73], v[198:201], v[230:233], 0
	v_mfma_f32_16x16x32_f16 v[122:125], v[194:197], v[210:213], v[122:125]
	v_mfma_f32_16x16x32_f16 v[118:121], v[202:205], v[210:213], v[118:121]
	v_mfma_f32_16x16x32_f16 v[106:109], v[194:197], v[218:221], v[106:109]
	v_mfma_f32_16x16x32_f16 v[102:105], v[202:205], v[218:221], v[102:105]
	v_mfma_f32_16x16x32_f16 v[90:93], v[194:197], v[226:229], v[90:93]
	v_mfma_f32_16x16x32_f16 v[86:89], v[202:205], v[226:229], v[86:89]
	v_mfma_f32_16x16x32_f16 v[74:77], v[194:197], v[234:237], v[74:77]
	v_mfma_f32_16x16x32_f16 v[70:73], v[202:205], v[234:237], v[70:73]
	s_barrier
	s_add_i32 s50, s51, s30
	v_lshl_add_u64 v[238:239], s[22:23], 0, v[0:1]
	s_mov_b32 m0, s50
	ds_read_b128 v[206:209], v151 offset:16384
	ds_read_b128 v[210:213], v151 offset:17408
	ds_read_b128 v[214:217], v151 offset:18432
	ds_read_b128 v[218:221], v151 offset:19456
	ds_read_b128 v[222:225], v151 offset:20480
	ds_read_b128 v[226:229], v151 offset:21504
	ds_read_b128 v[230:233], v151 offset:22528
	ds_read_b128 v[234:237], v151 offset:23552
	global_load_lds_dwordx4 v[238:239], off
	s_add_i32 m0, s50, 0x2000
	s_add_u32 s50, s22, 0x40000
	v_lshl_add_u64 v[240:241], s[22:23], 0, v[2:3]
	s_addc_u32 s51, s23, 0
	s_add_i32 s49, s49, s30
	global_load_lds_dwordx4 v[240:241], off
	v_lshl_add_u64 v[242:243], s[50:51], 0, v[0:1]
	s_mov_b32 m0, s49
	v_lshl_add_u64 v[244:245], s[26:27], 0, v[134:135]
	global_load_lds_dwordx4 v[242:243], off
	v_lshl_add_u64 v[242:243], s[50:51], 0, v[2:3]
	s_add_i32 m0, s49, 0x2000
	s_nop 0
	global_load_lds_dwordx4 v[242:243], off
	v_lshl_add_u64 v[242:243], s[26:27], 0, v[138:139]
	s_waitcnt vmcnt(6)
	s_waitcnt lgkmcnt(0)
	s_barrier
; #define STAGE(bufoff, gbase, voff) do { _Pragma("unroll") for (int _i = 0; _i < 2; ++_i) \
;     __builtin_amdgcn_global_load_lds((const unsigned*)((const char*)(gbase) + (voff)[_i]), (LAS unsigned*)(lds + (bufoff) + ldsw + _i * 8192), 16, 0, 0); } while (0)
; #define LDA(dst, b, h) do { _Pragma("unroll") for (int m = 0; m < 4; ++m) _Pragma("unroll") for (int k = 0; k < 2; ++k) dst[m][k] = *(const LAS half8*)(lds + SA(b, h) + aoff + m * 2048 + k * 1024); } while (0)
; #define LDB(dst, b, h) do { _Pragma("unroll") for (int n = 0; n < 2; ++n) _Pragma("unroll") for (int k = 0; k < 2; ++k) dst[n][k] = *(const LAS half8*)(lds + SB(b, h) + boff + n * 2048 + k * 1024); } while (0)
; #define MMA(ai, bj, At_, Bt_) do { __builtin_amdgcn_s_setprio(1); \
;     _Pragma("unroll") for (int m = 0; m < 4; ++m) _Pragma("unroll") for (int n = 0; n < 2; ++n) _Pragma("unroll") for (int k = 0; k < 2; ++k) \
;       acc[ai][bj][m][n] = MFMA16(Bt_[n][k], At_[m][k], acc[ai][bj][m][n]); \
;     __builtin_amdgcn_s_setprio(0); } while (0)
; #define WAIT_V(n) asm volatile("s_waitcnt vmcnt(" #n ")" ::: "memory")
; #define WAIT_L(n) asm volatile("s_waitcnt lgkmcnt(" #n ")" ::: "memory")
; #define BAR __builtin_amdgcn_s_barrier()
; #define SCHED __builtin_amdgcn_sched_barrier(0)
; template <int EPI>
; DI void gemm_phase(const int wid_s, const h16* __restrict__ A, const h16* __restrict__ Bt, const int N, const int K, const EpiArgs ea) {
;     ...
;       WAIT_V(8); WAIT_L(0); BAR; MMA(1, 0, At, B0); MMA(1, 1, At, B1); BAR; SCHED;
;       LDB(B0, 1, 0); LDB(B1, 1, 1); SCHED; LDA(At, 1, 0); STAGE(SA(0, 1), a2 + hstep, voffA);
;       WAIT_V(8); WAIT_L(0); BAR; MMA(0, 0, At, B0); MMA(0, 1, At, B1); BAR; SCHED;
	s_waitcnt lgkmcnt(0)
	v_mfma_f32_16x16x32_f16 v[66:69], v[152:155], v[206:209], 0
	v_mfma_f32_16x16x32_f16 v[62:65], v[182:185], v[206:209], 0
	v_mfma_f32_16x16x32_f16 v[50:53], v[152:155], v[214:217], 0
	v_mfma_f32_16x16x32_f16 v[46:49], v[182:185], v[214:217], 0
	v_mfma_f32_16x16x32_f16 v[34:37], v[152:155], v[222:225], 0
	v_mfma_f32_16x16x32_f16 v[30:33], v[182:185], v[222:225], 0
	v_mfma_f32_16x16x32_f16 v[18:21], v[152:155], v[230:233], 0
	v_mfma_f32_16x16x32_f16 v[14:17], v[182:185], v[230:233], 0
	v_mfma_f32_16x16x32_f16 v[66:69], v[178:181], v[210:213], v[66:69]
	v_mfma_f32_16x16x32_f16 v[62:65], v[186:189], v[210:213], v[62:65]
	v_mfma_f32_16x16x32_f16 v[50:53], v[178:181], v[218:221], v[50:53]
	v_mfma_f32_16x16x32_f16 v[46:49], v[186:189], v[218:221], v[46:49]
	v_mfma_f32_16x16x32_f16 v[34:37], v[178:181], v[226:229], v[34:37]
	v_mfma_f32_16x16x32_f16 v[30:33], v[186:189], v[226:229], v[30:33]
	v_mfma_f32_16x16x32_f16 v[18:21], v[178:181], v[234:237], v[18:21]
	v_mfma_f32_16x16x32_f16 v[14:17], v[186:189], v[234:237], v[14:17]
	v_mfma_f32_16x16x32_f16 v[58:61], v[190:193], v[206:209], 0
	v_mfma_f32_16x16x32_f16 v[54:57], v[198:201], v[206:209], 0
	v_mfma_f32_16x16x32_f16 v[42:45], v[190:193], v[214:217], 0
	v_mfma_f32_16x16x32_f16 v[38:41], v[198:201], v[214:217], 0
	v_mfma_f32_16x16x32_f16 v[26:29], v[190:193], v[222:225], 0
	v_mfma_f32_16x16x32_f16 v[22:25], v[198:201], v[222:225], 0
	v_mfma_f32_16x16x32_f16 v[10:13], v[190:193], v[230:233], 0
	v_mfma_f32_16x16x32_f16 v[6:9], v[198:201], v[230:233], 0
	v_mfma_f32_16x16x32_f16 v[58:61], v[194:197], v[210:213], v[58:61]
	v_mfma_f32_16x16x32_f16 v[54:57], v[202:205], v[210:213], v[54:57]
	v_mfma_f32_16x16x32_f16 v[42:45], v[194:197], v[218:221], v[42:45]
	v_mfma_f32_16x16x32_f16 v[38:41], v[202:205], v[218:221], v[38:41]
	v_mfma_f32_16x16x32_f16 v[26:29], v[194:197], v[226:229], v[26:29]
	v_mfma_f32_16x16x32_f16 v[22:25], v[202:205], v[226:229], v[22:25]
	v_mfma_f32_16x16x32_f16 v[10:13], v[194:197], v[234:237], v[10:13]
	v_mfma_f32_16x16x32_f16 v[6:9], v[202:205], v[234:237], v[6:9]
	s_barrier
	s_add_i32 s49, 0, 0x18000
	v_add_u32_e32 v177, s49, v148
	s_add_i32 s50, 0, 0x1c000
	ds_read_b128 v[152:155], v177
	ds_read_b128 v[178:181], v177 offset:1024
	ds_read_b128 v[182:185], v177 offset:2048
	ds_read_b128 v[186:189], v177 offset:3072
	v_add_u32_e32 v177, s50, v148
	ds_read_b128 v[190:193], v177
	ds_read_b128 v[194:197], v177 offset:1024
	ds_read_b128 v[198:201], v177 offset:2048
	ds_read_b128 v[202:205], v177 offset:3072
	s_add_u32 s26, s26, 0x40000
	s_addc_u32 s27, s27, 0
	v_lshl_add_u64 v[246:247], s[26:27], 0, v[138:139]
	ds_read_b128 v[206:209], v151 offset:32768
	ds_read_b128 v[210:213], v151 offset:33792
	ds_read_b128 v[214:217], v151 offset:34816
	ds_read_b128 v[218:221], v151 offset:35840
	ds_read_b128 v[222:225], v151 offset:36864
	ds_read_b128 v[226:229], v151 offset:37888
	ds_read_b128 v[230:233], v151 offset:38912
	ds_read_b128 v[234:237], v151 offset:39936
	s_mov_b32 m0, s17
	s_nop 0
	global_load_lds_dwordx4 v[242:243], off
	s_mov_b32 m0, s19
	s_nop 0
	global_load_lds_dwordx4 v[244:245], off
	s_mov_b32 m0, s31
	s_nop 0
	global_load_lds_dwordx4 v[246:247], off
	v_lshl_add_u64 v[246:247], s[26:27], 0, v[134:135]
	s_mov_b32 m0, s38
	s_nop 0
	global_load_lds_dwordx4 v[246:247], off
	s_waitcnt vmcnt(8)
	s_waitcnt lgkmcnt(0)
	s_barrier
	s_waitcnt lgkmcnt(0)
	v_mfma_f32_16x16x32_f16 v[130:133], v[152:155], v[206:209], v[130:133]
	v_mfma_f32_16x16x32_f16 v[126:129], v[182:185], v[206:209], v[126:129]
	v_mfma_f32_16x16x32_f16 v[114:117], v[152:155], v[214:217], v[114:117]
	v_mfma_f32_16x16x32_f16 v[110:113], v[182:185], v[214:217], v[110:113]
	v_mfma_f32_16x16x32_f16 v[98:101], v[152:155], v[222:225], v[98:101]
	v_mfma_f32_16x16x32_f16 v[94:97], v[182:185], v[222:225], v[94:97]
	v_mfma_f32_16x16x32_f16 v[82:85], v[152:155], v[230:233], v[82:85]
	v_mfma_f32_16x16x32_f16 v[78:81], v[182:185], v[230:233], v[78:81]
	v_mfma_f32_16x16x32_f16 v[130:133], v[178:181], v[210:213], v[130:133]
	v_mfma_f32_16x16x32_f16 v[126:129], v[186:189], v[210:213], v[126:129]
	v_mfma_f32_16x16x32_f16 v[114:117], v[178:181], v[218:221], v[114:117]
	v_mfma_f32_16x16x32_f16 v[110:113], v[186:189], v[218:221], v[110:113]
	v_mfma_f32_16x16x32_f16 v[98:101], v[178:181], v[226:229], v[98:101]
	v_mfma_f32_16x16x32_f16 v[94:97], v[186:189], v[226:229], v[94:97]
	v_mfma_f32_16x16x32_f16 v[82:85], v[178:181], v[234:237], v[82:85]
	v_mfma_f32_16x16x32_f16 v[78:81], v[186:189], v[234:237], v[78:81]
	v_mfma_f32_16x16x32_f16 v[122:125], v[190:193], v[206:209], v[122:125]
	v_mfma_f32_16x16x32_f16 v[118:121], v[198:201], v[206:209], v[118:121]
	v_mfma_f32_16x16x32_f16 v[106:109], v[190:193], v[214:217], v[106:109]
	v_mfma_f32_16x16x32_f16 v[102:105], v[198:201], v[214:217], v[102:105]
	v_mfma_f32_16x16x32_f16 v[90:93], v[190:193], v[222:225], v[90:93]
	v_mfma_f32_16x16x32_f16 v[86:89], v[198:201], v[222:225], v[86:89]
	v_mfma_f32_16x16x32_f16 v[74:77], v[190:193], v[230:233], v[74:77]
	v_mfma_f32_16x16x32_f16 v[70:73], v[198:201], v[230:233], v[70:73]
	v_mfma_f32_16x16x32_f16 v[122:125], v[194:197], v[210:213], v[122:125]
	v_mfma_f32_16x16x32_f16 v[118:121], v[202:205], v[210:213], v[118:121]
	v_mfma_f32_16x16x32_f16 v[106:109], v[194:197], v[218:221], v[106:109]
	v_mfma_f32_16x16x32_f16 v[102:105], v[202:205], v[218:221], v[102:105]
	v_mfma_f32_16x16x32_f16 v[90:93], v[194:197], v[226:229], v[90:93]
	v_mfma_f32_16x16x32_f16 v[86:89], v[202:205], v[226:229], v[86:89]
	v_mfma_f32_16x16x32_f16 v[74:77], v[194:197], v[234:237], v[74:77]
	v_mfma_f32_16x16x32_f16 v[70:73], v[202:205], v[234:237], v[70:73]
	s_barrier
; #define STAGE(bufoff, gbase, voff) do { _Pragma("unroll") for (int _i = 0; _i < 2; ++_i) \
;     __builtin_amdgcn_global_load_lds((const unsigned*)((const char*)(gbase) + (voff)[_i]), (LAS unsigned*)(lds + (bufoff) + ldsw + _i * 8192), 16, 0, 0); } while (0)
; #define LDA(dst, b, h) do { _Pragma("unroll") for (int m = 0; m < 4; ++m) _Pragma("unroll") for (int k = 0; k < 2; ++k) dst[m][k] = *(const LAS half8*)(lds + SA(b, h) + aoff + m * 2048 + k * 1024); } while (0)
; #define LDB(dst, b, h) do { _Pragma("unroll") for (int n = 0; n < 2; ++n) _Pragma("unroll") for (int k = 0; k < 2; ++k) dst[n][k] = *(const LAS half8*)(lds + SB(b, h) + boff + n * 2048 + k * 1024); } while (0)
; #define MMA(ai, bj, At_, Bt_) do { __builtin_amdgcn_s_setprio(1); \
;     _Pragma("unroll") for (int m = 0; m < 4; ++m) _Pragma("unroll") for (int n = 0; n < 2; ++n) _Pragma("unroll") for (int k = 0; k < 2; ++k) \
;       acc[ai][bj][m][n] = MFMA16(Bt_[n][k], At_[m][k], acc[ai][bj][m][n]); \
;     __builtin_amdgcn_s_setprio(0); } while (0)
; #define WAIT_V(n) asm volatile("s_waitcnt vmcnt(" #n ")" ::: "memory")
; #define WAIT_L(n) asm volatile("s_waitcnt lgkmcnt(" #n ")" ::: "memory")
; #define BAR __builtin_amdgcn_s_barrier()
; #define SCHED __builtin_amdgcn_sched_barrier(0)
; template <int EPI>
; DI void gemm_phase(const int wid_s, const h16* __restrict__ A, const h16* __restrict__ Bt, const int N, const int K, const EpiArgs ea) {
;     ...
;     for (int t = 0; t < nt; t += 2) {
;       const bool last = (t == nt - 2);
;       const char* a1 = cA + (size_t)(t + 1) * kstep;
;       const char* a2 = last ? nA : cA + (size_t)(t + 2) * kstep; const char* b2 = last ? nB : cB + (size_t)(t + 2) * kstep;
;       const char* a3 = a2 + kstep; const char* b3 = b2 + kstep;
;       LDB(B0, 0, 0); LDB(B1, 0, 1); SCHED; LDA(At, 0, 0); STAGE(SA(1, 1), a1 + hstep, voffA);
;     ...
;       LDA(At, 1, 1); STAGE(SB(1, 0), b3, voffB); STAGE(SB(1, 1), b3 + hstep, voffB); STAGE(SA(1, 0), a3, voffA);
;       WAIT_V(8); WAIT_L(0); BAR; MMA(1, 0, At, B0); MMA(1, 1, At, B1); BAR; SCHED;
	s_add_i32 s26, s49, s30
	v_lshl_add_u64 v[238:239], v[238:239], 0, s[36:37]
	s_mov_b32 m0, s26
	ds_read_b128 v[206:209], v151 offset:49152
	ds_read_b128 v[210:213], v151 offset:50176
	ds_read_b128 v[214:217], v151 offset:51200
	ds_read_b128 v[218:221], v151 offset:52224
	ds_read_b128 v[222:225], v151 offset:53248
	ds_read_b128 v[226:229], v151 offset:54272
	ds_read_b128 v[230:233], v151 offset:55296
	ds_read_b128 v[234:237], v151 offset:56320
	global_load_lds_dwordx4 v[238:239], off
	s_add_i32 m0, s26, 0x2000
	s_add_u32 s22, s22, 0x40080
	v_lshl_add_u64 v[238:239], v[240:241], 0, s[36:37]
	s_addc_u32 s23, s23, 0
	s_add_i32 s26, s50, s30
	global_load_lds_dwordx4 v[238:239], off
	v_lshl_add_u64 v[238:239], s[22:23], 0, v[0:1]
	s_mov_b32 m0, s26
	s_nop 0
	global_load_lds_dwordx4 v[238:239], off
	v_lshl_add_u64 v[238:239], s[22:23], 0, v[2:3]
	s_add_i32 m0, s26, 0x2000
	s_nop 0
	global_load_lds_dwordx4 v[238:239], off
	v_lshl_add_u64 v[238:239], v[242:243], 0, s[36:37]
	s_mov_b32 m0, s40
	s_nop 0
	global_load_lds_dwordx4 v[238:239], off
	v_lshl_add_u64 v[238:239], v[244:245], 0, s[36:37]
	s_mov_b32 m0, s41
	s_nop 0
	global_load_lds_dwordx4 v[238:239], off
	s_waitcnt vmcnt(8)
	s_waitcnt lgkmcnt(0)
	s_barrier
	s_waitcnt lgkmcnt(0)
	v_mfma_f32_16x16x32_f16 v[66:69], v[152:155], v[206:209], v[66:69]
	v_mfma_f32_16x16x32_f16 v[62:65], v[182:185], v[206:209], v[62:65]
	v_mfma_f32_16x16x32_f16 v[50:53], v[152:155], v[214:217], v[50:53]
	v_mfma_f32_16x16x32_f16 v[46:49], v[182:185], v[214:217], v[46:49]
	v_mfma_f32_16x16x32_f16 v[34:37], v[152:155], v[222:225], v[34:37]
	v_mfma_f32_16x16x32_f16 v[30:33], v[182:185], v[222:225], v[30:33]
	v_mfma_f32_16x16x32_f16 v[18:21], v[152:155], v[230:233], v[18:21]
	v_mfma_f32_16x16x32_f16 v[14:17], v[182:185], v[230:233], v[14:17]
	v_mfma_f32_16x16x32_f16 v[66:69], v[178:181], v[210:213], v[66:69]
	v_mfma_f32_16x16x32_f16 v[62:65], v[186:189], v[210:213], v[62:65]
	v_mfma_f32_16x16x32_f16 v[50:53], v[178:181], v[218:221], v[50:53]
	v_mfma_f32_16x16x32_f16 v[46:49], v[186:189], v[218:221], v[46:49]
	v_mfma_f32_16x16x32_f16 v[34:37], v[178:181], v[226:229], v[34:37]
	v_mfma_f32_16x16x32_f16 v[30:33], v[186:189], v[226:229], v[30:33]
	v_mfma_f32_16x16x32_f16 v[18:21], v[178:181], v[234:237], v[18:21]
	v_mfma_f32_16x16x32_f16 v[14:17], v[186:189], v[234:237], v[14:17]
	v_mfma_f32_16x16x32_f16 v[58:61], v[190:193], v[206:209], v[58:61]
	v_mfma_f32_16x16x32_f16 v[54:57], v[198:201], v[206:209], v[54:57]
	v_mfma_f32_16x16x32_f16 v[42:45], v[190:193], v[214:217], v[42:45]
	v_mfma_f32_16x16x32_f16 v[38:41], v[198:201], v[214:217], v[38:41]
	v_mfma_f32_16x16x32_f16 v[26:29], v[190:193], v[222:225], v[26:29]
	v_mfma_f32_16x16x32_f16 v[22:25], v[198:201], v[222:225], v[22:25]
	v_mfma_f32_16x16x32_f16 v[10:13], v[190:193], v[230:233], v[10:13]
	v_mfma_f32_16x16x32_f16 v[6:9], v[198:201], v[230:233], v[6:9]
	v_mfma_f32_16x16x32_f16 v[58:61], v[194:197], v[210:213], v[58:61]
	v_mfma_f32_16x16x32_f16 v[54:57], v[202:205], v[210:213], v[54:57]
	v_mfma_f32_16x16x32_f16 v[42:45], v[194:197], v[218:221], v[42:45]
	v_mfma_f32_16x16x32_f16 v[38:41], v[202:205], v[218:221], v[38:41]
	v_mfma_f32_16x16x32_f16 v[26:29], v[194:197], v[226:229], v[26:29]
	v_mfma_f32_16x16x32_f16 v[22:25], v[202:205], v[226:229], v[22:25]
	v_mfma_f32_16x16x32_f16 v[10:13], v[194:197], v[234:237], v[10:13]
	v_mfma_f32_16x16x32_f16 v[6:9], v[202:205], v[234:237], v[6:9]
	s_barrier
	s_add_i32 s48, s48, 2
	s_add_u32 s20, s20, 0x100
	s_addc_u32 s21, s21, 0
	s_cmp_gt_u32 s48, 13
.LBB0_141:
	s_add_u32 s22, s46, s20
	s_addc_u32 s23, s47, s21
	s_add_u32 s22, s22, 0x520e100
	s_addc_u32 s23, s23, 0
	s_add_u32 s49, s44, s20
	s_addc_u32 s50, s45, s21
	s_add_i32 s51, 0, 0x10000
	s_cmpk_eq_i32 s20, 0x700
	s_cselect_b32 s27, s42, s23
	s_cselect_b32 s26, s9, s22
	v_add_u32_e32 v177, s51, v148
	s_cselect_b32 s23, s43, s50
	s_cselect_b32 s22, s11, s49
	s_add_i32 s49, 0, 0x14000
	ds_read_b128 v[152:155], v177
	ds_read_b128 v[178:181], v177 offset:1024
	ds_read_b128 v[182:185], v177 offset:2048
	ds_read_b128 v[186:189], v177 offset:3072
	v_add_u32_e32 v177, s49, v148
	ds_read_b128 v[190:193], v177
	ds_read_b128 v[194:197], v177 offset:1024
	ds_read_b128 v[198:201], v177 offset:2048
	ds_read_b128 v[202:205], v177 offset:3072
	v_lshl_add_u64 v[238:239], v[146:147], 0, s[20:21]
	s_add_i32 m0, s17, 0xc000
	ds_read_b128 v[206:209], v151
	ds_read_b128 v[210:213], v151 offset:1024
	ds_read_b128 v[214:217], v151 offset:2048
	ds_read_b128 v[218:221], v151 offset:3072
	ds_read_b128 v[222:225], v151 offset:4096
	ds_read_b128 v[226:229], v151 offset:5120
	ds_read_b128 v[230:233], v151 offset:6144
	ds_read_b128 v[234:237], v151 offset:7168
	global_load_lds_dwordx4 v[238:239], off
	v_lshl_add_u64 v[238:239], v[144:145], 0, s[20:21]
	s_add_i32 m0, s17, 0xe000
	s_nop 0
	global_load_lds_dwordx4 v[238:239], off
	s_waitcnt vmcnt(8)
	s_waitcnt lgkmcnt(0)
	s_barrier
; #define STAGE(bufoff, gbase, voff) do { _Pragma("unroll") for (int _i = 0; _i < 2; ++_i) \
;     __builtin_amdgcn_global_load_lds((const unsigned*)((const char*)(gbase) + (voff)[_i]), (LAS unsigned*)(lds + (bufoff) + ldsw + _i * 8192), 16, 0, 0); } while (0)
; #define LDA(dst, b, h) do { _Pragma("unroll") for (int m = 0; m < 4; ++m) _Pragma("unroll") for (int k = 0; k < 2; ++k) dst[m][k] = *(const LAS half8*)(lds + SA(b, h) + aoff + m * 2048 + k * 1024); } while (0)
; #define LDB(dst, b, h) do { _Pragma("unroll") for (int n = 0; n < 2; ++n) _Pragma("unroll") for (int k = 0; k < 2; ++k) dst[n][k] = *(const LAS half8*)(lds + SB(b, h) + boff + n * 2048 + k * 1024); } while (0)
; #define MMA(ai, bj, At_, Bt_) do { __builtin_amdgcn_s_setprio(1); \
;     _Pragma("unroll") for (int m = 0; m < 4; ++m) _Pragma("unroll") for (int n = 0; n < 2; ++n) _Pragma("unroll") for (int k = 0; k < 2; ++k) \
;       acc[ai][bj][m][n] = MFMA16(Bt_[n][k], At_[m][k], acc[ai][bj][m][n]); \
;     __builtin_amdgcn_s_setprio(0); } while (0)
; #define WAIT_V(n) asm volatile("s_waitcnt vmcnt(" #n ")" ::: "memory")
; #define WAIT_L(n) asm volatile("s_waitcnt lgkmcnt(" #n ")" ::: "memory")
; #define BAR __builtin_amdgcn_s_barrier()
; #define SCHED __builtin_amdgcn_sched_barrier(0)
; template <int EPI>
; DI void gemm_phase(const int wid_s, const h16* __restrict__ A, const h16* __restrict__ Bt, const int N, const int K, const EpiArgs ea) {
;     ...
;       WAIT_V(8); WAIT_L(0); BAR; MMA(0, 0, At, B0); MMA(0, 1, At, B1); BAR; SCHED;
;       LDA(At, 0, 1); STAGE(SB(0, 0), b2, voffB); STAGE(SB(0, 1), b2 + hstep, voffB); STAGE(SA(0, 0), a2, voffA);
;       WAIT_V(8); WAIT_L(0); BAR; MMA(1, 0, At, B0); MMA(1, 1, At, B1); BAR; SCHED;
;       LDB(B0, 1, 0); LDB(B1, 1, 1); SCHED; LDA(At, 1, 0); STAGE(SA(0, 1), a2 + hstep, voffA);
;       WAIT_V(8); WAIT_L(0); BAR; MMA(0, 0, At, B0); MMA(0, 1, At, B1); BAR; SCHED;
	s_waitcnt lgkmcnt(0)
	v_mfma_f32_16x16x32_f16 v[130:133], v[152:155], v[206:209], v[130:133]
	v_mfma_f32_16x16x32_f16 v[126:129], v[182:185], v[206:209], v[126:129]
	v_mfma_f32_16x16x32_f16 v[114:117], v[152:155], v[214:217], v[114:117]
	v_mfma_f32_16x16x32_f16 v[110:113], v[182:185], v[214:217], v[110:113]
	v_mfma_f32_16x16x32_f16 v[98:101], v[152:155], v[222:225], v[98:101]
	v_mfma_f32_16x16x32_f16 v[94:97], v[182:185], v[222:225], v[94:97]
	v_mfma_f32_16x16x32_f16 v[82:85], v[152:155], v[230:233], v[82:85]
	v_mfma_f32_16x16x32_f16 v[78:81], v[182:185], v[230:233], v[78:81]
	v_mfma_f32_16x16x32_f16 v[130:133], v[178:181], v[210:213], v[130:133]
	v_mfma_f32_16x16x32_f16 v[126:129], v[186:189], v[210:213], v[126:129]
	v_mfma_f32_16x16x32_f16 v[114:117], v[178:181], v[218:221], v[114:117]
	v_mfma_f32_16x16x32_f16 v[110:113], v[186:189], v[218:221], v[110:113]
	v_mfma_f32_16x16x32_f16 v[98:101], v[178:181], v[226:229], v[98:101]
	v_mfma_f32_16x16x32_f16 v[94:97], v[186:189], v[226:229], v[94:97]
	v_mfma_f32_16x16x32_f16 v[82:85], v[178:181], v[234:237], v[82:85]
	v_mfma_f32_16x16x32_f16 v[78:81], v[186:189], v[234:237], v[78:81]
	v_mfma_f32_16x16x32_f16 v[122:125], v[190:193], v[206:209], v[122:125]
	v_mfma_f32_16x16x32_f16 v[118:121], v[198:201], v[206:209], v[118:121]
	v_mfma_f32_16x16x32_f16 v[106:109], v[190:193], v[214:217], v[106:109]
	v_mfma_f32_16x16x32_f16 v[102:105], v[198:201], v[214:217], v[102:105]
	v_mfma_f32_16x16x32_f16 v[90:93], v[190:193], v[222:225], v[90:93]
	v_mfma_f32_16x16x32_f16 v[86:89], v[198:201], v[222:225], v[86:89]
	v_mfma_f32_16x16x32_f16 v[74:77], v[190:193], v[230:233], v[74:77]
	v_mfma_f32_16x16x32_f16 v[70:73], v[198:201], v[230:233], v[70:73]
	v_mfma_f32_16x16x32_f16 v[122:125], v[194:197], v[210:213], v[122:125]
	v_mfma_f32_16x16x32_f16 v[118:121], v[202:205], v[210:213], v[118:121]
	v_mfma_f32_16x16x32_f16 v[106:109], v[194:197], v[218:221], v[106:109]
	v_mfma_f32_16x16x32_f16 v[102:105], v[202:205], v[218:221], v[102:105]
	v_mfma_f32_16x16x32_f16 v[90:93], v[194:197], v[226:229], v[90:93]
	v_mfma_f32_16x16x32_f16 v[86:89], v[202:205], v[226:229], v[86:89]
	v_mfma_f32_16x16x32_f16 v[74:77], v[194:197], v[234:237], v[74:77]
	v_mfma_f32_16x16x32_f16 v[70:73], v[202:205], v[234:237], v[70:73]
	s_barrier
	s_add_i32 s50, s51, s30
	v_lshl_add_u64 v[238:239], s[22:23], 0, v[0:1]
	s_mov_b32 m0, s50
	ds_read_b128 v[206:209], v151 offset:16384
	ds_read_b128 v[210:213], v151 offset:17408
	ds_read_b128 v[214:217], v151 offset:18432
	ds_read_b128 v[218:221], v151 offset:19456
	ds_read_b128 v[222:225], v151 offset:20480
	ds_read_b128 v[226:229], v151 offset:21504
	ds_read_b128 v[230:233], v151 offset:22528
	ds_read_b128 v[234:237], v151 offset:23552
	global_load_lds_dwordx4 v[238:239], off
	s_add_i32 m0, s50, 0x2000
	s_add_u32 s50, s22, 0x40000
	v_lshl_add_u64 v[240:241], s[22:23], 0, v[2:3]
	s_addc_u32 s51, s23, 0
	s_add_i32 s49, s49, s30
	global_load_lds_dwordx4 v[240:241], off
	v_lshl_add_u64 v[242:243], s[50:51], 0, v[0:1]
	s_mov_b32 m0, s49
	v_lshl_add_u64 v[244:245], s[26:27], 0, v[134:135]
	global_load_lds_dwordx4 v[242:243], off
	v_lshl_add_u64 v[242:243], s[50:51], 0, v[2:3]
	s_add_i32 m0, s49, 0x2000
	s_nop 0
	global_load_lds_dwordx4 v[242:243], off
	v_lshl_add_u64 v[242:243], s[26:27], 0, v[138:139]
	s_waitcnt vmcnt(6)
	s_waitcnt lgkmcnt(0)
	s_barrier
	s_waitcnt lgkmcnt(0)
	v_mfma_f32_16x16x32_f16 v[66:69], v[152:155], v[206:209], v[66:69]
	v_mfma_f32_16x16x32_f16 v[62:65], v[182:185], v[206:209], v[62:65]
	v_mfma_f32_16x16x32_f16 v[50:53], v[152:155], v[214:217], v[50:53]
	v_mfma_f32_16x16x32_f16 v[46:49], v[182:185], v[214:217], v[46:49]
	v_mfma_f32_16x16x32_f16 v[34:37], v[152:155], v[222:225], v[34:37]
	v_mfma_f32_16x16x32_f16 v[30:33], v[182:185], v[222:225], v[30:33]
	v_mfma_f32_16x16x32_f16 v[18:21], v[152:155], v[230:233], v[18:21]
	v_mfma_f32_16x16x32_f16 v[14:17], v[182:185], v[230:233], v[14:17]
	v_mfma_f32_16x16x32_f16 v[66:69], v[178:181], v[210:213], v[66:69]
	v_mfma_f32_16x16x32_f16 v[62:65], v[186:189], v[210:213], v[62:65]
	v_mfma_f32_16x16x32_f16 v[50:53], v[178:181], v[218:221], v[50:53]
	v_mfma_f32_16x16x32_f16 v[46:49], v[186:189], v[218:221], v[46:49]
	v_mfma_f32_16x16x32_f16 v[34:37], v[178:181], v[226:229], v[34:37]
	v_mfma_f32_16x16x32_f16 v[30:33], v[186:189], v[226:229], v[30:33]
	v_mfma_f32_16x16x32_f16 v[18:21], v[178:181], v[234:237], v[18:21]
	v_mfma_f32_16x16x32_f16 v[14:17], v[186:189], v[234:237], v[14:17]
	v_mfma_f32_16x16x32_f16 v[58:61], v[190:193], v[206:209], v[58:61]
	v_mfma_f32_16x16x32_f16 v[54:57], v[198:201], v[206:209], v[54:57]
	v_mfma_f32_16x16x32_f16 v[42:45], v[190:193], v[214:217], v[42:45]
	v_mfma_f32_16x16x32_f16 v[38:41], v[198:201], v[214:217], v[38:41]
	v_mfma_f32_16x16x32_f16 v[26:29], v[190:193], v[222:225], v[26:29]
	v_mfma_f32_16x16x32_f16 v[22:25], v[198:201], v[222:225], v[22:25]
	v_mfma_f32_16x16x32_f16 v[10:13], v[190:193], v[230:233], v[10:13]
	v_mfma_f32_16x16x32_f16 v[6:9], v[198:201], v[230:233], v[6:9]
	v_mfma_f32_16x16x32_f16 v[58:61], v[194:197], v[210:213], v[58:61]
	v_mfma_f32_16x16x32_f16 v[54:57], v[202:205], v[210:213], v[54:57]
	v_mfma_f32_16x16x32_f16 v[42:45], v[194:197], v[218:221], v[42:45]
	v_mfma_f32_16x16x32_f16 v[38:41], v[202:205], v[218:221], v[38:41]
	v_mfma_f32_16x16x32_f16 v[26:29], v[194:197], v[226:229], v[26:29]
	v_mfma_f32_16x16x32_f16 v[22:25], v[202:205], v[226:229], v[22:25]
	v_mfma_f32_16x16x32_f16 v[10:13], v[194:197], v[234:237], v[10:13]
	v_mfma_f32_16x16x32_f16 v[6:9], v[202:205], v[234:237], v[6:9]
	s_barrier
; #define STAGE(bufoff, gbase, voff) do { _Pragma("unroll") for (int _i = 0; _i < 2; ++_i) \
;     __builtin_amdgcn_global_load_lds((const unsigned*)((const char*)(gbase) + (voff)[_i]), (LAS unsigned*)(lds + (bufoff) + ldsw + _i * 8192), 16, 0, 0); } while (0)
; #define LDA(dst, b, h) do { _Pragma("unroll") for (int m = 0; m < 4; ++m) _Pragma("unroll") for (int k = 0; k < 2; ++k) dst[m][k] = *(const LAS half8*)(lds + SA(b, h) + aoff + m * 2048 + k * 1024); } while (0)
; #define LDB(dst, b, h) do { _Pragma("unroll") for (int n = 0; n < 2; ++n) _Pragma("unroll") for (int k = 0; k < 2; ++k) dst[n][k] = *(const LAS half8*)(lds + SB(b, h) + boff + n * 2048 + k * 1024); } while (0)
; #define MMA(ai, bj, At_, Bt_) do { __builtin_amdgcn_s_setprio(1); \
;     _Pragma("unroll") for (int m = 0; m < 4; ++m) _Pragma("unroll") for (int n = 0; n < 2; ++n) _Pragma("unroll") for (int k = 0; k < 2; ++k) \
;       acc[ai][bj][m][n] = MFMA16(Bt_[n][k], At_[m][k], acc[ai][bj][m][n]); \
;     __builtin_amdgcn_s_setprio(0); } while (0)
; #define WAIT_V(n) asm volatile("s_waitcnt vmcnt(" #n ")" ::: "memory")
; #define WAIT_L(n) asm volatile("s_waitcnt lgkmcnt(" #n ")" ::: "memory")
; #define BAR __builtin_amdgcn_s_barrier()
; #define SCHED __builtin_amdgcn_sched_barrier(0)
; template <int EPI>
; DI void gemm_phase(const int wid_s, const h16* __restrict__ A, const h16* __restrict__ Bt, const int N, const int K, const EpiArgs ea) {
;     ...
;       LDB(B0, 1, 0); LDB(B1, 1, 1); SCHED; LDA(At, 1, 0); STAGE(SA(0, 1), a2 + hstep, voffA);
;       WAIT_V(8); WAIT_L(0); BAR; MMA(0, 0, At, B0); MMA(0, 1, At, B1); BAR; SCHED;
;       LDA(At, 1, 1); STAGE(SB(1, 0), b3, voffB); STAGE(SB(1, 1), b3 + hstep, voffB); STAGE(SA(1, 0), a3, voffA);
	s_add_i32 s49, 0, 0x18000
	v_add_u32_e32 v177, s49, v148
	s_add_i32 s50, 0, 0x1c000
	ds_read_b128 v[152:155], v177
	ds_read_b128 v[178:181], v177 offset:1024
	ds_read_b128 v[182:185], v177 offset:2048
	ds_read_b128 v[186:189], v177 offset:3072
	v_add_u32_e32 v177, s50, v148
	ds_read_b128 v[190:193], v177
	ds_read_b128 v[194:197], v177 offset:1024
	ds_read_b128 v[198:201], v177 offset:2048
	ds_read_b128 v[202:205], v177 offset:3072
	s_add_u32 s26, s26, 0x40000
	s_addc_u32 s27, s27, 0
	v_lshl_add_u64 v[246:247], s[26:27], 0, v[138:139]
	ds_read_b128 v[206:209], v151 offset:32768
	ds_read_b128 v[210:213], v151 offset:33792
	ds_read_b128 v[214:217], v151 offset:34816
	ds_read_b128 v[218:221], v151 offset:35840
	ds_read_b128 v[222:225], v151 offset:36864
	ds_read_b128 v[226:229], v151 offset:37888
	ds_read_b128 v[230:233], v151 offset:38912
	ds_read_b128 v[234:237], v151 offset:39936
	s_mov_b32 m0, s17
	s_nop 0
	global_load_lds_dwordx4 v[242:243], off
	s_mov_b32 m0, s19
	s_nop 0
	global_load_lds_dwordx4 v[244:245], off
	s_mov_b32 m0, s31
	s_nop 0
	global_load_lds_dwordx4 v[246:247], off
	v_lshl_add_u64 v[246:247], s[26:27], 0, v[134:135]
	s_mov_b32 m0, s38
	s_nop 0
	global_load_lds_dwordx4 v[246:247], off
	s_waitcnt vmcnt(8)
	s_waitcnt lgkmcnt(0)
	s_barrier
	s_waitcnt lgkmcnt(0)
	v_mfma_f32_16x16x32_f16 v[130:133], v[152:155], v[206:209], v[130:133]
	v_mfma_f32_16x16x32_f16 v[126:129], v[182:185], v[206:209], v[126:129]
	v_mfma_f32_16x16x32_f16 v[114:117], v[152:155], v[214:217], v[114:117]
	v_mfma_f32_16x16x32_f16 v[110:113], v[182:185], v[214:217], v[110:113]
	v_mfma_f32_16x16x32_f16 v[98:101], v[152:155], v[222:225], v[98:101]
	v_mfma_f32_16x16x32_f16 v[94:97], v[182:185], v[222:225], v[94:97]
	v_mfma_f32_16x16x32_f16 v[82:85], v[152:155], v[230:233], v[82:85]
	v_mfma_f32_16x16x32_f16 v[78:81], v[182:185], v[230:233], v[78:81]
	v_mfma_f32_16x16x32_f16 v[130:133], v[178:181], v[210:213], v[130:133]
	v_mfma_f32_16x16x32_f16 v[126:129], v[186:189], v[210:213], v[126:129]
	v_mfma_f32_16x16x32_f16 v[114:117], v[178:181], v[218:221], v[114:117]
	v_mfma_f32_16x16x32_f16 v[110:113], v[186:189], v[218:221], v[110:113]
	v_mfma_f32_16x16x32_f16 v[98:101], v[178:181], v[226:229], v[98:101]
	v_mfma_f32_16x16x32_f16 v[94:97], v[186:189], v[226:229], v[94:97]
	v_mfma_f32_16x16x32_f16 v[82:85], v[178:181], v[234:237], v[82:85]
	v_mfma_f32_16x16x32_f16 v[78:81], v[186:189], v[234:237], v[78:81]
	v_mfma_f32_16x16x32_f16 v[122:125], v[190:193], v[206:209], v[122:125]
	v_mfma_f32_16x16x32_f16 v[118:121], v[198:201], v[206:209], v[118:121]
	v_mfma_f32_16x16x32_f16 v[106:109], v[190:193], v[214:217], v[106:109]
	v_mfma_f32_16x16x32_f16 v[102:105], v[198:201], v[214:217], v[102:105]
	v_mfma_f32_16x16x32_f16 v[90:93], v[190:193], v[222:225], v[90:93]
	v_mfma_f32_16x16x32_f16 v[86:89], v[198:201], v[222:225], v[86:89]
	v_mfma_f32_16x16x32_f16 v[74:77], v[190:193], v[230:233], v[74:77]
	v_mfma_f32_16x16x32_f16 v[70:73], v[198:201], v[230:233], v[70:73]
	v_mfma_f32_16x16x32_f16 v[122:125], v[194:197], v[210:213], v[122:125]
	v_mfma_f32_16x16x32_f16 v[118:121], v[202:205], v[210:213], v[118:121]
	v_mfma_f32_16x16x32_f16 v[106:109], v[194:197], v[218:221], v[106:109]
	v_mfma_f32_16x16x32_f16 v[102:105], v[202:205], v[218:221], v[102:105]
	v_mfma_f32_16x16x32_f16 v[90:93], v[194:197], v[226:229], v[90:93]
	v_mfma_f32_16x16x32_f16 v[86:89], v[202:205], v[226:229], v[86:89]
	v_mfma_f32_16x16x32_f16 v[74:77], v[194:197], v[234:237], v[74:77]
	v_mfma_f32_16x16x32_f16 v[70:73], v[202:205], v[234:237], v[70:73]
	s_barrier
; #define STAGE(bufoff, gbase, voff) do { _Pragma("unroll") for (int _i = 0; _i < 2; ++_i) \
;     __builtin_amdgcn_global_load_lds((const unsigned*)((const char*)(gbase) + (voff)[_i]), (LAS unsigned*)(lds + (bufoff) + ldsw + _i * 8192), 16, 0, 0); } while (0)
; #define LDA(dst, b, h) do { _Pragma("unroll") for (int m = 0; m < 4; ++m) _Pragma("unroll") for (int k = 0; k < 2; ++k) dst[m][k] = *(const LAS half8*)(lds + SA(b, h) + aoff + m * 2048 + k * 1024); } while (0)
; #define MMA(ai, bj, At_, Bt_) do { __builtin_amdgcn_s_setprio(1); \
;     _Pragma("unroll") for (int m = 0; m < 4; ++m) _Pragma("unroll") for (int n = 0; n < 2; ++n) _Pragma("unroll") for (int k = 0; k < 2; ++k) \
;       acc[ai][bj][m][n] = MFMA16(Bt_[n][k], At_[m][k], acc[ai][bj][m][n]); \
;     __builtin_amdgcn_s_setprio(0); } while (0)
; #define WAIT_V(n) asm volatile("s_waitcnt vmcnt(" #n ")" ::: "memory")
; #define WAIT_L(n) asm volatile("s_waitcnt lgkmcnt(" #n ")" ::: "memory")
; #define BAR __builtin_amdgcn_s_barrier()
; #define SCHED __builtin_amdgcn_sched_barrier(0)
; template <int EPI>
; DI void gemm_phase(const int wid_s, const h16* __restrict__ A, const h16* __restrict__ Bt, const int N, const int K, const EpiArgs ea) {
;     ...
;       LDA(At, 1, 1); STAGE(SB(1, 0), b3, voffB); STAGE(SB(1, 1), b3 + hstep, voffB); STAGE(SA(1, 0), a3, voffA);
;       WAIT_V(8); WAIT_L(0); BAR; MMA(1, 0, At, B0); MMA(1, 1, At, B1); BAR; SCHED;
;     }
;     if (wr == 0) BAR;
	s_add_i32 s26, s49, s30
	v_lshl_add_u64 v[238:239], v[238:239], 0, s[36:37]
	s_mov_b32 m0, s26
	ds_read_b128 v[206:209], v151 offset:49152
	ds_read_b128 v[210:213], v151 offset:50176
	ds_read_b128 v[214:217], v151 offset:51200
	ds_read_b128 v[218:221], v151 offset:52224
	ds_read_b128 v[222:225], v151 offset:53248
	ds_read_b128 v[226:229], v151 offset:54272
	ds_read_b128 v[230:233], v151 offset:55296
	ds_read_b128 v[234:237], v151 offset:56320
	global_load_lds_dwordx4 v[238:239], off
	s_add_i32 m0, s26, 0x2000
	s_add_u32 s22, s22, 0x40080
	v_lshl_add_u64 v[238:239], v[240:241], 0, s[36:37]
	s_addc_u32 s23, s23, 0
	s_add_i32 s26, s50, s30
	global_load_lds_dwordx4 v[238:239], off
	v_lshl_add_u64 v[238:239], s[22:23], 0, v[0:1]
	s_mov_b32 m0, s26
	s_nop 0
	global_load_lds_dwordx4 v[238:239], off
	v_lshl_add_u64 v[238:239], s[22:23], 0, v[2:3]
	s_add_i32 m0, s26, 0x2000
	s_nop 0
	global_load_lds_dwordx4 v[238:239], off
	v_lshl_add_u64 v[238:239], v[242:243], 0, s[36:37]
	s_mov_b32 m0, s40
	s_nop 0
	global_load_lds_dwordx4 v[238:239], off
	v_lshl_add_u64 v[238:239], v[244:245], 0, s[36:37]
	s_mov_b32 m0, s41
	s_nop 0
	global_load_lds_dwordx4 v[238:239], off
	s_waitcnt vmcnt(8)
	s_waitcnt lgkmcnt(0)
	s_barrier
	s_waitcnt lgkmcnt(0)
	v_mfma_f32_16x16x32_f16 v[66:69], v[152:155], v[206:209], v[66:69]
	v_mfma_f32_16x16x32_f16 v[62:65], v[182:185], v[206:209], v[62:65]
	v_mfma_f32_16x16x32_f16 v[50:53], v[152:155], v[214:217], v[50:53]
	v_mfma_f32_16x16x32_f16 v[46:49], v[182:185], v[214:217], v[46:49]
	v_mfma_f32_16x16x32_f16 v[34:37], v[152:155], v[222:225], v[34:37]
	v_mfma_f32_16x16x32_f16 v[30:33], v[182:185], v[222:225], v[30:33]
	v_mfma_f32_16x16x32_f16 v[18:21], v[152:155], v[230:233], v[18:21]
	v_mfma_f32_16x16x32_f16 v[14:17], v[182:185], v[230:233], v[14:17]
	v_mfma_f32_16x16x32_f16 v[66:69], v[178:181], v[210:213], v[66:69]
	v_mfma_f32_16x16x32_f16 v[62:65], v[186:189], v[210:213], v[62:65]
	v_mfma_f32_16x16x32_f16 v[50:53], v[178:181], v[218:221], v[50:53]
	v_mfma_f32_16x16x32_f16 v[46:49], v[186:189], v[218:221], v[46:49]
	v_mfma_f32_16x16x32_f16 v[34:37], v[178:181], v[226:229], v[34:37]
	v_mfma_f32_16x16x32_f16 v[30:33], v[186:189], v[226:229], v[30:33]
	v_mfma_f32_16x16x32_f16 v[18:21], v[178:181], v[234:237], v[18:21]
	v_mfma_f32_16x16x32_f16 v[14:17], v[186:189], v[234:237], v[14:17]
	v_mfma_f32_16x16x32_f16 v[58:61], v[190:193], v[206:209], v[58:61]
	v_mfma_f32_16x16x32_f16 v[54:57], v[198:201], v[206:209], v[54:57]
	v_mfma_f32_16x16x32_f16 v[42:45], v[190:193], v[214:217], v[42:45]
	v_mfma_f32_16x16x32_f16 v[38:41], v[198:201], v[214:217], v[38:41]
	v_mfma_f32_16x16x32_f16 v[26:29], v[190:193], v[222:225], v[26:29]
	v_mfma_f32_16x16x32_f16 v[22:25], v[198:201], v[222:225], v[22:25]
	v_mfma_f32_16x16x32_f16 v[10:13], v[190:193], v[230:233], v[10:13]
	v_mfma_f32_16x16x32_f16 v[6:9], v[198:201], v[230:233], v[6:9]
	v_mfma_f32_16x16x32_f16 v[58:61], v[194:197], v[210:213], v[58:61]
	v_mfma_f32_16x16x32_f16 v[54:57], v[202:205], v[210:213], v[54:57]
	v_mfma_f32_16x16x32_f16 v[42:45], v[194:197], v[218:221], v[42:45]
	v_mfma_f32_16x16x32_f16 v[38:41], v[202:205], v[218:221], v[38:41]
	v_mfma_f32_16x16x32_f16 v[26:29], v[194:197], v[226:229], v[26:29]
	v_mfma_f32_16x16x32_f16 v[22:25], v[202:205], v[226:229], v[22:25]
	v_mfma_f32_16x16x32_f16 v[10:13], v[194:197], v[234:237], v[10:13]
	v_mfma_f32_16x16x32_f16 v[6:9], v[202:205], v[234:237], v[6:9]
	s_barrier
	s_add_i32 s48, s48, 2
	s_add_u32 s20, s20, 0x100
	s_addc_u32 s21, s21, 0
	s_cmp_gt_u32 s48, 13
	s_cbranch_scc0 .LBB0_141
	s_and_b64 vcc, exec, s[4:5]
	s_cbranch_vccz .LBB0_144
	s_barrier

; #define STAGE(bufoff, gbase, voff) do { _Pragma("unroll") for (int _i = 0; _i < 2; ++_i) \
;     __builtin_amdgcn_global_load_lds((const unsigned*)((const char*)(gbase) + (voff)[_i]), (LAS unsigned*)(lds + (bufoff) + ldsw + _i * 8192), 16, 0, 0); } while (0)
; #define LDA(dst, b, h) do { _Pragma("unroll") for (int m = 0; m < 4; ++m) _Pragma("unroll") for (int k = 0; k < 2; ++k) dst[m][k] = *(const LAS half8*)(lds + SA(b, h) + aoff + m * 2048 + k * 1024); } while (0)
; #define LDB(dst, b, h) do { _Pragma("unroll") for (int n = 0; n < 2; ++n) _Pragma("unroll") for (int k = 0; k < 2; ++k) dst[n][k] = *(const LAS half8*)(lds + SB(b, h) + boff + n * 2048 + k * 1024); } while (0)
; #define MMA(ai, bj, At_, Bt_) do { __builtin_amdgcn_s_setprio(1); \
;     _Pragma("unroll") for (int m = 0; m < 4; ++m) _Pragma("unroll") for (int n = 0; n < 2; ++n) _Pragma("unroll") for (int k = 0; k < 2; ++k) \
;       acc[ai][bj][m][n] = MFMA16(Bt_[n][k], At_[m][k], acc[ai][bj][m][n]); \
;     __builtin_amdgcn_s_setprio(0); } while (0)
; #define WAIT_V(n) asm volatile("s_waitcnt vmcnt(" #n ")" ::: "memory")
; #define WAIT_L(n) asm volatile("s_waitcnt lgkmcnt(" #n ")" ::: "memory")
; #define BAR __builtin_amdgcn_s_barrier()
; template <int EPI>
; DI void gemm_phase(const int wid_s, const h16* __restrict__ A, const h16* __restrict__ Bt, const int N, const int K, const EpiArgs ea) {
;     ...
;     const int Ln = L + (int)gridDim.x;
;     const bool has_next = Ln < nwg;
;     int nbrow = brow, nbcol = bcol;
;     if (has_next) TILE_RC(Ln, nbrow, nbcol);
;     const char* nA = (const char*)A + (size_t)nbrow * K * 2;
;     const char* nB = (const char*)Bt + (size_t)nbcol * K * 2;
;     for (int t = 0; t < nt; t += 2) {
;       const bool last = (t == nt - 2);
;       const char* a1 = cA + (size_t)(t + 1) * kstep;
;       const char* a2 = last ? nA : cA + (size_t)(t + 2) * kstep; const char* b2 = last ? nB : cB + (size_t)(t + 2) * kstep;
;       const char* a3 = a2 + kstep; const char* b3 = b2 + kstep;
;       LDB(B0, 0, 0); LDB(B1, 0, 1); SCHED; LDA(At, 0, 0); STAGE(SA(1, 1), a1 + hstep, voffA);
;       WAIT_V(8); WAIT_L(0); BAR; MMA(0, 0, At, B0); MMA(0, 1, At, B1); BAR; SCHED;
;       LDA(At, 0, 1); STAGE(SB(0, 0), b2, voffB); STAGE(SB(0, 1), b2 + hstep, voffB); STAGE(SA(0, 0), a2, voffA);
;       WAIT_V(8); WAIT_L(0); BAR; MMA(1, 0, At, B0); MMA(1, 1, At, B1); BAR; SCHED;
.LBB0_174:
	s_ashr_i32 s9, s8, 31
	s_lshl_b64 s[12:13], s[8:9], 11
	v_readlane_b32 s14, v250, 46
	v_readlane_b32 s15, v250, 47
	s_add_u32 s12, s14, s12
	s_addc_u32 s13, s15, s13
	s_ashr_i32 s11, s10, 31
	s_lshl_b64 s[14:15], s[10:11], 11
	v_readlane_b32 s9, v249, 6
	s_add_u32 s9, s9, s14
	v_readlane_b32 s11, v249, 7
	s_addc_u32 s11, s11, s15
	v_readlane_b32 s26, v249, 27
	s_add_u32 s41, s26, s20
	v_readlane_b32 s20, v249, 28
	s_addc_u32 s42, s20, s21
	s_add_u32 s20, s22, 0x40080
	v_mov_b32_e32 v6, 0
	s_addc_u32 s21, s23, 0
	s_mov_b32 s43, -2
	s_add_u32 s22, s20, 0xfffc0080
	s_addc_u32 s23, s21, -1
	s_add_i32 s44, 0, 0x10000
	s_cmp_eq_u32 s43, 12
	s_cselect_b32 s27, s13, s23
	s_cselect_b32 s26, s12, s22
	v_add_u32_e32 v177, s44, v148
	s_cselect_b32 s23, s11, s42
	s_cselect_b32 s22, s9, s41
	s_add_i32 s46, 0, 0x14000
	ds_read_b128 v[144:147], v177
	ds_read_b128 v[152:155], v177 offset:1024
	ds_read_b128 v[178:181], v177 offset:2048
	ds_read_b128 v[182:185], v177 offset:3072
	v_add_u32_e32 v177, s46, v148
	ds_read_b128 v[186:189], v177
	ds_read_b128 v[190:193], v177 offset:1024
	ds_read_b128 v[194:197], v177 offset:2048
	ds_read_b128 v[198:201], v177 offset:3072
	v_lshl_add_u64 v[234:235], s[20:21], 0, v[142:143]
	s_add_i32 m0, s17, 0xc000
	ds_read_b128 v[202:205], v151
	ds_read_b128 v[206:209], v151 offset:1024
	ds_read_b128 v[210:213], v151 offset:2048
	ds_read_b128 v[214:217], v151 offset:3072
	ds_read_b128 v[218:221], v151 offset:4096
	ds_read_b128 v[222:225], v151 offset:5120
	ds_read_b128 v[226:229], v151 offset:6144
	ds_read_b128 v[230:233], v151 offset:7168
	global_load_lds_dwordx4 v[234:235], off
	v_lshl_add_u64 v[234:235], s[20:21], 0, v[140:141]
	s_add_i32 m0, s17, 0xe000
	s_nop 0
	global_load_lds_dwordx4 v[234:235], off
	s_waitcnt vmcnt(8)
	s_waitcnt lgkmcnt(0)
	s_barrier
	s_waitcnt lgkmcnt(0)
	v_mfma_f32_16x16x32_f16 v[130:133], v[144:147], v[202:205], 0
	v_mfma_f32_16x16x32_f16 v[126:129], v[178:181], v[202:205], 0
	v_mfma_f32_16x16x32_f16 v[114:117], v[144:147], v[210:213], 0
	v_mfma_f32_16x16x32_f16 v[110:113], v[178:181], v[210:213], 0
	v_mfma_f32_16x16x32_f16 v[98:101], v[144:147], v[218:221], 0
	v_mfma_f32_16x16x32_f16 v[94:97], v[178:181], v[218:221], 0
	v_mfma_f32_16x16x32_f16 v[82:85], v[144:147], v[226:229], 0
	v_mfma_f32_16x16x32_f16 v[78:81], v[178:181], v[226:229], 0
	v_mfma_f32_16x16x32_f16 v[130:133], v[152:155], v[206:209], v[130:133]
	v_mfma_f32_16x16x32_f16 v[126:129], v[182:185], v[206:209], v[126:129]
	v_mfma_f32_16x16x32_f16 v[114:117], v[152:155], v[214:217], v[114:117]
	v_mfma_f32_16x16x32_f16 v[110:113], v[182:185], v[214:217], v[110:113]
	v_mfma_f32_16x16x32_f16 v[98:101], v[152:155], v[222:225], v[98:101]
	v_mfma_f32_16x16x32_f16 v[94:97], v[182:185], v[222:225], v[94:97]
	v_mfma_f32_16x16x32_f16 v[82:85], v[152:155], v[230:233], v[82:85]
	v_mfma_f32_16x16x32_f16 v[78:81], v[182:185], v[230:233], v[78:81]
	v_mfma_f32_16x16x32_f16 v[122:125], v[186:189], v[202:205], 0
	v_mfma_f32_16x16x32_f16 v[118:121], v[194:197], v[202:205], 0
	v_mfma_f32_16x16x32_f16 v[106:109], v[186:189], v[210:213], 0
	v_mfma_f32_16x16x32_f16 v[102:105], v[194:197], v[210:213], 0
	v_mfma_f32_16x16x32_f16 v[90:93], v[186:189], v[218:221], 0
	v_mfma_f32_16x16x32_f16 v[86:89], v[194:197], v[218:221], 0
	v_mfma_f32_16x16x32_f16 v[74:77], v[186:189], v[226:229], 0
	v_mfma_f32_16x16x32_f16 v[70:73], v[194:197], v[226:229], 0
	v_mfma_f32_16x16x32_f16 v[122:125], v[190:193], v[206:209], v[122:125]
	v_mfma_f32_16x16x32_f16 v[118:121], v[198:201], v[206:209], v[118:121]
	v_mfma_f32_16x16x32_f16 v[106:109], v[190:193], v[214:217], v[106:109]
	v_mfma_f32_16x16x32_f16 v[102:105], v[198:201], v[214:217], v[102:105]
	v_mfma_f32_16x16x32_f16 v[90:93], v[190:193], v[222:225], v[90:93]
	v_mfma_f32_16x16x32_f16 v[86:89], v[198:201], v[222:225], v[86:89]
	v_mfma_f32_16x16x32_f16 v[74:77], v[190:193], v[230:233], v[74:77]
	v_mfma_f32_16x16x32_f16 v[70:73], v[198:201], v[230:233], v[70:73]
	s_barrier
	s_add_i32 s44, s44, s30
	v_lshl_add_u64 v[234:235], s[22:23], 0, v[0:1]
	s_mov_b32 m0, s44
	ds_read_b128 v[202:205], v151 offset:16384
	ds_read_b128 v[206:209], v151 offset:17408
	ds_read_b128 v[210:213], v151 offset:18432
	ds_read_b128 v[214:217], v151 offset:19456
	ds_read_b128 v[218:221], v151 offset:20480
	ds_read_b128 v[222:225], v151 offset:21504
	ds_read_b128 v[226:229], v151 offset:22528
	ds_read_b128 v[230:233], v151 offset:23552
	global_load_lds_dwordx4 v[234:235], off
	s_add_i32 m0, s44, 0x2000
	s_add_u32 s44, s22, 0x40000
	v_lshl_add_u64 v[236:237], s[22:23], 0, v[138:139]
	s_addc_u32 s45, s23, 0
	s_add_i32 s46, s46, s30
	global_load_lds_dwordx4 v[236:237], off
	v_lshl_add_u64 v[238:239], s[44:45], 0, v[0:1]
	s_mov_b32 m0, s46
	v_lshl_add_u64 v[240:241], s[26:27], 0, v[134:135]
	global_load_lds_dwordx4 v[238:239], off
	v_lshl_add_u64 v[238:239], s[44:45], 0, v[138:139]
	s_add_i32 m0, s46, 0x2000
	s_nop 0
	global_load_lds_dwordx4 v[238:239], off
	v_lshl_add_u64 v[238:239], s[26:27], 0, v[2:3]
	s_waitcnt vmcnt(6)
	s_waitcnt lgkmcnt(0)
	s_barrier
; #define STAGE(bufoff, gbase, voff) do { _Pragma("unroll") for (int _i = 0; _i < 2; ++_i) \
;     __builtin_amdgcn_global_load_lds((const unsigned*)((const char*)(gbase) + (voff)[_i]), (LAS unsigned*)(lds + (bufoff) + ldsw + _i * 8192), 16, 0, 0); } while (0)
; #define LDA(dst, b, h) do { _Pragma("unroll") for (int m = 0; m < 4; ++m) _Pragma("unroll") for (int k = 0; k < 2; ++k) dst[m][k] = *(const LAS half8*)(lds + SA(b, h) + aoff + m * 2048 + k * 1024); } while (0)
; #define LDB(dst, b, h) do { _Pragma("unroll") for (int n = 0; n < 2; ++n) _Pragma("unroll") for (int k = 0; k < 2; ++k) dst[n][k] = *(const LAS half8*)(lds + SB(b, h) + boff + n * 2048 + k * 1024); } while (0)
; #define MMA(ai, bj, At_, Bt_) do { __builtin_amdgcn_s_setprio(1); \
;     _Pragma("unroll") for (int m = 0; m < 4; ++m) _Pragma("unroll") for (int n = 0; n < 2; ++n) _Pragma("unroll") for (int k = 0; k < 2; ++k) \
;       acc[ai][bj][m][n] = MFMA16(Bt_[n][k], At_[m][k], acc[ai][bj][m][n]); \
;     __builtin_amdgcn_s_setprio(0); } while (0)
; #define WAIT_V(n) asm volatile("s_waitcnt vmcnt(" #n ")" ::: "memory")
; #define WAIT_L(n) asm volatile("s_waitcnt lgkmcnt(" #n ")" ::: "memory")
; #define BAR __builtin_amdgcn_s_barrier()
; #define SCHED __builtin_amdgcn_sched_barrier(0)
; template <int EPI>
; DI void gemm_phase(const int wid_s, const h16* __restrict__ A, const h16* __restrict__ Bt, const int N, const int K, const EpiArgs ea) {
;     ...
;       WAIT_V(8); WAIT_L(0); BAR; MMA(1, 0, At, B0); MMA(1, 1, At, B1); BAR; SCHED;
;       LDB(B0, 1, 0); LDB(B1, 1, 1); SCHED; LDA(At, 1, 0); STAGE(SA(0, 1), a2 + hstep, voffA);
;       WAIT_V(8); WAIT_L(0); BAR; MMA(0, 0, At, B0); MMA(0, 1, At, B1); BAR; SCHED;
;       LDA(At, 1, 1); STAGE(SB(1, 0), b3, voffB); STAGE(SB(1, 1), b3 + hstep, voffB); STAGE(SA(1, 0), a3, voffA);
	s_waitcnt lgkmcnt(0)
	v_mfma_f32_16x16x32_f16 v[66:69], v[144:147], v[202:205], 0
	v_mfma_f32_16x16x32_f16 v[62:65], v[178:181], v[202:205], 0
	v_mfma_f32_16x16x32_f16 v[50:53], v[144:147], v[210:213], 0
	v_mfma_f32_16x16x32_f16 v[46:49], v[178:181], v[210:213], 0
	v_mfma_f32_16x16x32_f16 v[34:37], v[144:147], v[218:221], 0
	v_mfma_f32_16x16x32_f16 v[30:33], v[178:181], v[218:221], 0
	v_mfma_f32_16x16x32_f16 v[18:21], v[144:147], v[226:229], 0
	v_mfma_f32_16x16x32_f16 v[14:17], v[178:181], v[226:229], 0
	v_mfma_f32_16x16x32_f16 v[66:69], v[152:155], v[206:209], v[66:69]
	v_mfma_f32_16x16x32_f16 v[62:65], v[182:185], v[206:209], v[62:65]
	v_mfma_f32_16x16x32_f16 v[50:53], v[152:155], v[214:217], v[50:53]
	v_mfma_f32_16x16x32_f16 v[46:49], v[182:185], v[214:217], v[46:49]
	v_mfma_f32_16x16x32_f16 v[34:37], v[152:155], v[222:225], v[34:37]
	v_mfma_f32_16x16x32_f16 v[30:33], v[182:185], v[222:225], v[30:33]
	v_mfma_f32_16x16x32_f16 v[18:21], v[152:155], v[230:233], v[18:21]
	v_mfma_f32_16x16x32_f16 v[14:17], v[182:185], v[230:233], v[14:17]
	v_mfma_f32_16x16x32_f16 v[58:61], v[186:189], v[202:205], 0
	v_mfma_f32_16x16x32_f16 v[54:57], v[194:197], v[202:205], 0
	v_mfma_f32_16x16x32_f16 v[42:45], v[186:189], v[210:213], 0
	v_mfma_f32_16x16x32_f16 v[38:41], v[194:197], v[210:213], 0
	v_mfma_f32_16x16x32_f16 v[26:29], v[186:189], v[218:221], 0
	v_mfma_f32_16x16x32_f16 v[22:25], v[194:197], v[218:221], 0
	v_mfma_f32_16x16x32_f16 v[10:13], v[186:189], v[226:229], 0
	v_mfma_f32_16x16x32_f16 v[6:9], v[194:197], v[226:229], 0
	v_mfma_f32_16x16x32_f16 v[58:61], v[190:193], v[206:209], v[58:61]
	v_mfma_f32_16x16x32_f16 v[54:57], v[198:201], v[206:209], v[54:57]
	v_mfma_f32_16x16x32_f16 v[42:45], v[190:193], v[214:217], v[42:45]
	v_mfma_f32_16x16x32_f16 v[38:41], v[198:201], v[214:217], v[38:41]
	v_mfma_f32_16x16x32_f16 v[26:29], v[190:193], v[222:225], v[26:29]
	v_mfma_f32_16x16x32_f16 v[22:25], v[198:201], v[222:225], v[22:25]
	v_mfma_f32_16x16x32_f16 v[10:13], v[190:193], v[230:233], v[10:13]
	v_mfma_f32_16x16x32_f16 v[6:9], v[198:201], v[230:233], v[6:9]
	s_barrier
	s_add_i32 s44, 0, 0x18000
	v_add_u32_e32 v177, s44, v148
	s_add_i32 s45, 0, 0x1c000
	ds_read_b128 v[144:147], v177
	ds_read_b128 v[152:155], v177 offset:1024
	ds_read_b128 v[178:181], v177 offset:2048
	ds_read_b128 v[182:185], v177 offset:3072
	v_add_u32_e32 v177, s45, v148
	ds_read_b128 v[186:189], v177
	ds_read_b128 v[190:193], v177 offset:1024
	ds_read_b128 v[194:197], v177 offset:2048
	ds_read_b128 v[198:201], v177 offset:3072
	s_add_u32 s26, s26, 0x40000
	s_addc_u32 s27, s27, 0
	v_lshl_add_u64 v[242:243], s[26:27], 0, v[2:3]
	ds_read_b128 v[202:205], v151 offset:32768
	ds_read_b128 v[206:209], v151 offset:33792
	ds_read_b128 v[210:213], v151 offset:34816
	ds_read_b128 v[214:217], v151 offset:35840
	ds_read_b128 v[218:221], v151 offset:36864
	ds_read_b128 v[222:225], v151 offset:37888
	ds_read_b128 v[226:229], v151 offset:38912
	ds_read_b128 v[230:233], v151 offset:39936
	s_mov_b32 m0, s17
	s_nop 0
	global_load_lds_dwordx4 v[238:239], off
	s_mov_b32 m0, s19
	s_nop 0
	global_load_lds_dwordx4 v[240:241], off
	s_mov_b32 m0, s31
	s_nop 0
	global_load_lds_dwordx4 v[242:243], off
	v_lshl_add_u64 v[242:243], s[26:27], 0, v[134:135]
	s_mov_b32 m0, s38
	s_nop 0
	global_load_lds_dwordx4 v[242:243], off
	s_waitcnt vmcnt(8)
	s_waitcnt lgkmcnt(0)
	s_barrier
	s_waitcnt lgkmcnt(0)
	v_mfma_f32_16x16x32_f16 v[130:133], v[144:147], v[202:205], v[130:133]
	v_mfma_f32_16x16x32_f16 v[126:129], v[178:181], v[202:205], v[126:129]
	v_mfma_f32_16x16x32_f16 v[114:117], v[144:147], v[210:213], v[114:117]
	v_mfma_f32_16x16x32_f16 v[110:113], v[178:181], v[210:213], v[110:113]
	v_mfma_f32_16x16x32_f16 v[98:101], v[144:147], v[218:221], v[98:101]
	v_mfma_f32_16x16x32_f16 v[94:97], v[178:181], v[218:221], v[94:97]
	v_mfma_f32_16x16x32_f16 v[82:85], v[144:147], v[226:229], v[82:85]
	v_mfma_f32_16x16x32_f16 v[78:81], v[178:181], v[226:229], v[78:81]
	v_mfma_f32_16x16x32_f16 v[130:133], v[152:155], v[206:209], v[130:133]
	v_mfma_f32_16x16x32_f16 v[126:129], v[182:185], v[206:209], v[126:129]
	v_mfma_f32_16x16x32_f16 v[114:117], v[152:155], v[214:217], v[114:117]
	v_mfma_f32_16x16x32_f16 v[110:113], v[182:185], v[214:217], v[110:113]
	v_mfma_f32_16x16x32_f16 v[98:101], v[152:155], v[222:225], v[98:101]
	v_mfma_f32_16x16x32_f16 v[94:97], v[182:185], v[222:225], v[94:97]
	v_mfma_f32_16x16x32_f16 v[82:85], v[152:155], v[230:233], v[82:85]
	v_mfma_f32_16x16x32_f16 v[78:81], v[182:185], v[230:233], v[78:81]
	v_mfma_f32_16x16x32_f16 v[122:125], v[186:189], v[202:205], v[122:125]
	v_mfma_f32_16x16x32_f16 v[118:121], v[194:197], v[202:205], v[118:121]
	v_mfma_f32_16x16x32_f16 v[106:109], v[186:189], v[210:213], v[106:109]
	v_mfma_f32_16x16x32_f16 v[102:105], v[194:197], v[210:213], v[102:105]
	v_mfma_f32_16x16x32_f16 v[90:93], v[186:189], v[218:221], v[90:93]
	v_mfma_f32_16x16x32_f16 v[86:89], v[194:197], v[218:221], v[86:89]
	v_mfma_f32_16x16x32_f16 v[74:77], v[186:189], v[226:229], v[74:77]
	v_mfma_f32_16x16x32_f16 v[70:73], v[194:197], v[226:229], v[70:73]
	v_mfma_f32_16x16x32_f16 v[122:125], v[190:193], v[206:209], v[122:125]
	v_mfma_f32_16x16x32_f16 v[118:121], v[198:201], v[206:209], v[118:121]
	v_mfma_f32_16x16x32_f16 v[106:109], v[190:193], v[214:217], v[106:109]
	v_mfma_f32_16x16x32_f16 v[102:105], v[198:201], v[214:217], v[102:105]
	v_mfma_f32_16x16x32_f16 v[90:93], v[190:193], v[222:225], v[90:93]
	v_mfma_f32_16x16x32_f16 v[86:89], v[198:201], v[222:225], v[86:89]
	v_mfma_f32_16x16x32_f16 v[74:77], v[190:193], v[230:233], v[74:77]
	v_mfma_f32_16x16x32_f16 v[70:73], v[198:201], v[230:233], v[70:73]
	s_barrier
; #define STAGE(bufoff, gbase, voff) do { _Pragma("unroll") for (int _i = 0; _i < 2; ++_i) \
;     __builtin_amdgcn_global_load_lds((const unsigned*)((const char*)(gbase) + (voff)[_i]), (LAS unsigned*)(lds + (bufoff) + ldsw + _i * 8192), 16, 0, 0); } while (0)
; #define LDA(dst, b, h) do { _Pragma("unroll") for (int m = 0; m < 4; ++m) _Pragma("unroll") for (int k = 0; k < 2; ++k) dst[m][k] = *(const LAS half8*)(lds + SA(b, h) + aoff + m * 2048 + k * 1024); } while (0)
; #define LDB(dst, b, h) do { _Pragma("unroll") for (int n = 0; n < 2; ++n) _Pragma("unroll") for (int k = 0; k < 2; ++k) dst[n][k] = *(const LAS half8*)(lds + SB(b, h) + boff + n * 2048 + k * 1024); } while (0)
; #define MMA(ai, bj, At_, Bt_) do { __builtin_amdgcn_s_setprio(1); \
;     _Pragma("unroll") for (int m = 0; m < 4; ++m) _Pragma("unroll") for (int n = 0; n < 2; ++n) _Pragma("unroll") for (int k = 0; k < 2; ++k) \
;       acc[ai][bj][m][n] = MFMA16(Bt_[n][k], At_[m][k], acc[ai][bj][m][n]); \
;     __builtin_amdgcn_s_setprio(0); } while (0)
; #define WAIT_V(n) asm volatile("s_waitcnt vmcnt(" #n ")" ::: "memory")
; #define WAIT_L(n) asm volatile("s_waitcnt lgkmcnt(" #n ")" ::: "memory")
; #define BAR __builtin_amdgcn_s_barrier()
; #define SCHED __builtin_amdgcn_sched_barrier(0)
; template <int EPI>
; DI void gemm_phase(const int wid_s, const h16* __restrict__ A, const h16* __restrict__ Bt, const int N, const int K, const EpiArgs ea) {
;     ...
;     for (int t = 0; t < nt; t += 2) {
;       const bool last = (t == nt - 2);
;       const char* a1 = cA + (size_t)(t + 1) * kstep;
;       const char* a2 = last ? nA : cA + (size_t)(t + 2) * kstep; const char* b2 = last ? nB : cB + (size_t)(t + 2) * kstep;
;       const char* a3 = a2 + kstep; const char* b3 = b2 + kstep;
;       LDB(B0, 0, 0); LDB(B1, 0, 1); SCHED; LDA(At, 0, 0); STAGE(SA(1, 1), a1 + hstep, voffA);
;     ...
;       LDA(At, 1, 1); STAGE(SB(1, 0), b3, voffB); STAGE(SB(1, 1), b3 + hstep, voffB); STAGE(SA(1, 0), a3, voffA);
;       WAIT_V(8); WAIT_L(0); BAR; MMA(1, 0, At, B0); MMA(1, 1, At, B1); BAR; SCHED;
	s_add_i32 s26, s44, s30
	v_lshl_add_u64 v[234:235], v[234:235], 0, s[36:37]
	s_mov_b32 m0, s26
	ds_read_b128 v[202:205], v151 offset:49152
	ds_read_b128 v[206:209], v151 offset:50176
	ds_read_b128 v[210:213], v151 offset:51200
	ds_read_b128 v[214:217], v151 offset:52224
	ds_read_b128 v[218:221], v151 offset:53248
	ds_read_b128 v[222:225], v151 offset:54272
	ds_read_b128 v[226:229], v151 offset:55296
	ds_read_b128 v[230:233], v151 offset:56320
	global_load_lds_dwordx4 v[234:235], off
	s_add_i32 m0, s26, 0x2000
	s_add_u32 s22, s22, 0x40080
	v_lshl_add_u64 v[234:235], v[236:237], 0, s[36:37]
	s_addc_u32 s23, s23, 0
	s_add_i32 s26, s45, s30
	global_load_lds_dwordx4 v[234:235], off
	v_lshl_add_u64 v[234:235], s[22:23], 0, v[0:1]
	s_mov_b32 m0, s26
	s_nop 0
	global_load_lds_dwordx4 v[234:235], off
	v_lshl_add_u64 v[234:235], s[22:23], 0, v[138:139]
	s_add_i32 m0, s26, 0x2000
	s_nop 0
	global_load_lds_dwordx4 v[234:235], off
	v_lshl_add_u64 v[234:235], v[238:239], 0, s[36:37]
	s_mov_b32 m0, s39
	s_nop 0
	global_load_lds_dwordx4 v[234:235], off
	v_lshl_add_u64 v[234:235], v[240:241], 0, s[36:37]
	s_mov_b32 m0, s40
	s_nop 0
	global_load_lds_dwordx4 v[234:235], off
	s_waitcnt vmcnt(8)
	s_waitcnt lgkmcnt(0)
	s_barrier
	s_waitcnt lgkmcnt(0)
	v_mfma_f32_16x16x32_f16 v[66:69], v[144:147], v[202:205], v[66:69]
	v_mfma_f32_16x16x32_f16 v[62:65], v[178:181], v[202:205], v[62:65]
	v_mfma_f32_16x16x32_f16 v[50:53], v[144:147], v[210:213], v[50:53]
	v_mfma_f32_16x16x32_f16 v[46:49], v[178:181], v[210:213], v[46:49]
	v_mfma_f32_16x16x32_f16 v[34:37], v[144:147], v[218:221], v[34:37]
	v_mfma_f32_16x16x32_f16 v[30:33], v[178:181], v[218:221], v[30:33]
	v_mfma_f32_16x16x32_f16 v[18:21], v[144:147], v[226:229], v[18:21]
	v_mfma_f32_16x16x32_f16 v[14:17], v[178:181], v[226:229], v[14:17]
	v_mfma_f32_16x16x32_f16 v[66:69], v[152:155], v[206:209], v[66:69]
	v_mfma_f32_16x16x32_f16 v[62:65], v[182:185], v[206:209], v[62:65]
	v_mfma_f32_16x16x32_f16 v[50:53], v[152:155], v[214:217], v[50:53]
	v_mfma_f32_16x16x32_f16 v[46:49], v[182:185], v[214:217], v[46:49]
	v_mfma_f32_16x16x32_f16 v[34:37], v[152:155], v[222:225], v[34:37]
	v_mfma_f32_16x16x32_f16 v[30:33], v[182:185], v[222:225], v[30:33]
	v_mfma_f32_16x16x32_f16 v[18:21], v[152:155], v[230:233], v[18:21]
	v_mfma_f32_16x16x32_f16 v[14:17], v[182:185], v[230:233], v[14:17]
	v_mfma_f32_16x16x32_f16 v[58:61], v[186:189], v[202:205], v[58:61]
	v_mfma_f32_16x16x32_f16 v[54:57], v[194:197], v[202:205], v[54:57]
	v_mfma_f32_16x16x32_f16 v[42:45], v[186:189], v[210:213], v[42:45]
	v_mfma_f32_16x16x32_f16 v[38:41], v[194:197], v[210:213], v[38:41]
	v_mfma_f32_16x16x32_f16 v[26:29], v[186:189], v[218:221], v[26:29]
	v_mfma_f32_16x16x32_f16 v[22:25], v[194:197], v[218:221], v[22:25]
	v_mfma_f32_16x16x32_f16 v[10:13], v[186:189], v[226:229], v[10:13]
	v_mfma_f32_16x16x32_f16 v[6:9], v[194:197], v[226:229], v[6:9]
	v_mfma_f32_16x16x32_f16 v[58:61], v[190:193], v[206:209], v[58:61]
	v_mfma_f32_16x16x32_f16 v[54:57], v[198:201], v[206:209], v[54:57]
	v_mfma_f32_16x16x32_f16 v[42:45], v[190:193], v[214:217], v[42:45]
	v_mfma_f32_16x16x32_f16 v[38:41], v[198:201], v[214:217], v[38:41]
	v_mfma_f32_16x16x32_f16 v[26:29], v[190:193], v[222:225], v[26:29]
	v_mfma_f32_16x16x32_f16 v[22:25], v[198:201], v[222:225], v[22:25]
	v_mfma_f32_16x16x32_f16 v[10:13], v[190:193], v[230:233], v[10:13]
	v_mfma_f32_16x16x32_f16 v[6:9], v[198:201], v[230:233], v[6:9]
	s_barrier
	s_add_i32 s43, s43, 2
	s_add_u32 s41, s41, 0x100
	s_addc_u32 s42, s42, 0
	s_add_u32 s20, s20, 0x100
	s_addc_u32 s21, s21, 0
	s_cmp_gt_u32 s43, 13
.LBB0_175:
	s_add_u32 s22, s20, 0xfffc0080
	s_addc_u32 s23, s21, -1
	s_add_i32 s44, 0, 0x10000
	s_cmp_eq_u32 s43, 12
	s_cselect_b32 s27, s13, s23
	s_cselect_b32 s26, s12, s22
	v_add_u32_e32 v177, s44, v148
	s_cselect_b32 s23, s11, s42
	s_cselect_b32 s22, s9, s41
	s_add_i32 s46, 0, 0x14000
	ds_read_b128 v[144:147], v177
	ds_read_b128 v[152:155], v177 offset:1024
	ds_read_b128 v[178:181], v177 offset:2048
	ds_read_b128 v[182:185], v177 offset:3072
	v_add_u32_e32 v177, s46, v148
	ds_read_b128 v[186:189], v177
	ds_read_b128 v[190:193], v177 offset:1024
	ds_read_b128 v[194:197], v177 offset:2048
	ds_read_b128 v[198:201], v177 offset:3072
	v_lshl_add_u64 v[234:235], s[20:21], 0, v[142:143]
	s_add_i32 m0, s17, 0xc000
	ds_read_b128 v[202:205], v151
	ds_read_b128 v[206:209], v151 offset:1024
	ds_read_b128 v[210:213], v151 offset:2048
	ds_read_b128 v[214:217], v151 offset:3072
	ds_read_b128 v[218:221], v151 offset:4096
	ds_read_b128 v[222:225], v151 offset:5120
	ds_read_b128 v[226:229], v151 offset:6144
	ds_read_b128 v[230:233], v151 offset:7168
	global_load_lds_dwordx4 v[234:235], off
	v_lshl_add_u64 v[234:235], s[20:21], 0, v[140:141]
	s_add_i32 m0, s17, 0xe000
	s_nop 0
	global_load_lds_dwordx4 v[234:235], off
	s_waitcnt vmcnt(8)
	s_waitcnt lgkmcnt(0)
	s_barrier
; #define STAGE(bufoff, gbase, voff) do { _Pragma("unroll") for (int _i = 0; _i < 2; ++_i) \
;     __builtin_amdgcn_global_load_lds((const unsigned*)((const char*)(gbase) + (voff)[_i]), (LAS unsigned*)(lds + (bufoff) + ldsw + _i * 8192), 16, 0, 0); } while (0)
; #define LDA(dst, b, h) do { _Pragma("unroll") for (int m = 0; m < 4; ++m) _Pragma("unroll") for (int k = 0; k < 2; ++k) dst[m][k] = *(const LAS half8*)(lds + SA(b, h) + aoff + m * 2048 + k * 1024); } while (0)
; #define LDB(dst, b, h) do { _Pragma("unroll") for (int n = 0; n < 2; ++n) _Pragma("unroll") for (int k = 0; k < 2; ++k) dst[n][k] = *(const LAS half8*)(lds + SB(b, h) + boff + n * 2048 + k * 1024); } while (0)
; #define MMA(ai, bj, At_, Bt_) do { __builtin_amdgcn_s_setprio(1); \
;     _Pragma("unroll") for (int m = 0; m < 4; ++m) _Pragma("unroll") for (int n = 0; n < 2; ++n) _Pragma("unroll") for (int k = 0; k < 2; ++k) \
;       acc[ai][bj][m][n] = MFMA16(Bt_[n][k], At_[m][k], acc[ai][bj][m][n]); \
;     __builtin_amdgcn_s_setprio(0); } while (0)
; #define WAIT_V(n) asm volatile("s_waitcnt vmcnt(" #n ")" ::: "memory")
; #define WAIT_L(n) asm volatile("s_waitcnt lgkmcnt(" #n ")" ::: "memory")
; #define BAR __builtin_amdgcn_s_barrier()
; #define SCHED __builtin_amdgcn_sched_barrier(0)
; template <int EPI>
; DI void gemm_phase(const int wid_s, const h16* __restrict__ A, const h16* __restrict__ Bt, const int N, const int K, const EpiArgs ea) {
;     ...
;       WAIT_V(8); WAIT_L(0); BAR; MMA(0, 0, At, B0); MMA(0, 1, At, B1); BAR; SCHED;
;       LDA(At, 0, 1); STAGE(SB(0, 0), b2, voffB); STAGE(SB(0, 1), b2 + hstep, voffB); STAGE(SA(0, 0), a2, voffA);
;       WAIT_V(8); WAIT_L(0); BAR; MMA(1, 0, At, B0); MMA(1, 1, At, B1); BAR; SCHED;
;       LDB(B0, 1, 0); LDB(B1, 1, 1); SCHED; LDA(At, 1, 0); STAGE(SA(0, 1), a2 + hstep, voffA);
;       WAIT_V(8); WAIT_L(0); BAR; MMA(0, 0, At, B0); MMA(0, 1, At, B1); BAR; SCHED;
	s_waitcnt lgkmcnt(0)
	v_mfma_f32_16x16x32_f16 v[130:133], v[144:147], v[202:205], v[130:133]
	v_mfma_f32_16x16x32_f16 v[126:129], v[178:181], v[202:205], v[126:129]
	v_mfma_f32_16x16x32_f16 v[114:117], v[144:147], v[210:213], v[114:117]
	v_mfma_f32_16x16x32_f16 v[110:113], v[178:181], v[210:213], v[110:113]
	v_mfma_f32_16x16x32_f16 v[98:101], v[144:147], v[218:221], v[98:101]
	v_mfma_f32_16x16x32_f16 v[94:97], v[178:181], v[218:221], v[94:97]
	v_mfma_f32_16x16x32_f16 v[82:85], v[144:147], v[226:229], v[82:85]
	v_mfma_f32_16x16x32_f16 v[78:81], v[178:181], v[226:229], v[78:81]
	v_mfma_f32_16x16x32_f16 v[130:133], v[152:155], v[206:209], v[130:133]
	v_mfma_f32_16x16x32_f16 v[126:129], v[182:185], v[206:209], v[126:129]
	v_mfma_f32_16x16x32_f16 v[114:117], v[152:155], v[214:217], v[114:117]
	v_mfma_f32_16x16x32_f16 v[110:113], v[182:185], v[214:217], v[110:113]
	v_mfma_f32_16x16x32_f16 v[98:101], v[152:155], v[222:225], v[98:101]
	v_mfma_f32_16x16x32_f16 v[94:97], v[182:185], v[222:225], v[94:97]
	v_mfma_f32_16x16x32_f16 v[82:85], v[152:155], v[230:233], v[82:85]
	v_mfma_f32_16x16x32_f16 v[78:81], v[182:185], v[230:233], v[78:81]
	v_mfma_f32_16x16x32_f16 v[122:125], v[186:189], v[202:205], v[122:125]
	v_mfma_f32_16x16x32_f16 v[118:121], v[194:197], v[202:205], v[118:121]
	v_mfma_f32_16x16x32_f16 v[106:109], v[186:189], v[210:213], v[106:109]
	v_mfma_f32_16x16x32_f16 v[102:105], v[194:197], v[210:213], v[102:105]
	v_mfma_f32_16x16x32_f16 v[90:93], v[186:189], v[218:221], v[90:93]
	v_mfma_f32_16x16x32_f16 v[86:89], v[194:197], v[218:221], v[86:89]
	v_mfma_f32_16x16x32_f16 v[74:77], v[186:189], v[226:229], v[74:77]
	v_mfma_f32_16x16x32_f16 v[70:73], v[194:197], v[226:229], v[70:73]
	v_mfma_f32_16x16x32_f16 v[122:125], v[190:193], v[206:209], v[122:125]
	v_mfma_f32_16x16x32_f16 v[118:121], v[198:201], v[206:209], v[118:121]
	v_mfma_f32_16x16x32_f16 v[106:109], v[190:193], v[214:217], v[106:109]
	v_mfma_f32_16x16x32_f16 v[102:105], v[198:201], v[214:217], v[102:105]
	v_mfma_f32_16x16x32_f16 v[90:93], v[190:193], v[222:225], v[90:93]
	v_mfma_f32_16x16x32_f16 v[86:89], v[198:201], v[222:225], v[86:89]
	v_mfma_f32_16x16x32_f16 v[74:77], v[190:193], v[230:233], v[74:77]
	v_mfma_f32_16x16x32_f16 v[70:73], v[198:201], v[230:233], v[70:73]
	s_barrier
	s_add_i32 s44, s44, s30
	v_lshl_add_u64 v[234:235], s[22:23], 0, v[0:1]
	s_mov_b32 m0, s44
	ds_read_b128 v[202:205], v151 offset:16384
	ds_read_b128 v[206:209], v151 offset:17408
	ds_read_b128 v[210:213], v151 offset:18432
	ds_read_b128 v[214:217], v151 offset:19456
	ds_read_b128 v[218:221], v151 offset:20480
	ds_read_b128 v[222:225], v151 offset:21504
	ds_read_b128 v[226:229], v151 offset:22528
	ds_read_b128 v[230:233], v151 offset:23552
	global_load_lds_dwordx4 v[234:235], off
	s_add_i32 m0, s44, 0x2000
	s_add_u32 s44, s22, 0x40000
	v_lshl_add_u64 v[236:237], s[22:23], 0, v[138:139]
	s_addc_u32 s45, s23, 0
	s_add_i32 s46, s46, s30
	global_load_lds_dwordx4 v[236:237], off
	v_lshl_add_u64 v[238:239], s[44:45], 0, v[0:1]
	s_mov_b32 m0, s46
	v_lshl_add_u64 v[240:241], s[26:27], 0, v[134:135]
	global_load_lds_dwordx4 v[238:239], off
	v_lshl_add_u64 v[238:239], s[44:45], 0, v[138:139]
	s_add_i32 m0, s46, 0x2000
	s_nop 0
	global_load_lds_dwordx4 v[238:239], off
	v_lshl_add_u64 v[238:239], s[26:27], 0, v[2:3]
	s_waitcnt vmcnt(6)
	s_waitcnt lgkmcnt(0)
	s_barrier
	s_waitcnt lgkmcnt(0)
	v_mfma_f32_16x16x32_f16 v[66:69], v[144:147], v[202:205], v[66:69]
	v_mfma_f32_16x16x32_f16 v[62:65], v[178:181], v[202:205], v[62:65]
	v_mfma_f32_16x16x32_f16 v[50:53], v[144:147], v[210:213], v[50:53]
	v_mfma_f32_16x16x32_f16 v[46:49], v[178:181], v[210:213], v[46:49]
	v_mfma_f32_16x16x32_f16 v[34:37], v[144:147], v[218:221], v[34:37]
	v_mfma_f32_16x16x32_f16 v[30:33], v[178:181], v[218:221], v[30:33]
	v_mfma_f32_16x16x32_f16 v[18:21], v[144:147], v[226:229], v[18:21]
	v_mfma_f32_16x16x32_f16 v[14:17], v[178:181], v[226:229], v[14:17]
	v_mfma_f32_16x16x32_f16 v[66:69], v[152:155], v[206:209], v[66:69]
	v_mfma_f32_16x16x32_f16 v[62:65], v[182:185], v[206:209], v[62:65]
	v_mfma_f32_16x16x32_f16 v[50:53], v[152:155], v[214:217], v[50:53]
	v_mfma_f32_16x16x32_f16 v[46:49], v[182:185], v[214:217], v[46:49]
	v_mfma_f32_16x16x32_f16 v[34:37], v[152:155], v[222:225], v[34:37]
	v_mfma_f32_16x16x32_f16 v[30:33], v[182:185], v[222:225], v[30:33]
	v_mfma_f32_16x16x32_f16 v[18:21], v[152:155], v[230:233], v[18:21]
	v_mfma_f32_16x16x32_f16 v[14:17], v[182:185], v[230:233], v[14:17]
	v_mfma_f32_16x16x32_f16 v[58:61], v[186:189], v[202:205], v[58:61]
	v_mfma_f32_16x16x32_f16 v[54:57], v[194:197], v[202:205], v[54:57]
	v_mfma_f32_16x16x32_f16 v[42:45], v[186:189], v[210:213], v[42:45]
	v_mfma_f32_16x16x32_f16 v[38:41], v[194:197], v[210:213], v[38:41]
	v_mfma_f32_16x16x32_f16 v[26:29], v[186:189], v[218:221], v[26:29]
	v_mfma_f32_16x16x32_f16 v[22:25], v[194:197], v[218:221], v[22:25]
	v_mfma_f32_16x16x32_f16 v[10:13], v[186:189], v[226:229], v[10:13]
	v_mfma_f32_16x16x32_f16 v[6:9], v[194:197], v[226:229], v[6:9]
	v_mfma_f32_16x16x32_f16 v[58:61], v[190:193], v[206:209], v[58:61]
	v_mfma_f32_16x16x32_f16 v[54:57], v[198:201], v[206:209], v[54:57]
	v_mfma_f32_16x16x32_f16 v[42:45], v[190:193], v[214:217], v[42:45]
	v_mfma_f32_16x16x32_f16 v[38:41], v[198:201], v[214:217], v[38:41]
	v_mfma_f32_16x16x32_f16 v[26:29], v[190:193], v[222:225], v[26:29]
	v_mfma_f32_16x16x32_f16 v[22:25], v[198:201], v[222:225], v[22:25]
	v_mfma_f32_16x16x32_f16 v[10:13], v[190:193], v[230:233], v[10:13]
	v_mfma_f32_16x16x32_f16 v[6:9], v[198:201], v[230:233], v[6:9]
	s_barrier
; #define STAGE(bufoff, gbase, voff) do { _Pragma("unroll") for (int _i = 0; _i < 2; ++_i) \
;     __builtin_amdgcn_global_load_lds((const unsigned*)((const char*)(gbase) + (voff)[_i]), (LAS unsigned*)(lds + (bufoff) + ldsw + _i * 8192), 16, 0, 0); } while (0)
; #define LDA(dst, b, h) do { _Pragma("unroll") for (int m = 0; m < 4; ++m) _Pragma("unroll") for (int k = 0; k < 2; ++k) dst[m][k] = *(const LAS half8*)(lds + SA(b, h) + aoff + m * 2048 + k * 1024); } while (0)
; #define LDB(dst, b, h) do { _Pragma("unroll") for (int n = 0; n < 2; ++n) _Pragma("unroll") for (int k = 0; k < 2; ++k) dst[n][k] = *(const LAS half8*)(lds + SB(b, h) + boff + n * 2048 + k * 1024); } while (0)
; #define MMA(ai, bj, At_, Bt_) do { __builtin_amdgcn_s_setprio(1); \
;     _Pragma("unroll") for (int m = 0; m < 4; ++m) _Pragma("unroll") for (int n = 0; n < 2; ++n) _Pragma("unroll") for (int k = 0; k < 2; ++k) \
;       acc[ai][bj][m][n] = MFMA16(Bt_[n][k], At_[m][k], acc[ai][bj][m][n]); \
;     __builtin_amdgcn_s_setprio(0); } while (0)
; #define WAIT_V(n) asm volatile("s_waitcnt vmcnt(" #n ")" ::: "memory")
; #define WAIT_L(n) asm volatile("s_waitcnt lgkmcnt(" #n ")" ::: "memory")
; #define BAR __builtin_amdgcn_s_barrier()
; #define SCHED __builtin_amdgcn_sched_barrier(0)
; template <int EPI>
; DI void gemm_phase(const int wid_s, const h16* __restrict__ A, const h16* __restrict__ Bt, const int N, const int K, const EpiArgs ea) {
;     ...
;       LDB(B0, 1, 0); LDB(B1, 1, 1); SCHED; LDA(At, 1, 0); STAGE(SA(0, 1), a2 + hstep, voffA);
;       WAIT_V(8); WAIT_L(0); BAR; MMA(0, 0, At, B0); MMA(0, 1, At, B1); BAR; SCHED;
;       LDA(At, 1, 1); STAGE(SB(1, 0), b3, voffB); STAGE(SB(1, 1), b3 + hstep, voffB); STAGE(SA(1, 0), a3, voffA);
	s_add_i32 s44, 0, 0x18000
	v_add_u32_e32 v177, s44, v148
	s_add_i32 s45, 0, 0x1c000
	ds_read_b128 v[144:147], v177
	ds_read_b128 v[152:155], v177 offset:1024
	ds_read_b128 v[178:181], v177 offset:2048
	ds_read_b128 v[182:185], v177 offset:3072
	v_add_u32_e32 v177, s45, v148
	ds_read_b128 v[186:189], v177
	ds_read_b128 v[190:193], v177 offset:1024
	ds_read_b128 v[194:197], v177 offset:2048
	ds_read_b128 v[198:201], v177 offset:3072
	s_add_u32 s26, s26, 0x40000
	s_addc_u32 s27, s27, 0
	v_lshl_add_u64 v[242:243], s[26:27], 0, v[2:3]
	ds_read_b128 v[202:205], v151 offset:32768
	ds_read_b128 v[206:209], v151 offset:33792
	ds_read_b128 v[210:213], v151 offset:34816
	ds_read_b128 v[214:217], v151 offset:35840
	ds_read_b128 v[218:221], v151 offset:36864
	ds_read_b128 v[222:225], v151 offset:37888
	ds_read_b128 v[226:229], v151 offset:38912
	ds_read_b128 v[230:233], v151 offset:39936
	s_mov_b32 m0, s17
	s_nop 0
	global_load_lds_dwordx4 v[238:239], off
	s_mov_b32 m0, s19
	s_nop 0
	global_load_lds_dwordx4 v[240:241], off
	s_mov_b32 m0, s31
	s_nop 0
	global_load_lds_dwordx4 v[242:243], off
	v_lshl_add_u64 v[242:243], s[26:27], 0, v[134:135]
	s_mov_b32 m0, s38
	s_nop 0
	global_load_lds_dwordx4 v[242:243], off
	s_waitcnt vmcnt(8)
	s_waitcnt lgkmcnt(0)
	s_barrier
	s_waitcnt lgkmcnt(0)
	v_mfma_f32_16x16x32_f16 v[130:133], v[144:147], v[202:205], v[130:133]
	v_mfma_f32_16x16x32_f16 v[126:129], v[178:181], v[202:205], v[126:129]
	v_mfma_f32_16x16x32_f16 v[114:117], v[144:147], v[210:213], v[114:117]
	v_mfma_f32_16x16x32_f16 v[110:113], v[178:181], v[210:213], v[110:113]
	v_mfma_f32_16x16x32_f16 v[98:101], v[144:147], v[218:221], v[98:101]
	v_mfma_f32_16x16x32_f16 v[94:97], v[178:181], v[218:221], v[94:97]
	v_mfma_f32_16x16x32_f16 v[82:85], v[144:147], v[226:229], v[82:85]
	v_mfma_f32_16x16x32_f16 v[78:81], v[178:181], v[226:229], v[78:81]
	v_mfma_f32_16x16x32_f16 v[130:133], v[152:155], v[206:209], v[130:133]
	v_mfma_f32_16x16x32_f16 v[126:129], v[182:185], v[206:209], v[126:129]
	v_mfma_f32_16x16x32_f16 v[114:117], v[152:155], v[214:217], v[114:117]
	v_mfma_f32_16x16x32_f16 v[110:113], v[182:185], v[214:217], v[110:113]
	v_mfma_f32_16x16x32_f16 v[98:101], v[152:155], v[222:225], v[98:101]
	v_mfma_f32_16x16x32_f16 v[94:97], v[182:185], v[222:225], v[94:97]
	v_mfma_f32_16x16x32_f16 v[82:85], v[152:155], v[230:233], v[82:85]
	v_mfma_f32_16x16x32_f16 v[78:81], v[182:185], v[230:233], v[78:81]
	v_mfma_f32_16x16x32_f16 v[122:125], v[186:189], v[202:205], v[122:125]
	v_mfma_f32_16x16x32_f16 v[118:121], v[194:197], v[202:205], v[118:121]
	v_mfma_f32_16x16x32_f16 v[106:109], v[186:189], v[210:213], v[106:109]
	v_mfma_f32_16x16x32_f16 v[102:105], v[194:197], v[210:213], v[102:105]
	v_mfma_f32_16x16x32_f16 v[90:93], v[186:189], v[218:221], v[90:93]
	v_mfma_f32_16x16x32_f16 v[86:89], v[194:197], v[218:221], v[86:89]
	v_mfma_f32_16x16x32_f16 v[74:77], v[186:189], v[226:229], v[74:77]
	v_mfma_f32_16x16x32_f16 v[70:73], v[194:197], v[226:229], v[70:73]
	v_mfma_f32_16x16x32_f16 v[122:125], v[190:193], v[206:209], v[122:125]
	v_mfma_f32_16x16x32_f16 v[118:121], v[198:201], v[206:209], v[118:121]
	v_mfma_f32_16x16x32_f16 v[106:109], v[190:193], v[214:217], v[106:109]
	v_mfma_f32_16x16x32_f16 v[102:105], v[198:201], v[214:217], v[102:105]
	v_mfma_f32_16x16x32_f16 v[90:93], v[190:193], v[222:225], v[90:93]
	v_mfma_f32_16x16x32_f16 v[86:89], v[198:201], v[222:225], v[86:89]
	v_mfma_f32_16x16x32_f16 v[74:77], v[190:193], v[230:233], v[74:77]
	v_mfma_f32_16x16x32_f16 v[70:73], v[198:201], v[230:233], v[70:73]
	s_barrier
; #define STAGE(bufoff, gbase, voff) do { _Pragma("unroll") for (int _i = 0; _i < 2; ++_i) \
;     __builtin_amdgcn_global_load_lds((const unsigned*)((const char*)(gbase) + (voff)[_i]), (LAS unsigned*)(lds + (bufoff) + ldsw + _i * 8192), 16, 0, 0); } while (0)
; #define LDA(dst, b, h) do { _Pragma("unroll") for (int m = 0; m < 4; ++m) _Pragma("unroll") for (int k = 0; k < 2; ++k) dst[m][k] = *(const LAS half8*)(lds + SA(b, h) + aoff + m * 2048 + k * 1024); } while (0)
; #define MMA(ai, bj, At_, Bt_) do { __builtin_amdgcn_s_setprio(1); \
;     _Pragma("unroll") for (int m = 0; m < 4; ++m) _Pragma("unroll") for (int n = 0; n < 2; ++n) _Pragma("unroll") for (int k = 0; k < 2; ++k) \
;       acc[ai][bj][m][n] = MFMA16(Bt_[n][k], At_[m][k], acc[ai][bj][m][n]); \
;     __builtin_amdgcn_s_setprio(0); } while (0)
; #define WAIT_V(n) asm volatile("s_waitcnt vmcnt(" #n ")" ::: "memory")
; #define WAIT_L(n) asm volatile("s_waitcnt lgkmcnt(" #n ")" ::: "memory")
; #define BAR __builtin_amdgcn_s_barrier()
; #define SCHED __builtin_amdgcn_sched_barrier(0)
; template <int EPI>
; DI void gemm_phase(const int wid_s, const h16* __restrict__ A, const h16* __restrict__ Bt, const int N, const int K, const EpiArgs ea) {
;     ...
;       LDA(At, 1, 1); STAGE(SB(1, 0), b3, voffB); STAGE(SB(1, 1), b3 + hstep, voffB); STAGE(SA(1, 0), a3, voffA);
;       WAIT_V(8); WAIT_L(0); BAR; MMA(1, 0, At, B0); MMA(1, 1, At, B1); BAR; SCHED;
;     }
;     if (wr == 0) BAR;
	s_add_i32 s26, s44, s30
	v_lshl_add_u64 v[234:235], v[234:235], 0, s[36:37]
	s_mov_b32 m0, s26
	ds_read_b128 v[202:205], v151 offset:49152
	ds_read_b128 v[206:209], v151 offset:50176
	ds_read_b128 v[210:213], v151 offset:51200
	ds_read_b128 v[214:217], v151 offset:52224
	ds_read_b128 v[218:221], v151 offset:53248
	ds_read_b128 v[222:225], v151 offset:54272
	ds_read_b128 v[226:229], v151 offset:55296
	ds_read_b128 v[230:233], v151 offset:56320
	global_load_lds_dwordx4 v[234:235], off
	s_add_i32 m0, s26, 0x2000
	s_add_u32 s22, s22, 0x40080
	v_lshl_add_u64 v[234:235], v[236:237], 0, s[36:37]
	s_addc_u32 s23, s23, 0
	s_add_i32 s26, s45, s30
	global_load_lds_dwordx4 v[234:235], off
	v_lshl_add_u64 v[234:235], s[22:23], 0, v[0:1]
	s_mov_b32 m0, s26
	s_nop 0
	global_load_lds_dwordx4 v[234:235], off
	v_lshl_add_u64 v[234:235], s[22:23], 0, v[138:139]
	s_add_i32 m0, s26, 0x2000
	s_nop 0
	global_load_lds_dwordx4 v[234:235], off
	v_lshl_add_u64 v[234:235], v[238:239], 0, s[36:37]
	s_mov_b32 m0, s39
	s_nop 0
	global_load_lds_dwordx4 v[234:235], off
	v_lshl_add_u64 v[234:235], v[240:241], 0, s[36:37]
	s_mov_b32 m0, s40
	s_nop 0
	global_load_lds_dwordx4 v[234:235], off
	s_waitcnt vmcnt(8)
	s_waitcnt lgkmcnt(0)
	s_barrier
	s_waitcnt lgkmcnt(0)
	v_mfma_f32_16x16x32_f16 v[66:69], v[144:147], v[202:205], v[66:69]
	v_mfma_f32_16x16x32_f16 v[62:65], v[178:181], v[202:205], v[62:65]
	v_mfma_f32_16x16x32_f16 v[50:53], v[144:147], v[210:213], v[50:53]
	v_mfma_f32_16x16x32_f16 v[46:49], v[178:181], v[210:213], v[46:49]
	v_mfma_f32_16x16x32_f16 v[34:37], v[144:147], v[218:221], v[34:37]
	v_mfma_f32_16x16x32_f16 v[30:33], v[178:181], v[218:221], v[30:33]
	v_mfma_f32_16x16x32_f16 v[18:21], v[144:147], v[226:229], v[18:21]
	v_mfma_f32_16x16x32_f16 v[14:17], v[178:181], v[226:229], v[14:17]
	v_mfma_f32_16x16x32_f16 v[66:69], v[152:155], v[206:209], v[66:69]
	v_mfma_f32_16x16x32_f16 v[62:65], v[182:185], v[206:209], v[62:65]
	v_mfma_f32_16x16x32_f16 v[50:53], v[152:155], v[214:217], v[50:53]
	v_mfma_f32_16x16x32_f16 v[46:49], v[182:185], v[214:217], v[46:49]
	v_mfma_f32_16x16x32_f16 v[34:37], v[152:155], v[222:225], v[34:37]
	v_mfma_f32_16x16x32_f16 v[30:33], v[182:185], v[222:225], v[30:33]
	v_mfma_f32_16x16x32_f16 v[18:21], v[152:155], v[230:233], v[18:21]
	v_mfma_f32_16x16x32_f16 v[14:17], v[182:185], v[230:233], v[14:17]
	v_mfma_f32_16x16x32_f16 v[58:61], v[186:189], v[202:205], v[58:61]
	v_mfma_f32_16x16x32_f16 v[54:57], v[194:197], v[202:205], v[54:57]
	v_mfma_f32_16x16x32_f16 v[42:45], v[186:189], v[210:213], v[42:45]
	v_mfma_f32_16x16x32_f16 v[38:41], v[194:197], v[210:213], v[38:41]
	v_mfma_f32_16x16x32_f16 v[26:29], v[186:189], v[218:221], v[26:29]
	v_mfma_f32_16x16x32_f16 v[22:25], v[194:197], v[218:221], v[22:25]
	v_mfma_f32_16x16x32_f16 v[10:13], v[186:189], v[226:229], v[10:13]
	v_mfma_f32_16x16x32_f16 v[6:9], v[194:197], v[226:229], v[6:9]
	v_mfma_f32_16x16x32_f16 v[58:61], v[190:193], v[206:209], v[58:61]
	v_mfma_f32_16x16x32_f16 v[54:57], v[198:201], v[206:209], v[54:57]
	v_mfma_f32_16x16x32_f16 v[42:45], v[190:193], v[214:217], v[42:45]
	v_mfma_f32_16x16x32_f16 v[38:41], v[198:201], v[214:217], v[38:41]
	v_mfma_f32_16x16x32_f16 v[26:29], v[190:193], v[222:225], v[26:29]
	v_mfma_f32_16x16x32_f16 v[22:25], v[198:201], v[222:225], v[22:25]
	v_mfma_f32_16x16x32_f16 v[10:13], v[190:193], v[230:233], v[10:13]
	v_mfma_f32_16x16x32_f16 v[6:9], v[198:201], v[230:233], v[6:9]
	s_barrier
	s_add_i32 s43, s43, 2
	s_add_u32 s41, s41, 0x100
	s_addc_u32 s42, s42, 0
	s_add_u32 s20, s20, 0x100
	s_addc_u32 s21, s21, 0
	s_cmp_gt_u32 s43, 13
	s_cbranch_scc0 .LBB0_175
	s_and_b64 vcc, exec, s[4:5]
	s_cbranch_vccz .LBB0_178
	s_barrier

; #define STAGE(bufoff, gbase, voff) do { _Pragma("unroll") for (int _i = 0; _i < 2; ++_i) \
;     __builtin_amdgcn_global_load_lds((const unsigned*)((const char*)(gbase) + (voff)[_i]), (LAS unsigned*)(lds + (bufoff) + ldsw + _i * 8192), 16, 0, 0); } while (0)
; #define LDA(dst, b, h) do { _Pragma("unroll") for (int m = 0; m < 4; ++m) _Pragma("unroll") for (int k = 0; k < 2; ++k) dst[m][k] = *(const LAS half8*)(lds + SA(b, h) + aoff + m * 2048 + k * 1024); } while (0)
; #define LDB(dst, b, h) do { _Pragma("unroll") for (int n = 0; n < 2; ++n) _Pragma("unroll") for (int k = 0; k < 2; ++k) dst[n][k] = *(const LAS half8*)(lds + SB(b, h) + boff + n * 2048 + k * 1024); } while (0)
; #define MMA(ai, bj, At_, Bt_) do { __builtin_amdgcn_s_setprio(1); \
;     _Pragma("unroll") for (int m = 0; m < 4; ++m) _Pragma("unroll") for (int n = 0; n < 2; ++n) _Pragma("unroll") for (int k = 0; k < 2; ++k) \
;       acc[ai][bj][m][n] = MFMA16(Bt_[n][k], At_[m][k], acc[ai][bj][m][n]); \
;     __builtin_amdgcn_s_setprio(0); } while (0)
; #define WAIT_V(n) asm volatile("s_waitcnt vmcnt(" #n ")" ::: "memory")
; #define WAIT_L(n) asm volatile("s_waitcnt lgkmcnt(" #n ")" ::: "memory")
; #define BAR __builtin_amdgcn_s_barrier()
; template <int EPI>
; DI void gemm_phase(const int wid_s, const h16* __restrict__ A, const h16* __restrict__ Bt, const int N, const int K, const EpiArgs ea) {
;     ...
;     const int Ln = L + (int)gridDim.x;
;     const bool has_next = Ln < nwg;
;     int nbrow = brow, nbcol = bcol;
;     if (has_next) TILE_RC(Ln, nbrow, nbcol);
;     const char* nA = (const char*)A + (size_t)nbrow * K * 2;
;     const char* nB = (const char*)Bt + (size_t)nbcol * K * 2;
;     for (int t = 0; t < nt; t += 2) {
;       const bool last = (t == nt - 2);
;       const char* a1 = cA + (size_t)(t + 1) * kstep;
;       const char* a2 = last ? nA : cA + (size_t)(t + 2) * kstep; const char* b2 = last ? nB : cB + (size_t)(t + 2) * kstep;
;       const char* a3 = a2 + kstep; const char* b3 = b2 + kstep;
;       LDB(B0, 0, 0); LDB(B1, 0, 1); SCHED; LDA(At, 0, 0); STAGE(SA(1, 1), a1 + hstep, voffA);
;       WAIT_V(8); WAIT_L(0); BAR; MMA(0, 0, At, B0); MMA(0, 1, At, B1); BAR; SCHED;
;       LDA(At, 0, 1); STAGE(SB(0, 0), b2, voffB); STAGE(SB(0, 1), b2 + hstep, voffB); STAGE(SA(0, 0), a2, voffA);
;       WAIT_V(8); WAIT_L(0); BAR; MMA(1, 0, At, B0); MMA(1, 1, At, B1); BAR; SCHED;
.LBB0_385:
	s_ashr_i32 s9, s8, 31
	s_lshl_b64 s[16:17], s[8:9], 11
	s_add_u32 s9, s92, s16
	s_addc_u32 s41, s93, s17
	s_ashr_i32 s11, s10, 31
	s_lshl_b64 s[18:19], s[10:11], 11
	v_readlane_b32 s11, v249, 29
	s_add_u32 s11, s11, s18
	v_readlane_b32 s26, v249, 31
	s_addc_u32 s42, s26, s19
	v_readlane_b32 s26, v249, 30
	s_add_u32 s43, s26, s22
	v_readlane_b32 s22, v249, 32
	s_addc_u32 s44, s22, s23
	s_add_u32 s45, s86, s20
	v_mov_b32_e32 v6, 0
	v_lshl_add_u64 v[144:145], v[140:141], 0, s[20:21]
	v_lshl_add_u64 v[146:147], v[142:143], 0, s[20:21]
	s_addc_u32 s46, s87, s21
	s_mov_b32 s47, -2
	s_mov_b64 s[20:21], 0
	s_add_u32 s22, s45, s20
	s_addc_u32 s23, s46, s21
	s_add_u32 s22, s22, 0x520e100
	s_addc_u32 s23, s23, 0
	s_add_u32 s48, s43, s20
	s_addc_u32 s49, s44, s21
	s_add_i32 s50, 0, 0x10000
	s_cmpk_eq_i32 s20, 0x700
	s_cselect_b32 s27, s41, s23
	s_cselect_b32 s26, s9, s22
	v_add_u32_e32 v177, s50, v148
	s_cselect_b32 s23, s42, s49
	s_cselect_b32 s22, s11, s48
	s_add_i32 s51, 0, 0x14000
	ds_read_b128 v[152:155], v177
	ds_read_b128 v[178:181], v177 offset:1024
	ds_read_b128 v[182:185], v177 offset:2048
	ds_read_b128 v[186:189], v177 offset:3072
	v_add_u32_e32 v177, s51, v148
	ds_read_b128 v[190:193], v177
	ds_read_b128 v[194:197], v177 offset:1024
	ds_read_b128 v[198:201], v177 offset:2048
	ds_read_b128 v[202:205], v177 offset:3072
	v_lshl_add_u64 v[238:239], v[146:147], 0, s[20:21]
	s_add_i32 m0, s13, 0xc000
	ds_read_b128 v[206:209], v151
	ds_read_b128 v[210:213], v151 offset:1024
	ds_read_b128 v[214:217], v151 offset:2048
	ds_read_b128 v[218:221], v151 offset:3072
	ds_read_b128 v[222:225], v151 offset:4096
	ds_read_b128 v[226:229], v151 offset:5120
	ds_read_b128 v[230:233], v151 offset:6144
	ds_read_b128 v[234:237], v151 offset:7168
	global_load_lds_dwordx4 v[238:239], off
	v_lshl_add_u64 v[238:239], v[144:145], 0, s[20:21]
	s_add_i32 m0, s13, 0xe000
	s_nop 0
	global_load_lds_dwordx4 v[238:239], off
	s_waitcnt vmcnt(8)
	s_waitcnt lgkmcnt(0)
	s_barrier
	s_waitcnt lgkmcnt(0)
	v_mfma_f32_16x16x32_f16 v[130:133], v[152:155], v[206:209], 0
	v_mfma_f32_16x16x32_f16 v[126:129], v[182:185], v[206:209], 0
	v_mfma_f32_16x16x32_f16 v[122:125], v[152:155], v[214:217], 0
	v_mfma_f32_16x16x32_f16 v[118:121], v[182:185], v[214:217], 0
	v_mfma_f32_16x16x32_f16 v[106:109], v[152:155], v[222:225], 0
	v_mfma_f32_16x16x32_f16 v[102:105], v[182:185], v[222:225], 0
	v_mfma_f32_16x16x32_f16 v[90:93], v[152:155], v[230:233], 0
	v_mfma_f32_16x16x32_f16 v[86:89], v[182:185], v[230:233], 0
	v_mfma_f32_16x16x32_f16 v[130:133], v[178:181], v[210:213], v[130:133]
	v_mfma_f32_16x16x32_f16 v[126:129], v[186:189], v[210:213], v[126:129]
	v_mfma_f32_16x16x32_f16 v[122:125], v[178:181], v[218:221], v[122:125]
	v_mfma_f32_16x16x32_f16 v[118:121], v[186:189], v[218:221], v[118:121]
	v_mfma_f32_16x16x32_f16 v[106:109], v[178:181], v[226:229], v[106:109]
	v_mfma_f32_16x16x32_f16 v[102:105], v[186:189], v[226:229], v[102:105]
	v_mfma_f32_16x16x32_f16 v[90:93], v[178:181], v[234:237], v[90:93]
	v_mfma_f32_16x16x32_f16 v[86:89], v[186:189], v[234:237], v[86:89]
	v_mfma_f32_16x16x32_f16 v[114:117], v[190:193], v[206:209], 0
	v_mfma_f32_16x16x32_f16 v[110:113], v[198:201], v[206:209], 0
	v_mfma_f32_16x16x32_f16 v[98:101], v[190:193], v[214:217], 0
	v_mfma_f32_16x16x32_f16 v[94:97], v[198:201], v[214:217], 0
	v_mfma_f32_16x16x32_f16 v[82:85], v[190:193], v[222:225], 0
	v_mfma_f32_16x16x32_f16 v[78:81], v[198:201], v[222:225], 0
	v_mfma_f32_16x16x32_f16 v[74:77], v[190:193], v[230:233], 0
	v_mfma_f32_16x16x32_f16 v[70:73], v[198:201], v[230:233], 0
	v_mfma_f32_16x16x32_f16 v[114:117], v[194:197], v[210:213], v[114:117]
	v_mfma_f32_16x16x32_f16 v[110:113], v[202:205], v[210:213], v[110:113]
	v_mfma_f32_16x16x32_f16 v[98:101], v[194:197], v[218:221], v[98:101]
	v_mfma_f32_16x16x32_f16 v[94:97], v[202:205], v[218:221], v[94:97]
	v_mfma_f32_16x16x32_f16 v[82:85], v[194:197], v[226:229], v[82:85]
	v_mfma_f32_16x16x32_f16 v[78:81], v[202:205], v[226:229], v[78:81]
	v_mfma_f32_16x16x32_f16 v[74:77], v[194:197], v[234:237], v[74:77]
	v_mfma_f32_16x16x32_f16 v[70:73], v[202:205], v[234:237], v[70:73]
	s_barrier
	s_add_i32 s48, s50, s30
	v_lshl_add_u64 v[238:239], s[22:23], 0, v[0:1]
	s_mov_b32 m0, s48
	ds_read_b128 v[206:209], v151 offset:16384
	ds_read_b128 v[210:213], v151 offset:17408
	ds_read_b128 v[214:217], v151 offset:18432
	ds_read_b128 v[218:221], v151 offset:19456
	ds_read_b128 v[222:225], v151 offset:20480
	ds_read_b128 v[226:229], v151 offset:21504
	ds_read_b128 v[230:233], v151 offset:22528
	ds_read_b128 v[234:237], v151 offset:23552
	global_load_lds_dwordx4 v[238:239], off
	s_add_i32 m0, s48, 0x2000
	s_add_u32 s48, s22, 0x40000
	v_lshl_add_u64 v[240:241], s[22:23], 0, v[2:3]
	s_addc_u32 s49, s23, 0
	s_add_i32 s50, s51, s30
	global_load_lds_dwordx4 v[240:241], off
	v_lshl_add_u64 v[242:243], s[48:49], 0, v[0:1]
	s_mov_b32 m0, s50
	v_lshl_add_u64 v[244:245], s[26:27], 0, v[134:135]
	global_load_lds_dwordx4 v[242:243], off
	v_lshl_add_u64 v[242:243], s[48:49], 0, v[2:3]
	s_add_i32 m0, s50, 0x2000
	s_nop 0
	global_load_lds_dwordx4 v[242:243], off
	v_lshl_add_u64 v[242:243], s[26:27], 0, v[138:139]
	s_waitcnt vmcnt(6)
	s_waitcnt lgkmcnt(0)
	s_barrier
; #define STAGE(bufoff, gbase, voff) do { _Pragma("unroll") for (int _i = 0; _i < 2; ++_i) \
;     __builtin_amdgcn_global_load_lds((const unsigned*)((const char*)(gbase) + (voff)[_i]), (LAS unsigned*)(lds + (bufoff) + ldsw + _i * 8192), 16, 0, 0); } while (0)
; #define LDA(dst, b, h) do { _Pragma("unroll") for (int m = 0; m < 4; ++m) _Pragma("unroll") for (int k = 0; k < 2; ++k) dst[m][k] = *(const LAS half8*)(lds + SA(b, h) + aoff + m * 2048 + k * 1024); } while (0)
; #define LDB(dst, b, h) do { _Pragma("unroll") for (int n = 0; n < 2; ++n) _Pragma("unroll") for (int k = 0; k < 2; ++k) dst[n][k] = *(const LAS half8*)(lds + SB(b, h) + boff + n * 2048 + k * 1024); } while (0)
; #define MMA(ai, bj, At_, Bt_) do { __builtin_amdgcn_s_setprio(1); \
;     _Pragma("unroll") for (int m = 0; m < 4; ++m) _Pragma("unroll") for (int n = 0; n < 2; ++n) _Pragma("unroll") for (int k = 0; k < 2; ++k) \
;       acc[ai][bj][m][n] = MFMA16(Bt_[n][k], At_[m][k], acc[ai][bj][m][n]); \
;     __builtin_amdgcn_s_setprio(0); } while (0)
; #define WAIT_V(n) asm volatile("s_waitcnt vmcnt(" #n ")" ::: "memory")
; #define WAIT_L(n) asm volatile("s_waitcnt lgkmcnt(" #n ")" ::: "memory")
; #define BAR __builtin_amdgcn_s_barrier()
; #define SCHED __builtin_amdgcn_sched_barrier(0)
; template <int EPI>
; DI void gemm_phase(const int wid_s, const h16* __restrict__ A, const h16* __restrict__ Bt, const int N, const int K, const EpiArgs ea) {
;     ...
;       WAIT_V(8); WAIT_L(0); BAR; MMA(1, 0, At, B0); MMA(1, 1, At, B1); BAR; SCHED;
;       LDB(B0, 1, 0); LDB(B1, 1, 1); SCHED; LDA(At, 1, 0); STAGE(SA(0, 1), a2 + hstep, voffA);
;       WAIT_V(8); WAIT_L(0); BAR; MMA(0, 0, At, B0); MMA(0, 1, At, B1); BAR; SCHED;
;       LDA(At, 1, 1); STAGE(SB(1, 0), b3, voffB); STAGE(SB(1, 1), b3 + hstep, voffB); STAGE(SA(1, 0), a3, voffA);
	s_waitcnt lgkmcnt(0)
	v_mfma_f32_16x16x32_f16 v[66:69], v[152:155], v[206:209], 0
	v_mfma_f32_16x16x32_f16 v[62:65], v[182:185], v[206:209], 0
	v_mfma_f32_16x16x32_f16 v[58:61], v[152:155], v[214:217], 0
	v_mfma_f32_16x16x32_f16 v[54:57], v[182:185], v[214:217], 0
	v_mfma_f32_16x16x32_f16 v[42:45], v[152:155], v[222:225], 0
	v_mfma_f32_16x16x32_f16 v[38:41], v[182:185], v[222:225], 0
	v_mfma_f32_16x16x32_f16 v[26:29], v[152:155], v[230:233], 0
	v_mfma_f32_16x16x32_f16 v[22:25], v[182:185], v[230:233], 0
	v_mfma_f32_16x16x32_f16 v[66:69], v[178:181], v[210:213], v[66:69]
	v_mfma_f32_16x16x32_f16 v[62:65], v[186:189], v[210:213], v[62:65]
	v_mfma_f32_16x16x32_f16 v[58:61], v[178:181], v[218:221], v[58:61]
	v_mfma_f32_16x16x32_f16 v[54:57], v[186:189], v[218:221], v[54:57]
	v_mfma_f32_16x16x32_f16 v[42:45], v[178:181], v[226:229], v[42:45]
	v_mfma_f32_16x16x32_f16 v[38:41], v[186:189], v[226:229], v[38:41]
	v_mfma_f32_16x16x32_f16 v[26:29], v[178:181], v[234:237], v[26:29]
	v_mfma_f32_16x16x32_f16 v[22:25], v[186:189], v[234:237], v[22:25]
	v_mfma_f32_16x16x32_f16 v[50:53], v[190:193], v[206:209], 0
	v_mfma_f32_16x16x32_f16 v[46:49], v[198:201], v[206:209], 0
	v_mfma_f32_16x16x32_f16 v[34:37], v[190:193], v[214:217], 0
	v_mfma_f32_16x16x32_f16 v[30:33], v[198:201], v[214:217], 0
	v_mfma_f32_16x16x32_f16 v[18:21], v[190:193], v[222:225], 0
	v_mfma_f32_16x16x32_f16 v[14:17], v[198:201], v[222:225], 0
	v_mfma_f32_16x16x32_f16 v[10:13], v[190:193], v[230:233], 0
	v_mfma_f32_16x16x32_f16 v[6:9], v[198:201], v[230:233], 0
	v_mfma_f32_16x16x32_f16 v[50:53], v[194:197], v[210:213], v[50:53]
	v_mfma_f32_16x16x32_f16 v[46:49], v[202:205], v[210:213], v[46:49]
	v_mfma_f32_16x16x32_f16 v[34:37], v[194:197], v[218:221], v[34:37]
	v_mfma_f32_16x16x32_f16 v[30:33], v[202:205], v[218:221], v[30:33]
	v_mfma_f32_16x16x32_f16 v[18:21], v[194:197], v[226:229], v[18:21]
	v_mfma_f32_16x16x32_f16 v[14:17], v[202:205], v[226:229], v[14:17]
	v_mfma_f32_16x16x32_f16 v[10:13], v[194:197], v[234:237], v[10:13]
	v_mfma_f32_16x16x32_f16 v[6:9], v[202:205], v[234:237], v[6:9]
	s_barrier
	s_add_i32 s48, 0, 0x18000
	v_add_u32_e32 v177, s48, v148
	s_add_i32 s49, 0, 0x1c000
	ds_read_b128 v[152:155], v177
	ds_read_b128 v[178:181], v177 offset:1024
	ds_read_b128 v[182:185], v177 offset:2048
	ds_read_b128 v[186:189], v177 offset:3072
	v_add_u32_e32 v177, s49, v148
	ds_read_b128 v[190:193], v177
	ds_read_b128 v[194:197], v177 offset:1024
	ds_read_b128 v[198:201], v177 offset:2048
	ds_read_b128 v[202:205], v177 offset:3072
	s_add_u32 s26, s26, 0x40000
	s_addc_u32 s27, s27, 0
	v_lshl_add_u64 v[246:247], s[26:27], 0, v[138:139]
	ds_read_b128 v[206:209], v151 offset:32768
	ds_read_b128 v[210:213], v151 offset:33792
	ds_read_b128 v[214:217], v151 offset:34816
	ds_read_b128 v[218:221], v151 offset:35840
	ds_read_b128 v[222:225], v151 offset:36864
	ds_read_b128 v[226:229], v151 offset:37888
	ds_read_b128 v[230:233], v151 offset:38912
	ds_read_b128 v[234:237], v151 offset:39936
	s_mov_b32 m0, s13
	s_nop 0
	global_load_lds_dwordx4 v[242:243], off
	s_mov_b32 m0, s15
	s_nop 0
	global_load_lds_dwordx4 v[244:245], off
	s_mov_b32 m0, s31
	s_nop 0
	global_load_lds_dwordx4 v[246:247], off
	v_lshl_add_u64 v[246:247], s[26:27], 0, v[134:135]
	s_mov_b32 m0, s38
	s_nop 0
	global_load_lds_dwordx4 v[246:247], off
	s_waitcnt vmcnt(8)
	s_waitcnt lgkmcnt(0)
	s_barrier
	s_waitcnt lgkmcnt(0)
	v_mfma_f32_16x16x32_f16 v[130:133], v[152:155], v[206:209], v[130:133]
	v_mfma_f32_16x16x32_f16 v[126:129], v[182:185], v[206:209], v[126:129]
	v_mfma_f32_16x16x32_f16 v[122:125], v[152:155], v[214:217], v[122:125]
	v_mfma_f32_16x16x32_f16 v[118:121], v[182:185], v[214:217], v[118:121]
	v_mfma_f32_16x16x32_f16 v[106:109], v[152:155], v[222:225], v[106:109]
	v_mfma_f32_16x16x32_f16 v[102:105], v[182:185], v[222:225], v[102:105]
	v_mfma_f32_16x16x32_f16 v[90:93], v[152:155], v[230:233], v[90:93]
	v_mfma_f32_16x16x32_f16 v[86:89], v[182:185], v[230:233], v[86:89]
	v_mfma_f32_16x16x32_f16 v[130:133], v[178:181], v[210:213], v[130:133]
	v_mfma_f32_16x16x32_f16 v[126:129], v[186:189], v[210:213], v[126:129]
	v_mfma_f32_16x16x32_f16 v[122:125], v[178:181], v[218:221], v[122:125]
	v_mfma_f32_16x16x32_f16 v[118:121], v[186:189], v[218:221], v[118:121]
	v_mfma_f32_16x16x32_f16 v[106:109], v[178:181], v[226:229], v[106:109]
	v_mfma_f32_16x16x32_f16 v[102:105], v[186:189], v[226:229], v[102:105]
	v_mfma_f32_16x16x32_f16 v[90:93], v[178:181], v[234:237], v[90:93]
	v_mfma_f32_16x16x32_f16 v[86:89], v[186:189], v[234:237], v[86:89]
	v_mfma_f32_16x16x32_f16 v[114:117], v[190:193], v[206:209], v[114:117]
	v_mfma_f32_16x16x32_f16 v[110:113], v[198:201], v[206:209], v[110:113]
	v_mfma_f32_16x16x32_f16 v[98:101], v[190:193], v[214:217], v[98:101]
	v_mfma_f32_16x16x32_f16 v[94:97], v[198:201], v[214:217], v[94:97]
	v_mfma_f32_16x16x32_f16 v[82:85], v[190:193], v[222:225], v[82:85]
	v_mfma_f32_16x16x32_f16 v[78:81], v[198:201], v[222:225], v[78:81]
	v_mfma_f32_16x16x32_f16 v[74:77], v[190:193], v[230:233], v[74:77]
	v_mfma_f32_16x16x32_f16 v[70:73], v[198:201], v[230:233], v[70:73]
	v_mfma_f32_16x16x32_f16 v[114:117], v[194:197], v[210:213], v[114:117]
	v_mfma_f32_16x16x32_f16 v[110:113], v[202:205], v[210:213], v[110:113]
	v_mfma_f32_16x16x32_f16 v[98:101], v[194:197], v[218:221], v[98:101]
	v_mfma_f32_16x16x32_f16 v[94:97], v[202:205], v[218:221], v[94:97]
	v_mfma_f32_16x16x32_f16 v[82:85], v[194:197], v[226:229], v[82:85]
	v_mfma_f32_16x16x32_f16 v[78:81], v[202:205], v[226:229], v[78:81]
	v_mfma_f32_16x16x32_f16 v[74:77], v[194:197], v[234:237], v[74:77]
	v_mfma_f32_16x16x32_f16 v[70:73], v[202:205], v[234:237], v[70:73]
	s_barrier
; #define STAGE(bufoff, gbase, voff) do { _Pragma("unroll") for (int _i = 0; _i < 2; ++_i) \
;     __builtin_amdgcn_global_load_lds((const unsigned*)((const char*)(gbase) + (voff)[_i]), (LAS unsigned*)(lds + (bufoff) + ldsw + _i * 8192), 16, 0, 0); } while (0)
; #define LDA(dst, b, h) do { _Pragma("unroll") for (int m = 0; m < 4; ++m) _Pragma("unroll") for (int k = 0; k < 2; ++k) dst[m][k] = *(const LAS half8*)(lds + SA(b, h) + aoff + m * 2048 + k * 1024); } while (0)
; #define LDB(dst, b, h) do { _Pragma("unroll") for (int n = 0; n < 2; ++n) _Pragma("unroll") for (int k = 0; k < 2; ++k) dst[n][k] = *(const LAS half8*)(lds + SB(b, h) + boff + n * 2048 + k * 1024); } while (0)
; #define MMA(ai, bj, At_, Bt_) do { __builtin_amdgcn_s_setprio(1); \
;     _Pragma("unroll") for (int m = 0; m < 4; ++m) _Pragma("unroll") for (int n = 0; n < 2; ++n) _Pragma("unroll") for (int k = 0; k < 2; ++k) \
;       acc[ai][bj][m][n] = MFMA16(Bt_[n][k], At_[m][k], acc[ai][bj][m][n]); \
;     __builtin_amdgcn_s_setprio(0); } while (0)
; #define WAIT_V(n) asm volatile("s_waitcnt vmcnt(" #n ")" ::: "memory")
; #define WAIT_L(n) asm volatile("s_waitcnt lgkmcnt(" #n ")" ::: "memory")
; #define BAR __builtin_amdgcn_s_barrier()
; #define SCHED __builtin_amdgcn_sched_barrier(0)
; template <int EPI>
; DI void gemm_phase(const int wid_s, const h16* __restrict__ A, const h16* __restrict__ Bt, const int N, const int K, const EpiArgs ea) {
;     ...
;     for (int t = 0; t < nt; t += 2) {
;       const bool last = (t == nt - 2);
;       const char* a1 = cA + (size_t)(t + 1) * kstep;
;       const char* a2 = last ? nA : cA + (size_t)(t + 2) * kstep; const char* b2 = last ? nB : cB + (size_t)(t + 2) * kstep;
;       const char* a3 = a2 + kstep; const char* b3 = b2 + kstep;
;       LDB(B0, 0, 0); LDB(B1, 0, 1); SCHED; LDA(At, 0, 0); STAGE(SA(1, 1), a1 + hstep, voffA);
;     ...
;       LDA(At, 1, 1); STAGE(SB(1, 0), b3, voffB); STAGE(SB(1, 1), b3 + hstep, voffB); STAGE(SA(1, 0), a3, voffA);
;       WAIT_V(8); WAIT_L(0); BAR; MMA(1, 0, At, B0); MMA(1, 1, At, B1); BAR; SCHED;
	s_add_i32 s26, s48, s30
	v_lshl_add_u64 v[238:239], v[238:239], 0, s[36:37]
	s_mov_b32 m0, s26
	ds_read_b128 v[206:209], v151 offset:49152
	ds_read_b128 v[210:213], v151 offset:50176
	ds_read_b128 v[214:217], v151 offset:51200
	ds_read_b128 v[218:221], v151 offset:52224
	ds_read_b128 v[222:225], v151 offset:53248
	ds_read_b128 v[226:229], v151 offset:54272
	ds_read_b128 v[230:233], v151 offset:55296
	ds_read_b128 v[234:237], v151 offset:56320
	global_load_lds_dwordx4 v[238:239], off
	s_add_i32 m0, s26, 0x2000
	s_add_u32 s22, s22, 0x40080
	v_lshl_add_u64 v[238:239], v[240:241], 0, s[36:37]
	s_addc_u32 s23, s23, 0
	s_add_i32 s26, s49, s30
	global_load_lds_dwordx4 v[238:239], off
	v_lshl_add_u64 v[238:239], s[22:23], 0, v[0:1]
	s_mov_b32 m0, s26
	s_nop 0
	global_load_lds_dwordx4 v[238:239], off
	v_lshl_add_u64 v[238:239], s[22:23], 0, v[2:3]
	s_add_i32 m0, s26, 0x2000
	s_nop 0
	global_load_lds_dwordx4 v[238:239], off
	v_lshl_add_u64 v[238:239], v[242:243], 0, s[36:37]
	s_mov_b32 m0, s39
	s_nop 0
	global_load_lds_dwordx4 v[238:239], off
	v_lshl_add_u64 v[238:239], v[244:245], 0, s[36:37]
	s_mov_b32 m0, s40
	s_nop 0
	global_load_lds_dwordx4 v[238:239], off
	s_waitcnt vmcnt(8)
	s_waitcnt lgkmcnt(0)
	s_barrier
	s_waitcnt lgkmcnt(0)
	v_mfma_f32_16x16x32_f16 v[66:69], v[152:155], v[206:209], v[66:69]
	v_mfma_f32_16x16x32_f16 v[62:65], v[182:185], v[206:209], v[62:65]
	v_mfma_f32_16x16x32_f16 v[58:61], v[152:155], v[214:217], v[58:61]
	v_mfma_f32_16x16x32_f16 v[54:57], v[182:185], v[214:217], v[54:57]
	v_mfma_f32_16x16x32_f16 v[42:45], v[152:155], v[222:225], v[42:45]
	v_mfma_f32_16x16x32_f16 v[38:41], v[182:185], v[222:225], v[38:41]
	v_mfma_f32_16x16x32_f16 v[26:29], v[152:155], v[230:233], v[26:29]
	v_mfma_f32_16x16x32_f16 v[22:25], v[182:185], v[230:233], v[22:25]
	v_mfma_f32_16x16x32_f16 v[66:69], v[178:181], v[210:213], v[66:69]
	v_mfma_f32_16x16x32_f16 v[62:65], v[186:189], v[210:213], v[62:65]
	v_mfma_f32_16x16x32_f16 v[58:61], v[178:181], v[218:221], v[58:61]
	v_mfma_f32_16x16x32_f16 v[54:57], v[186:189], v[218:221], v[54:57]
	v_mfma_f32_16x16x32_f16 v[42:45], v[178:181], v[226:229], v[42:45]
	v_mfma_f32_16x16x32_f16 v[38:41], v[186:189], v[226:229], v[38:41]
	v_mfma_f32_16x16x32_f16 v[26:29], v[178:181], v[234:237], v[26:29]
	v_mfma_f32_16x16x32_f16 v[22:25], v[186:189], v[234:237], v[22:25]
	v_mfma_f32_16x16x32_f16 v[50:53], v[190:193], v[206:209], v[50:53]
	v_mfma_f32_16x16x32_f16 v[46:49], v[198:201], v[206:209], v[46:49]
	v_mfma_f32_16x16x32_f16 v[34:37], v[190:193], v[214:217], v[34:37]
	v_mfma_f32_16x16x32_f16 v[30:33], v[198:201], v[214:217], v[30:33]
	v_mfma_f32_16x16x32_f16 v[18:21], v[190:193], v[222:225], v[18:21]
	v_mfma_f32_16x16x32_f16 v[14:17], v[198:201], v[222:225], v[14:17]
	v_mfma_f32_16x16x32_f16 v[10:13], v[190:193], v[230:233], v[10:13]
	v_mfma_f32_16x16x32_f16 v[6:9], v[198:201], v[230:233], v[6:9]
	v_mfma_f32_16x16x32_f16 v[50:53], v[194:197], v[210:213], v[50:53]
	v_mfma_f32_16x16x32_f16 v[46:49], v[202:205], v[210:213], v[46:49]
	v_mfma_f32_16x16x32_f16 v[34:37], v[194:197], v[218:221], v[34:37]
	v_mfma_f32_16x16x32_f16 v[30:33], v[202:205], v[218:221], v[30:33]
	v_mfma_f32_16x16x32_f16 v[18:21], v[194:197], v[226:229], v[18:21]
	v_mfma_f32_16x16x32_f16 v[14:17], v[202:205], v[226:229], v[14:17]
	v_mfma_f32_16x16x32_f16 v[10:13], v[194:197], v[234:237], v[10:13]
	v_mfma_f32_16x16x32_f16 v[6:9], v[202:205], v[234:237], v[6:9]
	s_barrier
	s_add_i32 s47, s47, 2
	s_add_u32 s20, s20, 0x100
	s_addc_u32 s21, s21, 0
	s_cmp_gt_u32 s47, 13
.LBB0_386:
	s_add_u32 s22, s45, s20
	s_addc_u32 s23, s46, s21
	s_add_u32 s22, s22, 0x520e100
	s_addc_u32 s23, s23, 0
	s_add_u32 s48, s43, s20
	s_addc_u32 s49, s44, s21
	s_add_i32 s50, 0, 0x10000
	s_cmpk_eq_i32 s20, 0x700
	s_cselect_b32 s27, s41, s23
	s_cselect_b32 s26, s9, s22
	v_add_u32_e32 v177, s50, v148
	s_cselect_b32 s23, s42, s49
	s_cselect_b32 s22, s11, s48
	s_add_i32 s51, 0, 0x14000
	ds_read_b128 v[152:155], v177
	ds_read_b128 v[178:181], v177 offset:1024
	ds_read_b128 v[182:185], v177 offset:2048
	ds_read_b128 v[186:189], v177 offset:3072
	v_add_u32_e32 v177, s51, v148
	ds_read_b128 v[190:193], v177
	ds_read_b128 v[194:197], v177 offset:1024
	ds_read_b128 v[198:201], v177 offset:2048
	ds_read_b128 v[202:205], v177 offset:3072
	v_lshl_add_u64 v[238:239], v[146:147], 0, s[20:21]
	s_add_i32 m0, s13, 0xc000
	ds_read_b128 v[206:209], v151
	ds_read_b128 v[210:213], v151 offset:1024
	ds_read_b128 v[214:217], v151 offset:2048
	ds_read_b128 v[218:221], v151 offset:3072
	ds_read_b128 v[222:225], v151 offset:4096
	ds_read_b128 v[226:229], v151 offset:5120
	ds_read_b128 v[230:233], v151 offset:6144
	ds_read_b128 v[234:237], v151 offset:7168
	global_load_lds_dwordx4 v[238:239], off
	v_lshl_add_u64 v[238:239], v[144:145], 0, s[20:21]
	s_add_i32 m0, s13, 0xe000
	s_nop 0
	global_load_lds_dwordx4 v[238:239], off
	s_waitcnt vmcnt(8)
	s_waitcnt lgkmcnt(0)
	s_barrier
; #define STAGE(bufoff, gbase, voff) do { _Pragma("unroll") for (int _i = 0; _i < 2; ++_i) \
;     __builtin_amdgcn_global_load_lds((const unsigned*)((const char*)(gbase) + (voff)[_i]), (LAS unsigned*)(lds + (bufoff) + ldsw + _i * 8192), 16, 0, 0); } while (0)
; #define LDA(dst, b, h) do { _Pragma("unroll") for (int m = 0; m < 4; ++m) _Pragma("unroll") for (int k = 0; k < 2; ++k) dst[m][k] = *(const LAS half8*)(lds + SA(b, h) + aoff + m * 2048 + k * 1024); } while (0)
; #define LDB(dst, b, h) do { _Pragma("unroll") for (int n = 0; n < 2; ++n) _Pragma("unroll") for (int k = 0; k < 2; ++k) dst[n][k] = *(const LAS half8*)(lds + SB(b, h) + boff + n * 2048 + k * 1024); } while (0)
; #define MMA(ai, bj, At_, Bt_) do { __builtin_amdgcn_s_setprio(1); \
;     _Pragma("unroll") for (int m = 0; m < 4; ++m) _Pragma("unroll") for (int n = 0; n < 2; ++n) _Pragma("unroll") for (int k = 0; k < 2; ++k) \
;       acc[ai][bj][m][n] = MFMA16(Bt_[n][k], At_[m][k], acc[ai][bj][m][n]); \
;     __builtin_amdgcn_s_setprio(0); } while (0)
; #define WAIT_V(n) asm volatile("s_waitcnt vmcnt(" #n ")" ::: "memory")
; #define WAIT_L(n) asm volatile("s_waitcnt lgkmcnt(" #n ")" ::: "memory")
; #define BAR __builtin_amdgcn_s_barrier()
; #define SCHED __builtin_amdgcn_sched_barrier(0)
; template <int EPI>
; DI void gemm_phase(const int wid_s, const h16* __restrict__ A, const h16* __restrict__ Bt, const int N, const int K, const EpiArgs ea) {
;     ...
;       WAIT_V(8); WAIT_L(0); BAR; MMA(0, 0, At, B0); MMA(0, 1, At, B1); BAR; SCHED;
;       LDA(At, 0, 1); STAGE(SB(0, 0), b2, voffB); STAGE(SB(0, 1), b2 + hstep, voffB); STAGE(SA(0, 0), a2, voffA);
;       WAIT_V(8); WAIT_L(0); BAR; MMA(1, 0, At, B0); MMA(1, 1, At, B1); BAR; SCHED;
;       LDB(B0, 1, 0); LDB(B1, 1, 1); SCHED; LDA(At, 1, 0); STAGE(SA(0, 1), a2 + hstep, voffA);
;       WAIT_V(8); WAIT_L(0); BAR; MMA(0, 0, At, B0); MMA(0, 1, At, B1); BAR; SCHED;
	s_waitcnt lgkmcnt(0)
	v_mfma_f32_16x16x32_f16 v[130:133], v[152:155], v[206:209], v[130:133]
	v_mfma_f32_16x16x32_f16 v[126:129], v[182:185], v[206:209], v[126:129]
	v_mfma_f32_16x16x32_f16 v[122:125], v[152:155], v[214:217], v[122:125]
	v_mfma_f32_16x16x32_f16 v[118:121], v[182:185], v[214:217], v[118:121]
	v_mfma_f32_16x16x32_f16 v[106:109], v[152:155], v[222:225], v[106:109]
	v_mfma_f32_16x16x32_f16 v[102:105], v[182:185], v[222:225], v[102:105]
	v_mfma_f32_16x16x32_f16 v[90:93], v[152:155], v[230:233], v[90:93]
	v_mfma_f32_16x16x32_f16 v[86:89], v[182:185], v[230:233], v[86:89]
	v_mfma_f32_16x16x32_f16 v[130:133], v[178:181], v[210:213], v[130:133]
	v_mfma_f32_16x16x32_f16 v[126:129], v[186:189], v[210:213], v[126:129]
	v_mfma_f32_16x16x32_f16 v[122:125], v[178:181], v[218:221], v[122:125]
	v_mfma_f32_16x16x32_f16 v[118:121], v[186:189], v[218:221], v[118:121]
	v_mfma_f32_16x16x32_f16 v[106:109], v[178:181], v[226:229], v[106:109]
	v_mfma_f32_16x16x32_f16 v[102:105], v[186:189], v[226:229], v[102:105]
	v_mfma_f32_16x16x32_f16 v[90:93], v[178:181], v[234:237], v[90:93]
	v_mfma_f32_16x16x32_f16 v[86:89], v[186:189], v[234:237], v[86:89]
	v_mfma_f32_16x16x32_f16 v[114:117], v[190:193], v[206:209], v[114:117]
	v_mfma_f32_16x16x32_f16 v[110:113], v[198:201], v[206:209], v[110:113]
	v_mfma_f32_16x16x32_f16 v[98:101], v[190:193], v[214:217], v[98:101]
	v_mfma_f32_16x16x32_f16 v[94:97], v[198:201], v[214:217], v[94:97]
	v_mfma_f32_16x16x32_f16 v[82:85], v[190:193], v[222:225], v[82:85]
	v_mfma_f32_16x16x32_f16 v[78:81], v[198:201], v[222:225], v[78:81]
	v_mfma_f32_16x16x32_f16 v[74:77], v[190:193], v[230:233], v[74:77]
	v_mfma_f32_16x16x32_f16 v[70:73], v[198:201], v[230:233], v[70:73]
	v_mfma_f32_16x16x32_f16 v[114:117], v[194:197], v[210:213], v[114:117]
	v_mfma_f32_16x16x32_f16 v[110:113], v[202:205], v[210:213], v[110:113]
	v_mfma_f32_16x16x32_f16 v[98:101], v[194:197], v[218:221], v[98:101]
	v_mfma_f32_16x16x32_f16 v[94:97], v[202:205], v[218:221], v[94:97]
	v_mfma_f32_16x16x32_f16 v[82:85], v[194:197], v[226:229], v[82:85]
	v_mfma_f32_16x16x32_f16 v[78:81], v[202:205], v[226:229], v[78:81]
	v_mfma_f32_16x16x32_f16 v[74:77], v[194:197], v[234:237], v[74:77]
	v_mfma_f32_16x16x32_f16 v[70:73], v[202:205], v[234:237], v[70:73]
	s_barrier
	s_add_i32 s48, s50, s30
	v_lshl_add_u64 v[238:239], s[22:23], 0, v[0:1]
	s_mov_b32 m0, s48
	ds_read_b128 v[206:209], v151 offset:16384
	ds_read_b128 v[210:213], v151 offset:17408
	ds_read_b128 v[214:217], v151 offset:18432
	ds_read_b128 v[218:221], v151 offset:19456
	ds_read_b128 v[222:225], v151 offset:20480
	ds_read_b128 v[226:229], v151 offset:21504
	ds_read_b128 v[230:233], v151 offset:22528
	ds_read_b128 v[234:237], v151 offset:23552
	global_load_lds_dwordx4 v[238:239], off
	s_add_i32 m0, s48, 0x2000
	s_add_u32 s48, s22, 0x40000
	v_lshl_add_u64 v[240:241], s[22:23], 0, v[2:3]
	s_addc_u32 s49, s23, 0
	s_add_i32 s50, s51, s30
	global_load_lds_dwordx4 v[240:241], off
	v_lshl_add_u64 v[242:243], s[48:49], 0, v[0:1]
	s_mov_b32 m0, s50
	v_lshl_add_u64 v[244:245], s[26:27], 0, v[134:135]
	global_load_lds_dwordx4 v[242:243], off
	v_lshl_add_u64 v[242:243], s[48:49], 0, v[2:3]
	s_add_i32 m0, s50, 0x2000
	s_nop 0
	global_load_lds_dwordx4 v[242:243], off
	v_lshl_add_u64 v[242:243], s[26:27], 0, v[138:139]
	s_waitcnt vmcnt(6)
	s_waitcnt lgkmcnt(0)
	s_barrier
	s_waitcnt lgkmcnt(0)
	v_mfma_f32_16x16x32_f16 v[66:69], v[152:155], v[206:209], v[66:69]
	v_mfma_f32_16x16x32_f16 v[62:65], v[182:185], v[206:209], v[62:65]
	v_mfma_f32_16x16x32_f16 v[58:61], v[152:155], v[214:217], v[58:61]
	v_mfma_f32_16x16x32_f16 v[54:57], v[182:185], v[214:217], v[54:57]
	v_mfma_f32_16x16x32_f16 v[42:45], v[152:155], v[222:225], v[42:45]
	v_mfma_f32_16x16x32_f16 v[38:41], v[182:185], v[222:225], v[38:41]
	v_mfma_f32_16x16x32_f16 v[26:29], v[152:155], v[230:233], v[26:29]
	v_mfma_f32_16x16x32_f16 v[22:25], v[182:185], v[230:233], v[22:25]
	v_mfma_f32_16x16x32_f16 v[66:69], v[178:181], v[210:213], v[66:69]
	v_mfma_f32_16x16x32_f16 v[62:65], v[186:189], v[210:213], v[62:65]
	v_mfma_f32_16x16x32_f16 v[58:61], v[178:181], v[218:221], v[58:61]
	v_mfma_f32_16x16x32_f16 v[54:57], v[186:189], v[218:221], v[54:57]
	v_mfma_f32_16x16x32_f16 v[42:45], v[178:181], v[226:229], v[42:45]
	v_mfma_f32_16x16x32_f16 v[38:41], v[186:189], v[226:229], v[38:41]
	v_mfma_f32_16x16x32_f16 v[26:29], v[178:181], v[234:237], v[26:29]
	v_mfma_f32_16x16x32_f16 v[22:25], v[186:189], v[234:237], v[22:25]
	v_mfma_f32_16x16x32_f16 v[50:53], v[190:193], v[206:209], v[50:53]
	v_mfma_f32_16x16x32_f16 v[46:49], v[198:201], v[206:209], v[46:49]
	v_mfma_f32_16x16x32_f16 v[34:37], v[190:193], v[214:217], v[34:37]
	v_mfma_f32_16x16x32_f16 v[30:33], v[198:201], v[214:217], v[30:33]
	v_mfma_f32_16x16x32_f16 v[18:21], v[190:193], v[222:225], v[18:21]
	v_mfma_f32_16x16x32_f16 v[14:17], v[198:201], v[222:225], v[14:17]
	v_mfma_f32_16x16x32_f16 v[10:13], v[190:193], v[230:233], v[10:13]
	v_mfma_f32_16x16x32_f16 v[6:9], v[198:201], v[230:233], v[6:9]
	v_mfma_f32_16x16x32_f16 v[50:53], v[194:197], v[210:213], v[50:53]
	v_mfma_f32_16x16x32_f16 v[46:49], v[202:205], v[210:213], v[46:49]
	v_mfma_f32_16x16x32_f16 v[34:37], v[194:197], v[218:221], v[34:37]
	v_mfma_f32_16x16x32_f16 v[30:33], v[202:205], v[218:221], v[30:33]
	v_mfma_f32_16x16x32_f16 v[18:21], v[194:197], v[226:229], v[18:21]
	v_mfma_f32_16x16x32_f16 v[14:17], v[202:205], v[226:229], v[14:17]
	v_mfma_f32_16x16x32_f16 v[10:13], v[194:197], v[234:237], v[10:13]
	v_mfma_f32_16x16x32_f16 v[6:9], v[202:205], v[234:237], v[6:9]
	s_barrier
; #define STAGE(bufoff, gbase, voff) do { _Pragma("unroll") for (int _i = 0; _i < 2; ++_i) \
;     __builtin_amdgcn_global_load_lds((const unsigned*)((const char*)(gbase) + (voff)[_i]), (LAS unsigned*)(lds + (bufoff) + ldsw + _i * 8192), 16, 0, 0); } while (0)
; #define LDA(dst, b, h) do { _Pragma("unroll") for (int m = 0; m < 4; ++m) _Pragma("unroll") for (int k = 0; k < 2; ++k) dst[m][k] = *(const LAS half8*)(lds + SA(b, h) + aoff + m * 2048 + k * 1024); } while (0)
; #define LDB(dst, b, h) do { _Pragma("unroll") for (int n = 0; n < 2; ++n) _Pragma("unroll") for (int k = 0; k < 2; ++k) dst[n][k] = *(const LAS half8*)(lds + SB(b, h) + boff + n * 2048 + k * 1024); } while (0)
; #define MMA(ai, bj, At_, Bt_) do { __builtin_amdgcn_s_setprio(1); \
;     _Pragma("unroll") for (int m = 0; m < 4; ++m) _Pragma("unroll") for (int n = 0; n < 2; ++n) _Pragma("unroll") for (int k = 0; k < 2; ++k) \
;       acc[ai][bj][m][n] = MFMA16(Bt_[n][k], At_[m][k], acc[ai][bj][m][n]); \
;     __builtin_amdgcn_s_setprio(0); } while (0)
; #define WAIT_V(n) asm volatile("s_waitcnt vmcnt(" #n ")" ::: "memory")
; #define WAIT_L(n) asm volatile("s_waitcnt lgkmcnt(" #n ")" ::: "memory")
; #define BAR __builtin_amdgcn_s_barrier()
; #define SCHED __builtin_amdgcn_sched_barrier(0)
; template <int EPI>
; DI void gemm_phase(const int wid_s, const h16* __restrict__ A, const h16* __restrict__ Bt, const int N, const int K, const EpiArgs ea) {
;     ...
;       LDB(B0, 1, 0); LDB(B1, 1, 1); SCHED; LDA(At, 1, 0); STAGE(SA(0, 1), a2 + hstep, voffA);
;       WAIT_V(8); WAIT_L(0); BAR; MMA(0, 0, At, B0); MMA(0, 1, At, B1); BAR; SCHED;
;       LDA(At, 1, 1); STAGE(SB(1, 0), b3, voffB); STAGE(SB(1, 1), b3 + hstep, voffB); STAGE(SA(1, 0), a3, voffA);
	s_add_i32 s48, 0, 0x18000
	v_add_u32_e32 v177, s48, v148
	s_add_i32 s49, 0, 0x1c000
	ds_read_b128 v[152:155], v177
	ds_read_b128 v[178:181], v177 offset:1024
	ds_read_b128 v[182:185], v177 offset:2048
	ds_read_b128 v[186:189], v177 offset:3072
	v_add_u32_e32 v177, s49, v148
	ds_read_b128 v[190:193], v177
	ds_read_b128 v[194:197], v177 offset:1024
	ds_read_b128 v[198:201], v177 offset:2048
	ds_read_b128 v[202:205], v177 offset:3072
	s_add_u32 s26, s26, 0x40000
	s_addc_u32 s27, s27, 0
	v_lshl_add_u64 v[246:247], s[26:27], 0, v[138:139]
	ds_read_b128 v[206:209], v151 offset:32768
	ds_read_b128 v[210:213], v151 offset:33792
	ds_read_b128 v[214:217], v151 offset:34816
	ds_read_b128 v[218:221], v151 offset:35840
	ds_read_b128 v[222:225], v151 offset:36864
	ds_read_b128 v[226:229], v151 offset:37888
	ds_read_b128 v[230:233], v151 offset:38912
	ds_read_b128 v[234:237], v151 offset:39936
	s_mov_b32 m0, s13
	s_nop 0
	global_load_lds_dwordx4 v[242:243], off
	s_mov_b32 m0, s15
	s_nop 0
	global_load_lds_dwordx4 v[244:245], off
	s_mov_b32 m0, s31
	s_nop 0
	global_load_lds_dwordx4 v[246:247], off
	v_lshl_add_u64 v[246:247], s[26:27], 0, v[134:135]
	s_mov_b32 m0, s38
	s_nop 0
	global_load_lds_dwordx4 v[246:247], off
	s_waitcnt vmcnt(8)
	s_waitcnt lgkmcnt(0)
	s_barrier
	s_waitcnt lgkmcnt(0)
	v_mfma_f32_16x16x32_f16 v[130:133], v[152:155], v[206:209], v[130:133]
	v_mfma_f32_16x16x32_f16 v[126:129], v[182:185], v[206:209], v[126:129]
	v_mfma_f32_16x16x32_f16 v[122:125], v[152:155], v[214:217], v[122:125]
	v_mfma_f32_16x16x32_f16 v[118:121], v[182:185], v[214:217], v[118:121]
	v_mfma_f32_16x16x32_f16 v[106:109], v[152:155], v[222:225], v[106:109]
	v_mfma_f32_16x16x32_f16 v[102:105], v[182:185], v[222:225], v[102:105]
	v_mfma_f32_16x16x32_f16 v[90:93], v[152:155], v[230:233], v[90:93]
	v_mfma_f32_16x16x32_f16 v[86:89], v[182:185], v[230:233], v[86:89]
	v_mfma_f32_16x16x32_f16 v[130:133], v[178:181], v[210:213], v[130:133]
	v_mfma_f32_16x16x32_f16 v[126:129], v[186:189], v[210:213], v[126:129]
	v_mfma_f32_16x16x32_f16 v[122:125], v[178:181], v[218:221], v[122:125]
	v_mfma_f32_16x16x32_f16 v[118:121], v[186:189], v[218:221], v[118:121]
	v_mfma_f32_16x16x32_f16 v[106:109], v[178:181], v[226:229], v[106:109]
	v_mfma_f32_16x16x32_f16 v[102:105], v[186:189], v[226:229], v[102:105]
	v_mfma_f32_16x16x32_f16 v[90:93], v[178:181], v[234:237], v[90:93]
	v_mfma_f32_16x16x32_f16 v[86:89], v[186:189], v[234:237], v[86:89]
	v_mfma_f32_16x16x32_f16 v[114:117], v[190:193], v[206:209], v[114:117]
	v_mfma_f32_16x16x32_f16 v[110:113], v[198:201], v[206:209], v[110:113]
	v_mfma_f32_16x16x32_f16 v[98:101], v[190:193], v[214:217], v[98:101]
	v_mfma_f32_16x16x32_f16 v[94:97], v[198:201], v[214:217], v[94:97]
	v_mfma_f32_16x16x32_f16 v[82:85], v[190:193], v[222:225], v[82:85]
	v_mfma_f32_16x16x32_f16 v[78:81], v[198:201], v[222:225], v[78:81]
	v_mfma_f32_16x16x32_f16 v[74:77], v[190:193], v[230:233], v[74:77]
	v_mfma_f32_16x16x32_f16 v[70:73], v[198:201], v[230:233], v[70:73]
	v_mfma_f32_16x16x32_f16 v[114:117], v[194:197], v[210:213], v[114:117]
	v_mfma_f32_16x16x32_f16 v[110:113], v[202:205], v[210:213], v[110:113]
	v_mfma_f32_16x16x32_f16 v[98:101], v[194:197], v[218:221], v[98:101]
	v_mfma_f32_16x16x32_f16 v[94:97], v[202:205], v[218:221], v[94:97]
	v_mfma_f32_16x16x32_f16 v[82:85], v[194:197], v[226:229], v[82:85]
	v_mfma_f32_16x16x32_f16 v[78:81], v[202:205], v[226:229], v[78:81]
	v_mfma_f32_16x16x32_f16 v[74:77], v[194:197], v[234:237], v[74:77]
	v_mfma_f32_16x16x32_f16 v[70:73], v[202:205], v[234:237], v[70:73]
	s_barrier
; #define STAGE(bufoff, gbase, voff) do { _Pragma("unroll") for (int _i = 0; _i < 2; ++_i) \
;     __builtin_amdgcn_global_load_lds((const unsigned*)((const char*)(gbase) + (voff)[_i]), (LAS unsigned*)(lds + (bufoff) + ldsw + _i * 8192), 16, 0, 0); } while (0)
; #define LDA(dst, b, h) do { _Pragma("unroll") for (int m = 0; m < 4; ++m) _Pragma("unroll") for (int k = 0; k < 2; ++k) dst[m][k] = *(const LAS half8*)(lds + SA(b, h) + aoff + m * 2048 + k * 1024); } while (0)
; #define MMA(ai, bj, At_, Bt_) do { __builtin_amdgcn_s_setprio(1); \
;     _Pragma("unroll") for (int m = 0; m < 4; ++m) _Pragma("unroll") for (int n = 0; n < 2; ++n) _Pragma("unroll") for (int k = 0; k < 2; ++k) \
;       acc[ai][bj][m][n] = MFMA16(Bt_[n][k], At_[m][k], acc[ai][bj][m][n]); \
;     __builtin_amdgcn_s_setprio(0); } while (0)
; #define WAIT_V(n) asm volatile("s_waitcnt vmcnt(" #n ")" ::: "memory")
; #define WAIT_L(n) asm volatile("s_waitcnt lgkmcnt(" #n ")" ::: "memory")
; #define BAR __builtin_amdgcn_s_barrier()
; #define SCHED __builtin_amdgcn_sched_barrier(0)
; template <int EPI>
; DI void gemm_phase(const int wid_s, const h16* __restrict__ A, const h16* __restrict__ Bt, const int N, const int K, const EpiArgs ea) {
;     ...
;       LDA(At, 1, 1); STAGE(SB(1, 0), b3, voffB); STAGE(SB(1, 1), b3 + hstep, voffB); STAGE(SA(1, 0), a3, voffA);
;       WAIT_V(8); WAIT_L(0); BAR; MMA(1, 0, At, B0); MMA(1, 1, At, B1); BAR; SCHED;
;     }
;     if (wr == 0) BAR;
	s_add_i32 s26, s48, s30
	v_lshl_add_u64 v[238:239], v[238:239], 0, s[36:37]
	s_mov_b32 m0, s26
	ds_read_b128 v[206:209], v151 offset:49152
	ds_read_b128 v[210:213], v151 offset:50176
	ds_read_b128 v[214:217], v151 offset:51200
	ds_read_b128 v[218:221], v151 offset:52224
	ds_read_b128 v[222:225], v151 offset:53248
	ds_read_b128 v[226:229], v151 offset:54272
	ds_read_b128 v[230:233], v151 offset:55296
	ds_read_b128 v[234:237], v151 offset:56320
	global_load_lds_dwordx4 v[238:239], off
	s_add_i32 m0, s26, 0x2000
	s_add_u32 s22, s22, 0x40080
	v_lshl_add_u64 v[238:239], v[240:241], 0, s[36:37]
	s_addc_u32 s23, s23, 0
	s_add_i32 s26, s49, s30
	global_load_lds_dwordx4 v[238:239], off
	v_lshl_add_u64 v[238:239], s[22:23], 0, v[0:1]
	s_mov_b32 m0, s26
	s_nop 0
	global_load_lds_dwordx4 v[238:239], off
	v_lshl_add_u64 v[238:239], s[22:23], 0, v[2:3]
	s_add_i32 m0, s26, 0x2000
	s_nop 0
	global_load_lds_dwordx4 v[238:239], off
	v_lshl_add_u64 v[238:239], v[242:243], 0, s[36:37]
	s_mov_b32 m0, s39
	s_nop 0
	global_load_lds_dwordx4 v[238:239], off
	v_lshl_add_u64 v[238:239], v[244:245], 0, s[36:37]
	s_mov_b32 m0, s40
	s_nop 0
	global_load_lds_dwordx4 v[238:239], off
	s_waitcnt vmcnt(8)
	s_waitcnt lgkmcnt(0)
	s_barrier
	s_waitcnt lgkmcnt(0)
	v_mfma_f32_16x16x32_f16 v[66:69], v[152:155], v[206:209], v[66:69]
	v_mfma_f32_16x16x32_f16 v[62:65], v[182:185], v[206:209], v[62:65]
	v_mfma_f32_16x16x32_f16 v[58:61], v[152:155], v[214:217], v[58:61]
	v_mfma_f32_16x16x32_f16 v[54:57], v[182:185], v[214:217], v[54:57]
	v_mfma_f32_16x16x32_f16 v[42:45], v[152:155], v[222:225], v[42:45]
	v_mfma_f32_16x16x32_f16 v[38:41], v[182:185], v[222:225], v[38:41]
	v_mfma_f32_16x16x32_f16 v[26:29], v[152:155], v[230:233], v[26:29]
	v_mfma_f32_16x16x32_f16 v[22:25], v[182:185], v[230:233], v[22:25]
	v_mfma_f32_16x16x32_f16 v[66:69], v[178:181], v[210:213], v[66:69]
	v_mfma_f32_16x16x32_f16 v[62:65], v[186:189], v[210:213], v[62:65]
	v_mfma_f32_16x16x32_f16 v[58:61], v[178:181], v[218:221], v[58:61]
	v_mfma_f32_16x16x32_f16 v[54:57], v[186:189], v[218:221], v[54:57]
	v_mfma_f32_16x16x32_f16 v[42:45], v[178:181], v[226:229], v[42:45]
	v_mfma_f32_16x16x32_f16 v[38:41], v[186:189], v[226:229], v[38:41]
	v_mfma_f32_16x16x32_f16 v[26:29], v[178:181], v[234:237], v[26:29]
	v_mfma_f32_16x16x32_f16 v[22:25], v[186:189], v[234:237], v[22:25]
	v_mfma_f32_16x16x32_f16 v[50:53], v[190:193], v[206:209], v[50:53]
	v_mfma_f32_16x16x32_f16 v[46:49], v[198:201], v[206:209], v[46:49]
	v_mfma_f32_16x16x32_f16 v[34:37], v[190:193], v[214:217], v[34:37]
	v_mfma_f32_16x16x32_f16 v[30:33], v[198:201], v[214:217], v[30:33]
	v_mfma_f32_16x16x32_f16 v[18:21], v[190:193], v[222:225], v[18:21]
	v_mfma_f32_16x16x32_f16 v[14:17], v[198:201], v[222:225], v[14:17]
	v_mfma_f32_16x16x32_f16 v[10:13], v[190:193], v[230:233], v[10:13]
	v_mfma_f32_16x16x32_f16 v[6:9], v[198:201], v[230:233], v[6:9]
	v_mfma_f32_16x16x32_f16 v[50:53], v[194:197], v[210:213], v[50:53]
	v_mfma_f32_16x16x32_f16 v[46:49], v[202:205], v[210:213], v[46:49]
	v_mfma_f32_16x16x32_f16 v[34:37], v[194:197], v[218:221], v[34:37]
	v_mfma_f32_16x16x32_f16 v[30:33], v[202:205], v[218:221], v[30:33]
	v_mfma_f32_16x16x32_f16 v[18:21], v[194:197], v[226:229], v[18:21]
	v_mfma_f32_16x16x32_f16 v[14:17], v[202:205], v[226:229], v[14:17]
	v_mfma_f32_16x16x32_f16 v[10:13], v[194:197], v[234:237], v[10:13]
	v_mfma_f32_16x16x32_f16 v[6:9], v[202:205], v[234:237], v[6:9]
	s_barrier
	s_add_i32 s47, s47, 2
	s_add_u32 s20, s20, 0x100
	s_addc_u32 s21, s21, 0
	s_cmp_gt_u32 s47, 13
	s_cbranch_scc0 .LBB0_386
	s_and_b64 vcc, exec, s[4:5]
	s_cbranch_vccz .LBB0_389
	s_barrier
